# K-loop LDS-DMA in saddr+32-bit-voffset form (no per-DMA 64-bit VALU adds), redundant setprio/waitcnt trimmed, on top of v12
# speedup vs baseline: 1.0099x; 1.0099x over previous
; #define PG8_STAGE(bufoff, gbase, voff) do { _Pragma("unroll") for (int _i = 0; _i < 2; ++_i) \
;         __builtin_amdgcn_global_load_lds((const unsigned*)((const char*)(gbase) + (voff)[_i]), (PG8_LAS unsigned*)(lds + (bufoff) + ldsw + _i * 8192), 16, 0, 0); } while (0)
; #define PG8_LDA(dst, b, h) do { _Pragma("unroll") for (int m = 0; m < 4; ++m) _Pragma("unroll") for (int k = 0; k < 2; ++k) dst[m][k] = *(const PG8_LAS bf16x8*)(lds + PG8_SA(b, h) + aoff + m * 2048 + k * 1024); } while (0)
; #define PG8_LDB(dst, b, h) do { _Pragma("unroll") for (int n = 0; n < 2; ++n) _Pragma("unroll") for (int k = 0; k < 2; ++k) dst[n][k] = *(const PG8_LAS bf16x8*)(lds + PG8_SB(b, h) + boff + n * 2048 + k * 1024); } while (0)
; #define PG8_MMA(ai, bj, At, Bt) do { __builtin_amdgcn_s_setprio(1); _Pragma("unroll") for (int m = 0; m < 4; ++m) _Pragma("unroll") for (int n = 0; n < 2; ++n) _Pragma("unroll") for (int k = 0; k < 2; ++k) \
;         acc[ai][bj][m][n] = __builtin_amdgcn_mfma_f32_16x16x32_bf16(Bt[n][k], At[m][k], acc[ai][bj][m][n], 0, 0, 0); __builtin_amdgcn_s_setprio(0); } while (0)
; #define PG8_WAIT_V(n) asm volatile("s_waitcnt vmcnt(" #n ")" ::: "memory")
; #define PG8_WAIT_L(n) asm volatile("s_waitcnt lgkmcnt(" #n ")" ::: "memory")
; #define PG8_BAR __builtin_amdgcn_s_barrier()
; #define PG8_SCHED __builtin_amdgcn_sched_barrier(0)
; template <class Epi, class Sched, bool ALIGN_EPI = false, bool SP2 = false>
; __device__ __forceinline__ void gemm_phase(PG8_LAS unsigned char* lds, const Gemm g, const Sched& S, const Epi& E) {
;     ...
;             const char* a2 = last ? nA : cA + (size_t)(t + 2) * kstep; const char* b2 = last ? nB : cB + (size_t)(t + 2) * kstep;
;             const char* a3 = a2 + kstep; const char* b3 = b2 + kstep;
;             if (last && has_next) S.a_ready_inloop(nxt, ui + 1);
;             if constexpr (SP2) {
;             PG8_LDB(B0, 0, 0); PG8_LDB(B1, 0, 1); PG8_SCHED; PG8_LDA(At, 0, 0); PG8_STAGE(PG8_SA(1, 1), a1 + hstep, voffA);
;             PG8_WAIT_V(8); PG8_WAIT_L(0); PG8_BAR; PG8_MMA(0, 0, At, B0); PG8_MMA(0, 1, At, B1); PG8_BAR; PG8_SCHED;
;             PG8_LDA(At, 0, 1); PG8_STAGE(PG8_SB(0, 0), b2, voffB); PG8_STAGE(PG8_SB(0, 1), b2 + hstep, voffB); PG8_STAGE(PG8_SA(0, 0), a2, voffA);
.LBB0_120:
	s_ashr_i32 s13, s12, 31
	s_lshl_b64 s[16:17], s[12:13], 19
	s_add_u32 s16, s28, s16
	s_addc_u32 s17, s29, s17
	s_and_b64 s[18:19], s[2:3], exec
	s_cselect_b32 s13, s17, s21
	s_cselect_b32 s52, s16, s20
	s_ashr_i32 s15, s14, 31
	s_lshl_b64 s[18:19], s[14:15], 19
	s_add_u32 s18, s30, s18
	s_addc_u32 s19, s31, s19
	s_and_b64 s[24:25], s[2:3], exec
	s_cselect_b32 s15, s19, s23
	s_cselect_b32 s53, s18, s22
	s_add_u32 s20, s20, 0x40080
	s_addc_u32 s21, s21, 0
	s_add_u32 s62, s22, 0x100
	s_addc_u32 s63, s23, 0
	s_mov_b32 s64, -2
	s_add_u32 s22, s20, 0xfffc0080
	s_addc_u32 s23, s21, -1
	s_add_i32 s90, 0, 0x10000
	s_cmp_eq_u32 s64, 12
	s_cselect_b32 s25, s13, s23
	s_cselect_b32 s24, s52, s22
	v_add_u32_e32 v158, s90, v160
	s_cselect_b32 s23, s15, s63
	s_cselect_b32 s22, s53, s62
	s_add_u32 s98, s22, s46
	s_addc_u32 s99, s23, s47
	s_add_u32 s100, s24, s46
	s_addc_u32 s101, s25, s47
	s_add_i32 s81, 0, 0x14000
	ds_read_b128 v[164:167], v158
	ds_read_b128 v[168:171], v158 offset:1024
	ds_read_b128 v[172:175], v158 offset:2048
	ds_read_b128 v[176:179], v158 offset:3072
	v_add_u32_e32 v158, s81, v160
	ds_read_b128 v[180:183], v158
	ds_read_b128 v[184:187], v158 offset:1024
	ds_read_b128 v[188:191], v158 offset:2048
	ds_read_b128 v[192:195], v158 offset:3072
	s_add_i32 m0, s35, 0xc000
	ds_read_b128 v[196:199], v163
	ds_read_b128 v[200:203], v163 offset:1024
	ds_read_b128 v[216:219], v163 offset:2048
	ds_read_b128 v[220:223], v163 offset:3072
	ds_read_b128 v[224:227], v163 offset:4096
	ds_read_b128 v[228:231], v163 offset:5120
	ds_read_b128 v[232:235], v163 offset:6144
	ds_read_b128 v[236:239], v163 offset:7168
	global_load_lds_dwordx4 v154, s[20:21]
	s_add_i32 m0, s35, 0xe000
	s_nop 0
	global_load_lds_dwordx4 v156, s[20:21]
	s_waitcnt vmcnt(8) lgkmcnt(0)
	s_barrier
	s_setprio 1
	v_mfma_f32_16x16x32_bf16 v[142:145], v[164:167], v[196:199], 0
	v_mfma_f32_16x16x32_bf16 v[138:141], v[172:175], v[196:199], 0
	v_mfma_f32_16x16x32_bf16 v[126:129], v[164:167], v[216:219], 0
	v_mfma_f32_16x16x32_bf16 v[122:125], v[172:175], v[216:219], 0
	v_mfma_f32_16x16x32_bf16 v[110:113], v[164:167], v[224:227], 0
	v_mfma_f32_16x16x32_bf16 v[106:109], v[172:175], v[224:227], 0
	v_mfma_f32_16x16x32_bf16 v[94:97], v[164:167], v[232:235], 0
	v_mfma_f32_16x16x32_bf16 v[90:93], v[172:175], v[232:235], 0
	v_mfma_f32_16x16x32_bf16 v[142:145], v[168:171], v[200:203], v[142:145]
	v_mfma_f32_16x16x32_bf16 v[138:141], v[176:179], v[200:203], v[138:141]
	v_mfma_f32_16x16x32_bf16 v[126:129], v[168:171], v[220:223], v[126:129]
	v_mfma_f32_16x16x32_bf16 v[122:125], v[176:179], v[220:223], v[122:125]
	v_mfma_f32_16x16x32_bf16 v[110:113], v[168:171], v[228:231], v[110:113]
	v_mfma_f32_16x16x32_bf16 v[106:109], v[176:179], v[228:231], v[106:109]
	v_mfma_f32_16x16x32_bf16 v[94:97], v[168:171], v[236:239], v[94:97]
	v_mfma_f32_16x16x32_bf16 v[90:93], v[176:179], v[236:239], v[90:93]
	v_mfma_f32_16x16x32_bf16 v[134:137], v[180:183], v[196:199], 0
	v_mfma_f32_16x16x32_bf16 v[130:133], v[188:191], v[196:199], 0
	v_mfma_f32_16x16x32_bf16 v[118:121], v[180:183], v[216:219], 0
	v_mfma_f32_16x16x32_bf16 v[114:117], v[188:191], v[216:219], 0
	v_mfma_f32_16x16x32_bf16 v[102:105], v[180:183], v[224:227], 0
	v_mfma_f32_16x16x32_bf16 v[98:101], v[188:191], v[224:227], 0
	v_mfma_f32_16x16x32_bf16 v[86:89], v[180:183], v[232:235], 0
	v_mfma_f32_16x16x32_bf16 v[82:85], v[188:191], v[232:235], 0
	v_mfma_f32_16x16x32_bf16 v[134:137], v[184:187], v[200:203], v[134:137]
	v_mfma_f32_16x16x32_bf16 v[130:133], v[192:195], v[200:203], v[130:133]
	v_mfma_f32_16x16x32_bf16 v[118:121], v[184:187], v[220:223], v[118:121]
	v_mfma_f32_16x16x32_bf16 v[114:117], v[192:195], v[220:223], v[114:117]
	v_mfma_f32_16x16x32_bf16 v[102:105], v[184:187], v[228:231], v[102:105]
	v_mfma_f32_16x16x32_bf16 v[98:101], v[192:195], v[228:231], v[98:101]
	v_mfma_f32_16x16x32_bf16 v[86:89], v[184:187], v[236:239], v[86:89]
	v_mfma_f32_16x16x32_bf16 v[82:85], v[192:195], v[236:239], v[82:85]
	s_setprio 0
	s_barrier
	s_add_i32 s65, s90, s34
	s_mov_b32 m0, s65
	ds_read_b128 v[196:199], v163 offset:16384
	ds_read_b128 v[200:203], v163 offset:17408
	ds_read_b128 v[216:219], v163 offset:18432
	ds_read_b128 v[220:223], v163 offset:19456
	ds_read_b128 v[224:227], v163 offset:20480
	ds_read_b128 v[228:231], v163 offset:21504
	ds_read_b128 v[232:235], v163 offset:22528
	ds_read_b128 v[236:239], v163 offset:23552
	global_load_lds_dwordx4 v148, s[22:23]
	s_add_i32 m0, s65, 0x2000
	s_add_u32 s66, s22, 0x40000
	s_addc_u32 s67, s23, 0
	s_add_i32 s65, s81, s34
	global_load_lds_dwordx4 v152, s[22:23]
	s_mov_b32 m0, s65
	s_nop 0
	global_load_lds_dwordx4 v148, s[66:67]
	s_add_i32 m0, s65, 0x2000
	s_nop 0
	global_load_lds_dwordx4 v152, s[66:67]
	s_mov_b32 m0, s35
	s_nop 0
	global_load_lds_dwordx4 v146, s[24:25]
	s_mov_b32 m0, s36
	s_nop 0
	global_load_lds_dwordx4 v150, s[24:25]
	s_waitcnt vmcnt(8) lgkmcnt(0)
	s_barrier
; #define PG8_STAGE(bufoff, gbase, voff) do { _Pragma("unroll") for (int _i = 0; _i < 2; ++_i) \
;         __builtin_amdgcn_global_load_lds((const unsigned*)((const char*)(gbase) + (voff)[_i]), (PG8_LAS unsigned*)(lds + (bufoff) + ldsw + _i * 8192), 16, 0, 0); } while (0)
; #define PG8_LDA(dst, b, h) do { _Pragma("unroll") for (int m = 0; m < 4; ++m) _Pragma("unroll") for (int k = 0; k < 2; ++k) dst[m][k] = *(const PG8_LAS bf16x8*)(lds + PG8_SA(b, h) + aoff + m * 2048 + k * 1024); } while (0)
; #define PG8_LDB(dst, b, h) do { _Pragma("unroll") for (int n = 0; n < 2; ++n) _Pragma("unroll") for (int k = 0; k < 2; ++k) dst[n][k] = *(const PG8_LAS bf16x8*)(lds + PG8_SB(b, h) + boff + n * 2048 + k * 1024); } while (0)
; #define PG8_MMA(ai, bj, At, Bt) do { __builtin_amdgcn_s_setprio(1); _Pragma("unroll") for (int m = 0; m < 4; ++m) _Pragma("unroll") for (int n = 0; n < 2; ++n) _Pragma("unroll") for (int k = 0; k < 2; ++k) \
;         acc[ai][bj][m][n] = __builtin_amdgcn_mfma_f32_16x16x32_bf16(Bt[n][k], At[m][k], acc[ai][bj][m][n], 0, 0, 0); __builtin_amdgcn_s_setprio(0); } while (0)
; #define PG8_WAIT_V(n) asm volatile("s_waitcnt vmcnt(" #n ")" ::: "memory")
; #define PG8_WAIT_L(n) asm volatile("s_waitcnt lgkmcnt(" #n ")" ::: "memory")
; #define PG8_BAR __builtin_amdgcn_s_barrier()
; #define PG8_SCHED __builtin_amdgcn_sched_barrier(0)
; template <class Epi, class Sched, bool ALIGN_EPI = false, bool SP2 = false>
; __device__ __forceinline__ void gemm_phase(PG8_LAS unsigned char* lds, const Gemm g, const Sched& S, const Epi& E) {
;     ...
;             PG8_WAIT_V(8); PG8_WAIT_L(0); PG8_BAR; PG8_MMA(1, 0, At, B0); PG8_MMA(1, 1, At, B1); PG8_BAR; PG8_SCHED;
;             PG8_LDB(B0, 1, 0); PG8_LDB(B1, 1, 1); PG8_SCHED; PG8_LDA(At, 1, 0); PG8_STAGE(PG8_SA(0, 1), a2 + hstep, voffA);
;             PG8_WAIT_V(8); PG8_WAIT_L(0); PG8_BAR; PG8_MMA(0, 0, At, B0); PG8_MMA(0, 1, At, B1); PG8_BAR; PG8_SCHED;
	s_setprio 1
	v_mfma_f32_16x16x32_bf16 v[78:81], v[164:167], v[196:199], 0
	v_mfma_f32_16x16x32_bf16 v[74:77], v[172:175], v[196:199], 0
	v_mfma_f32_16x16x32_bf16 v[62:65], v[164:167], v[216:219], 0
	v_mfma_f32_16x16x32_bf16 v[58:61], v[172:175], v[216:219], 0
	v_mfma_f32_16x16x32_bf16 v[46:49], v[164:167], v[224:227], 0
	v_mfma_f32_16x16x32_bf16 v[42:45], v[172:175], v[224:227], 0
	v_mfma_f32_16x16x32_bf16 v[30:33], v[164:167], v[232:235], 0
	v_mfma_f32_16x16x32_bf16 v[26:29], v[172:175], v[232:235], 0
	v_mfma_f32_16x16x32_bf16 v[78:81], v[168:171], v[200:203], v[78:81]
	v_mfma_f32_16x16x32_bf16 v[74:77], v[176:179], v[200:203], v[74:77]
	v_mfma_f32_16x16x32_bf16 v[62:65], v[168:171], v[220:223], v[62:65]
	v_mfma_f32_16x16x32_bf16 v[58:61], v[176:179], v[220:223], v[58:61]
	v_mfma_f32_16x16x32_bf16 v[46:49], v[168:171], v[228:231], v[46:49]
	v_mfma_f32_16x16x32_bf16 v[42:45], v[176:179], v[228:231], v[42:45]
	v_mfma_f32_16x16x32_bf16 v[30:33], v[168:171], v[236:239], v[30:33]
	v_mfma_f32_16x16x32_bf16 v[26:29], v[176:179], v[236:239], v[26:29]
	v_mfma_f32_16x16x32_bf16 v[70:73], v[180:183], v[196:199], 0
	v_mfma_f32_16x16x32_bf16 v[66:69], v[188:191], v[196:199], 0
	v_mfma_f32_16x16x32_bf16 v[54:57], v[180:183], v[216:219], 0
	v_mfma_f32_16x16x32_bf16 v[50:53], v[188:191], v[216:219], 0
	v_mfma_f32_16x16x32_bf16 v[38:41], v[180:183], v[224:227], 0
	v_mfma_f32_16x16x32_bf16 v[34:37], v[188:191], v[224:227], 0
	v_mfma_f32_16x16x32_bf16 v[22:25], v[180:183], v[232:235], 0
	v_mfma_f32_16x16x32_bf16 v[18:21], v[188:191], v[232:235], 0
	v_mfma_f32_16x16x32_bf16 v[70:73], v[184:187], v[200:203], v[70:73]
	v_mfma_f32_16x16x32_bf16 v[66:69], v[192:195], v[200:203], v[66:69]
	v_mfma_f32_16x16x32_bf16 v[54:57], v[184:187], v[220:223], v[54:57]
	v_mfma_f32_16x16x32_bf16 v[50:53], v[192:195], v[220:223], v[50:53]
	v_mfma_f32_16x16x32_bf16 v[38:41], v[184:187], v[228:231], v[38:41]
	v_mfma_f32_16x16x32_bf16 v[34:37], v[192:195], v[228:231], v[34:37]
	v_mfma_f32_16x16x32_bf16 v[22:25], v[184:187], v[236:239], v[22:25]
	v_mfma_f32_16x16x32_bf16 v[18:21], v[192:195], v[236:239], v[18:21]
	s_setprio 0
	s_barrier
	s_add_i32 s82, 0, 0x18000
	s_add_i32 s83, 0, 0x1c000
	v_add_u32_e32 v176, s82, v160
	v_add_u32_e32 v192, s83, v160
	ds_read_b128 v[164:167], v176
	ds_read_b128 v[168:171], v176 offset:1024
	ds_read_b128 v[172:175], v176 offset:2048
	ds_read_b128 v[176:179], v176 offset:3072
	ds_read_b128 v[180:183], v192
	ds_read_b128 v[184:187], v192 offset:1024
	ds_read_b128 v[188:191], v192 offset:2048
	ds_read_b128 v[192:195], v192 offset:3072
	s_add_u32 s24, s24, 0x40000
	s_addc_u32 s25, s25, 0
	s_mov_b32 m0, s37
	ds_read_b128 v[196:199], v163 offset:32768
	ds_read_b128 v[200:203], v163 offset:33792
	ds_read_b128 v[216:219], v163 offset:34816
	ds_read_b128 v[220:223], v163 offset:35840
	ds_read_b128 v[224:227], v163 offset:36864
	ds_read_b128 v[228:231], v163 offset:37888
	ds_read_b128 v[232:235], v163 offset:38912
	ds_read_b128 v[236:239], v163 offset:39936
	global_load_lds_dwordx4 v146, s[24:25]
	s_mov_b32 m0, s38
	s_nop 0
	global_load_lds_dwordx4 v150, s[24:25]
	s_waitcnt vmcnt(8) lgkmcnt(0)
	s_barrier
	s_setprio 1
	v_mfma_f32_16x16x32_bf16 v[142:145], v[164:167], v[196:199], v[142:145]
	v_mfma_f32_16x16x32_bf16 v[138:141], v[172:175], v[196:199], v[138:141]
	v_mfma_f32_16x16x32_bf16 v[126:129], v[164:167], v[216:219], v[126:129]
	v_mfma_f32_16x16x32_bf16 v[122:125], v[172:175], v[216:219], v[122:125]
	v_mfma_f32_16x16x32_bf16 v[110:113], v[164:167], v[224:227], v[110:113]
	v_mfma_f32_16x16x32_bf16 v[106:109], v[172:175], v[224:227], v[106:109]
	v_mfma_f32_16x16x32_bf16 v[94:97], v[164:167], v[232:235], v[94:97]
	v_mfma_f32_16x16x32_bf16 v[90:93], v[172:175], v[232:235], v[90:93]
	v_mfma_f32_16x16x32_bf16 v[142:145], v[168:171], v[200:203], v[142:145]
	v_mfma_f32_16x16x32_bf16 v[138:141], v[176:179], v[200:203], v[138:141]
	v_mfma_f32_16x16x32_bf16 v[126:129], v[168:171], v[220:223], v[126:129]
	v_mfma_f32_16x16x32_bf16 v[122:125], v[176:179], v[220:223], v[122:125]
	v_mfma_f32_16x16x32_bf16 v[110:113], v[168:171], v[228:231], v[110:113]
	v_mfma_f32_16x16x32_bf16 v[106:109], v[176:179], v[228:231], v[106:109]
	v_mfma_f32_16x16x32_bf16 v[94:97], v[168:171], v[236:239], v[94:97]
	v_mfma_f32_16x16x32_bf16 v[90:93], v[176:179], v[236:239], v[90:93]
	v_mfma_f32_16x16x32_bf16 v[134:137], v[180:183], v[196:199], v[134:137]
	v_mfma_f32_16x16x32_bf16 v[130:133], v[188:191], v[196:199], v[130:133]
	v_mfma_f32_16x16x32_bf16 v[118:121], v[180:183], v[216:219], v[118:121]
	v_mfma_f32_16x16x32_bf16 v[114:117], v[188:191], v[216:219], v[114:117]
	v_mfma_f32_16x16x32_bf16 v[102:105], v[180:183], v[224:227], v[102:105]
	v_mfma_f32_16x16x32_bf16 v[98:101], v[188:191], v[224:227], v[98:101]
	v_mfma_f32_16x16x32_bf16 v[86:89], v[180:183], v[232:235], v[86:89]
	v_mfma_f32_16x16x32_bf16 v[82:85], v[188:191], v[232:235], v[82:85]
	v_mfma_f32_16x16x32_bf16 v[134:137], v[184:187], v[200:203], v[134:137]
	v_mfma_f32_16x16x32_bf16 v[130:133], v[192:195], v[200:203], v[130:133]
	v_mfma_f32_16x16x32_bf16 v[118:121], v[184:187], v[220:223], v[118:121]
	v_mfma_f32_16x16x32_bf16 v[114:117], v[192:195], v[220:223], v[114:117]
	v_mfma_f32_16x16x32_bf16 v[102:105], v[184:187], v[228:231], v[102:105]
	v_mfma_f32_16x16x32_bf16 v[98:101], v[192:195], v[228:231], v[98:101]
	v_mfma_f32_16x16x32_bf16 v[86:89], v[184:187], v[236:239], v[86:89]
	v_mfma_f32_16x16x32_bf16 v[82:85], v[192:195], v[236:239], v[82:85]
	s_setprio 0
	s_barrier
; #define PG8_STAGE(bufoff, gbase, voff) do { _Pragma("unroll") for (int _i = 0; _i < 2; ++_i) \
;         __builtin_amdgcn_global_load_lds((const unsigned*)((const char*)(gbase) + (voff)[_i]), (PG8_LAS unsigned*)(lds + (bufoff) + ldsw + _i * 8192), 16, 0, 0); } while (0)
; #define PG8_LDA(dst, b, h) do { _Pragma("unroll") for (int m = 0; m < 4; ++m) _Pragma("unroll") for (int k = 0; k < 2; ++k) dst[m][k] = *(const PG8_LAS bf16x8*)(lds + PG8_SA(b, h) + aoff + m * 2048 + k * 1024); } while (0)
; #define PG8_WAIT_V(n) asm volatile("s_waitcnt vmcnt(" #n ")" ::: "memory")
; #define PG8_WAIT_L(n) asm volatile("s_waitcnt lgkmcnt(" #n ")" ::: "memory")
; #define PG8_BAR __builtin_amdgcn_s_barrier()
; template <class Epi, class Sched, bool ALIGN_EPI = false, bool SP2 = false>
; __device__ __forceinline__ void gemm_phase(PG8_LAS unsigned char* lds, const Gemm g, const Sched& S, const Epi& E) {
;     ...
;         for (int t = t_lo; t < t_hi; t += 2) {
;             const bool last = (t == nt - 2);
;             const char* a1 = cA + (size_t)(t + 1) * kstep;
;             const char* a2 = last ? nA : cA + (size_t)(t + 2) * kstep; const char* b2 = last ? nB : cB + (size_t)(t + 2) * kstep;
;             const char* a3 = a2 + kstep; const char* b3 = b2 + kstep;
;             if (last && has_next) S.a_ready_inloop(nxt, ui + 1);
;             if constexpr (SP2) {
;             PG8_LDB(B0, 0, 0); PG8_LDB(B1, 0, 1); PG8_SCHED; PG8_LDA(At, 0, 0); PG8_STAGE(PG8_SA(1, 1), a1 + hstep, voffA);
;             PG8_WAIT_V(8); PG8_WAIT_L(0); PG8_BAR; PG8_MMA(0, 0, At, B0); PG8_MMA(0, 1, At, B1); PG8_BAR; PG8_SCHED;
;             PG8_LDA(At, 0, 1); PG8_STAGE(PG8_SB(0, 0), b2, voffB); PG8_STAGE(PG8_SB(0, 1), b2 + hstep, voffB); PG8_STAGE(PG8_SA(0, 0), a2, voffA);
;             PG8_WAIT_V(8); PG8_WAIT_L(0); PG8_BAR; PG8_MMA(1, 0, At, B0); PG8_MMA(1, 1, At, B1); PG8_BAR; PG8_SCHED;
;             PG8_LDB(B0, 1, 0); PG8_LDB(B1, 1, 1); PG8_SCHED; PG8_LDA(At, 1, 0); PG8_STAGE(PG8_SA(0, 1), a2 + hstep, voffA);
;             PG8_WAIT_V(8); PG8_WAIT_L(0); PG8_BAR; PG8_MMA(0, 0, At, B0); PG8_MMA(0, 1, At, B1); PG8_BAR; PG8_SCHED;
;             PG8_LDA(At, 1, 1); PG8_STAGE(PG8_SB(1, 0), b3, voffB); PG8_STAGE(PG8_SB(1, 1), b3 + hstep, voffB); PG8_STAGE(PG8_SA(1, 0), a3, voffA);
;             PG8_WAIT_V(8); PG8_WAIT_L(0); PG8_BAR; PG8_MMA(1, 0, At, B0); PG8_MMA(1, 1, At, B1); PG8_BAR; PG8_SCHED;
	s_add_i32 s24, s82, s34
	s_mov_b32 m0, s24
	ds_read_b128 v[196:199], v163 offset:49152
	ds_read_b128 v[200:203], v163 offset:50176
	ds_read_b128 v[216:219], v163 offset:51200
	ds_read_b128 v[220:223], v163 offset:52224
	ds_read_b128 v[224:227], v163 offset:53248
	ds_read_b128 v[228:231], v163 offset:54272
	ds_read_b128 v[232:235], v163 offset:55296
	ds_read_b128 v[236:239], v163 offset:56320
	global_load_lds_dwordx4 v148, s[98:99]
	s_add_i32 m0, s24, 0x2000
	s_add_u32 s22, s22, 0x40080
	s_addc_u32 s23, s23, 0
	s_add_i32 s24, s83, s34
	global_load_lds_dwordx4 v152, s[98:99]
	s_mov_b32 m0, s24
	s_nop 0
	global_load_lds_dwordx4 v148, s[22:23]
	s_add_i32 m0, s24, 0x2000
	s_nop 0
	global_load_lds_dwordx4 v152, s[22:23]
	s_mov_b32 m0, s39
	s_nop 0
	global_load_lds_dwordx4 v146, s[100:101]
	s_mov_b32 m0, s42
	s_nop 0
	global_load_lds_dwordx4 v150, s[100:101]
	s_waitcnt vmcnt(8) lgkmcnt(0)
	s_barrier
	s_setprio 1
	v_mfma_f32_16x16x32_bf16 v[78:81], v[164:167], v[196:199], v[78:81]
	v_mfma_f32_16x16x32_bf16 v[74:77], v[172:175], v[196:199], v[74:77]
	v_mfma_f32_16x16x32_bf16 v[62:65], v[164:167], v[216:219], v[62:65]
	v_mfma_f32_16x16x32_bf16 v[58:61], v[172:175], v[216:219], v[58:61]
	v_mfma_f32_16x16x32_bf16 v[46:49], v[164:167], v[224:227], v[46:49]
	v_mfma_f32_16x16x32_bf16 v[42:45], v[172:175], v[224:227], v[42:45]
	v_mfma_f32_16x16x32_bf16 v[30:33], v[164:167], v[232:235], v[30:33]
	v_mfma_f32_16x16x32_bf16 v[26:29], v[172:175], v[232:235], v[26:29]
	v_mfma_f32_16x16x32_bf16 v[78:81], v[168:171], v[200:203], v[78:81]
	v_mfma_f32_16x16x32_bf16 v[74:77], v[176:179], v[200:203], v[74:77]
	v_mfma_f32_16x16x32_bf16 v[62:65], v[168:171], v[220:223], v[62:65]
	v_mfma_f32_16x16x32_bf16 v[58:61], v[176:179], v[220:223], v[58:61]
	v_mfma_f32_16x16x32_bf16 v[46:49], v[168:171], v[228:231], v[46:49]
	v_mfma_f32_16x16x32_bf16 v[42:45], v[176:179], v[228:231], v[42:45]
	v_mfma_f32_16x16x32_bf16 v[30:33], v[168:171], v[236:239], v[30:33]
	v_mfma_f32_16x16x32_bf16 v[26:29], v[176:179], v[236:239], v[26:29]
	v_mfma_f32_16x16x32_bf16 v[70:73], v[180:183], v[196:199], v[70:73]
	v_mfma_f32_16x16x32_bf16 v[66:69], v[188:191], v[196:199], v[66:69]
	v_mfma_f32_16x16x32_bf16 v[54:57], v[180:183], v[216:219], v[54:57]
	v_mfma_f32_16x16x32_bf16 v[50:53], v[188:191], v[216:219], v[50:53]
	v_mfma_f32_16x16x32_bf16 v[38:41], v[180:183], v[224:227], v[38:41]
	v_mfma_f32_16x16x32_bf16 v[34:37], v[188:191], v[224:227], v[34:37]
	v_mfma_f32_16x16x32_bf16 v[22:25], v[180:183], v[232:235], v[22:25]
	v_mfma_f32_16x16x32_bf16 v[18:21], v[188:191], v[232:235], v[18:21]
	v_mfma_f32_16x16x32_bf16 v[70:73], v[184:187], v[200:203], v[70:73]
	v_mfma_f32_16x16x32_bf16 v[66:69], v[192:195], v[200:203], v[66:69]
	v_mfma_f32_16x16x32_bf16 v[54:57], v[184:187], v[220:223], v[54:57]
	v_mfma_f32_16x16x32_bf16 v[50:53], v[192:195], v[220:223], v[50:53]
	v_mfma_f32_16x16x32_bf16 v[38:41], v[184:187], v[228:231], v[38:41]
	v_mfma_f32_16x16x32_bf16 v[34:37], v[192:195], v[228:231], v[34:37]
	v_mfma_f32_16x16x32_bf16 v[22:25], v[184:187], v[236:239], v[22:25]
	v_mfma_f32_16x16x32_bf16 v[18:21], v[192:195], v[236:239], v[18:21]
	s_setprio 0
	s_barrier
	s_add_i32 s64, s64, 2
	s_add_u32 s20, s20, 0x100
	s_addc_u32 s21, s21, 0
	s_add_u32 s62, s62, 0x100
	s_addc_u32 s63, s63, 0
.LBB0_121:
	s_add_u32 s22, s20, 0xfffc0080
	s_addc_u32 s23, s21, -1
	s_add_i32 s90, 0, 0x10000
	s_cmp_eq_u32 s64, 12
	s_cselect_b32 s25, s13, s23
	s_cselect_b32 s24, s52, s22
	v_add_u32_e32 v158, s90, v160
	s_cselect_b32 s23, s15, s63
	s_cselect_b32 s22, s53, s62
	s_add_u32 s98, s22, s46
	s_addc_u32 s99, s23, s47
	s_add_u32 s100, s24, s46
	s_addc_u32 s101, s25, s47
	s_add_i32 s81, 0, 0x14000
	ds_read_b128 v[164:167], v158
	ds_read_b128 v[168:171], v158 offset:1024
	ds_read_b128 v[172:175], v158 offset:2048
	ds_read_b128 v[176:179], v158 offset:3072
	v_add_u32_e32 v158, s81, v160
	ds_read_b128 v[180:183], v158
	ds_read_b128 v[184:187], v158 offset:1024
	ds_read_b128 v[188:191], v158 offset:2048
	ds_read_b128 v[192:195], v158 offset:3072
	s_add_i32 m0, s35, 0xc000
	ds_read_b128 v[196:199], v163
	ds_read_b128 v[200:203], v163 offset:1024
	ds_read_b128 v[216:219], v163 offset:2048
	ds_read_b128 v[220:223], v163 offset:3072
	ds_read_b128 v[224:227], v163 offset:4096
	ds_read_b128 v[228:231], v163 offset:5120
	ds_read_b128 v[232:235], v163 offset:6144
	ds_read_b128 v[236:239], v163 offset:7168
	global_load_lds_dwordx4 v154, s[20:21]
	s_add_i32 m0, s35, 0xe000
	s_nop 0
	global_load_lds_dwordx4 v156, s[20:21]
	s_waitcnt vmcnt(8) lgkmcnt(0)
	s_barrier
; #define PG8_STAGE(bufoff, gbase, voff) do { _Pragma("unroll") for (int _i = 0; _i < 2; ++_i) \
;         __builtin_amdgcn_global_load_lds((const unsigned*)((const char*)(gbase) + (voff)[_i]), (PG8_LAS unsigned*)(lds + (bufoff) + ldsw + _i * 8192), 16, 0, 0); } while (0)
; #define PG8_LDA(dst, b, h) do { _Pragma("unroll") for (int m = 0; m < 4; ++m) _Pragma("unroll") for (int k = 0; k < 2; ++k) dst[m][k] = *(const PG8_LAS bf16x8*)(lds + PG8_SA(b, h) + aoff + m * 2048 + k * 1024); } while (0)
; #define PG8_MMA(ai, bj, At, Bt) do { __builtin_amdgcn_s_setprio(1); _Pragma("unroll") for (int m = 0; m < 4; ++m) _Pragma("unroll") for (int n = 0; n < 2; ++n) _Pragma("unroll") for (int k = 0; k < 2; ++k) \
;         acc[ai][bj][m][n] = __builtin_amdgcn_mfma_f32_16x16x32_bf16(Bt[n][k], At[m][k], acc[ai][bj][m][n], 0, 0, 0); __builtin_amdgcn_s_setprio(0); } while (0)
; #define PG8_WAIT_V(n) asm volatile("s_waitcnt vmcnt(" #n ")" ::: "memory")
; #define PG8_WAIT_L(n) asm volatile("s_waitcnt lgkmcnt(" #n ")" ::: "memory")
; #define PG8_BAR __builtin_amdgcn_s_barrier()
; #define PG8_SCHED __builtin_amdgcn_sched_barrier(0)
; template <class Epi, class Sched, bool ALIGN_EPI = false, bool SP2 = false>
; __device__ __forceinline__ void gemm_phase(PG8_LAS unsigned char* lds, const Gemm g, const Sched& S, const Epi& E) {
;     ...
;             PG8_WAIT_V(8); PG8_WAIT_L(0); PG8_BAR; PG8_MMA(0, 0, At, B0); PG8_MMA(0, 1, At, B1); PG8_BAR; PG8_SCHED;
;             PG8_LDA(At, 0, 1); PG8_STAGE(PG8_SB(0, 0), b2, voffB); PG8_STAGE(PG8_SB(0, 1), b2 + hstep, voffB); PG8_STAGE(PG8_SA(0, 0), a2, voffA);
;             PG8_WAIT_V(8); PG8_WAIT_L(0); PG8_BAR; PG8_MMA(1, 0, At, B0); PG8_MMA(1, 1, At, B1); PG8_BAR; PG8_SCHED;
	s_setprio 1
	v_mfma_f32_16x16x32_bf16 v[142:145], v[164:167], v[196:199], v[142:145]
	v_mfma_f32_16x16x32_bf16 v[138:141], v[172:175], v[196:199], v[138:141]
	v_mfma_f32_16x16x32_bf16 v[126:129], v[164:167], v[216:219], v[126:129]
	v_mfma_f32_16x16x32_bf16 v[122:125], v[172:175], v[216:219], v[122:125]
	v_mfma_f32_16x16x32_bf16 v[110:113], v[164:167], v[224:227], v[110:113]
	v_mfma_f32_16x16x32_bf16 v[106:109], v[172:175], v[224:227], v[106:109]
	v_mfma_f32_16x16x32_bf16 v[94:97], v[164:167], v[232:235], v[94:97]
	v_mfma_f32_16x16x32_bf16 v[90:93], v[172:175], v[232:235], v[90:93]
	v_mfma_f32_16x16x32_bf16 v[142:145], v[168:171], v[200:203], v[142:145]
	v_mfma_f32_16x16x32_bf16 v[138:141], v[176:179], v[200:203], v[138:141]
	v_mfma_f32_16x16x32_bf16 v[126:129], v[168:171], v[220:223], v[126:129]
	v_mfma_f32_16x16x32_bf16 v[122:125], v[176:179], v[220:223], v[122:125]
	v_mfma_f32_16x16x32_bf16 v[110:113], v[168:171], v[228:231], v[110:113]
	v_mfma_f32_16x16x32_bf16 v[106:109], v[176:179], v[228:231], v[106:109]
	v_mfma_f32_16x16x32_bf16 v[94:97], v[168:171], v[236:239], v[94:97]
	v_mfma_f32_16x16x32_bf16 v[90:93], v[176:179], v[236:239], v[90:93]
	v_mfma_f32_16x16x32_bf16 v[134:137], v[180:183], v[196:199], v[134:137]
	v_mfma_f32_16x16x32_bf16 v[130:133], v[188:191], v[196:199], v[130:133]
	v_mfma_f32_16x16x32_bf16 v[118:121], v[180:183], v[216:219], v[118:121]
	v_mfma_f32_16x16x32_bf16 v[114:117], v[188:191], v[216:219], v[114:117]
	v_mfma_f32_16x16x32_bf16 v[102:105], v[180:183], v[224:227], v[102:105]
	v_mfma_f32_16x16x32_bf16 v[98:101], v[188:191], v[224:227], v[98:101]
	v_mfma_f32_16x16x32_bf16 v[86:89], v[180:183], v[232:235], v[86:89]
	v_mfma_f32_16x16x32_bf16 v[82:85], v[188:191], v[232:235], v[82:85]
	v_mfma_f32_16x16x32_bf16 v[134:137], v[184:187], v[200:203], v[134:137]
	v_mfma_f32_16x16x32_bf16 v[130:133], v[192:195], v[200:203], v[130:133]
	v_mfma_f32_16x16x32_bf16 v[118:121], v[184:187], v[220:223], v[118:121]
	v_mfma_f32_16x16x32_bf16 v[114:117], v[192:195], v[220:223], v[114:117]
	v_mfma_f32_16x16x32_bf16 v[102:105], v[184:187], v[228:231], v[102:105]
	v_mfma_f32_16x16x32_bf16 v[98:101], v[192:195], v[228:231], v[98:101]
	v_mfma_f32_16x16x32_bf16 v[86:89], v[184:187], v[236:239], v[86:89]
	v_mfma_f32_16x16x32_bf16 v[82:85], v[192:195], v[236:239], v[82:85]
	s_setprio 0
	s_barrier
	s_add_i32 s65, s90, s34
	s_mov_b32 m0, s65
	ds_read_b128 v[196:199], v163 offset:16384
	ds_read_b128 v[200:203], v163 offset:17408
	ds_read_b128 v[216:219], v163 offset:18432
	ds_read_b128 v[220:223], v163 offset:19456
	ds_read_b128 v[224:227], v163 offset:20480
	ds_read_b128 v[228:231], v163 offset:21504
	ds_read_b128 v[232:235], v163 offset:22528
	ds_read_b128 v[236:239], v163 offset:23552
	global_load_lds_dwordx4 v148, s[22:23]
	s_add_i32 m0, s65, 0x2000
	s_add_u32 s66, s22, 0x40000
	s_addc_u32 s67, s23, 0
	s_add_i32 s65, s81, s34
	global_load_lds_dwordx4 v152, s[22:23]
	s_mov_b32 m0, s65
	s_nop 0
	global_load_lds_dwordx4 v148, s[66:67]
	s_add_i32 m0, s65, 0x2000
	s_nop 0
	global_load_lds_dwordx4 v152, s[66:67]
	s_mov_b32 m0, s35
	s_nop 0
	global_load_lds_dwordx4 v146, s[24:25]
	s_mov_b32 m0, s36
	s_nop 0
	global_load_lds_dwordx4 v150, s[24:25]
	s_waitcnt vmcnt(8) lgkmcnt(0)
	s_barrier
	s_setprio 1
	v_mfma_f32_16x16x32_bf16 v[78:81], v[164:167], v[196:199], v[78:81]
	v_mfma_f32_16x16x32_bf16 v[74:77], v[172:175], v[196:199], v[74:77]
	v_mfma_f32_16x16x32_bf16 v[62:65], v[164:167], v[216:219], v[62:65]
	v_mfma_f32_16x16x32_bf16 v[58:61], v[172:175], v[216:219], v[58:61]
	v_mfma_f32_16x16x32_bf16 v[46:49], v[164:167], v[224:227], v[46:49]
	v_mfma_f32_16x16x32_bf16 v[42:45], v[172:175], v[224:227], v[42:45]
	v_mfma_f32_16x16x32_bf16 v[30:33], v[164:167], v[232:235], v[30:33]
	v_mfma_f32_16x16x32_bf16 v[26:29], v[172:175], v[232:235], v[26:29]
	v_mfma_f32_16x16x32_bf16 v[78:81], v[168:171], v[200:203], v[78:81]
	v_mfma_f32_16x16x32_bf16 v[74:77], v[176:179], v[200:203], v[74:77]
	v_mfma_f32_16x16x32_bf16 v[62:65], v[168:171], v[220:223], v[62:65]
	v_mfma_f32_16x16x32_bf16 v[58:61], v[176:179], v[220:223], v[58:61]
	v_mfma_f32_16x16x32_bf16 v[46:49], v[168:171], v[228:231], v[46:49]
	v_mfma_f32_16x16x32_bf16 v[42:45], v[176:179], v[228:231], v[42:45]
	v_mfma_f32_16x16x32_bf16 v[30:33], v[168:171], v[236:239], v[30:33]
	v_mfma_f32_16x16x32_bf16 v[26:29], v[176:179], v[236:239], v[26:29]
	v_mfma_f32_16x16x32_bf16 v[70:73], v[180:183], v[196:199], v[70:73]
	v_mfma_f32_16x16x32_bf16 v[66:69], v[188:191], v[196:199], v[66:69]
	v_mfma_f32_16x16x32_bf16 v[54:57], v[180:183], v[216:219], v[54:57]
	v_mfma_f32_16x16x32_bf16 v[50:53], v[188:191], v[216:219], v[50:53]
	v_mfma_f32_16x16x32_bf16 v[38:41], v[180:183], v[224:227], v[38:41]
	v_mfma_f32_16x16x32_bf16 v[34:37], v[188:191], v[224:227], v[34:37]
	v_mfma_f32_16x16x32_bf16 v[22:25], v[180:183], v[232:235], v[22:25]
	v_mfma_f32_16x16x32_bf16 v[18:21], v[188:191], v[232:235], v[18:21]
	v_mfma_f32_16x16x32_bf16 v[70:73], v[184:187], v[200:203], v[70:73]
	v_mfma_f32_16x16x32_bf16 v[66:69], v[192:195], v[200:203], v[66:69]
	v_mfma_f32_16x16x32_bf16 v[54:57], v[184:187], v[220:223], v[54:57]
	v_mfma_f32_16x16x32_bf16 v[50:53], v[192:195], v[220:223], v[50:53]
	v_mfma_f32_16x16x32_bf16 v[38:41], v[184:187], v[228:231], v[38:41]
	v_mfma_f32_16x16x32_bf16 v[34:37], v[192:195], v[228:231], v[34:37]
	v_mfma_f32_16x16x32_bf16 v[22:25], v[184:187], v[236:239], v[22:25]
	v_mfma_f32_16x16x32_bf16 v[18:21], v[192:195], v[236:239], v[18:21]
	s_setprio 0
	s_barrier
; #define PG8_STAGE(bufoff, gbase, voff) do { _Pragma("unroll") for (int _i = 0; _i < 2; ++_i) \
;         __builtin_amdgcn_global_load_lds((const unsigned*)((const char*)(gbase) + (voff)[_i]), (PG8_LAS unsigned*)(lds + (bufoff) + ldsw + _i * 8192), 16, 0, 0); } while (0)
; #define PG8_LDA(dst, b, h) do { _Pragma("unroll") for (int m = 0; m < 4; ++m) _Pragma("unroll") for (int k = 0; k < 2; ++k) dst[m][k] = *(const PG8_LAS bf16x8*)(lds + PG8_SA(b, h) + aoff + m * 2048 + k * 1024); } while (0)
; #define PG8_LDB(dst, b, h) do { _Pragma("unroll") for (int n = 0; n < 2; ++n) _Pragma("unroll") for (int k = 0; k < 2; ++k) dst[n][k] = *(const PG8_LAS bf16x8*)(lds + PG8_SB(b, h) + boff + n * 2048 + k * 1024); } while (0)
; #define PG8_MMA(ai, bj, At, Bt) do { __builtin_amdgcn_s_setprio(1); _Pragma("unroll") for (int m = 0; m < 4; ++m) _Pragma("unroll") for (int n = 0; n < 2; ++n) _Pragma("unroll") for (int k = 0; k < 2; ++k) \
;         acc[ai][bj][m][n] = __builtin_amdgcn_mfma_f32_16x16x32_bf16(Bt[n][k], At[m][k], acc[ai][bj][m][n], 0, 0, 0); __builtin_amdgcn_s_setprio(0); } while (0)
; #define PG8_WAIT_V(n) asm volatile("s_waitcnt vmcnt(" #n ")" ::: "memory")
; #define PG8_WAIT_L(n) asm volatile("s_waitcnt lgkmcnt(" #n ")" ::: "memory")
; #define PG8_BAR __builtin_amdgcn_s_barrier()
; #define PG8_SCHED __builtin_amdgcn_sched_barrier(0)
; template <class Epi, class Sched, bool ALIGN_EPI = false, bool SP2 = false>
; __device__ __forceinline__ void gemm_phase(PG8_LAS unsigned char* lds, const Gemm g, const Sched& S, const Epi& E) {
;     ...
;             PG8_LDB(B0, 1, 0); PG8_LDB(B1, 1, 1); PG8_SCHED; PG8_LDA(At, 1, 0); PG8_STAGE(PG8_SA(0, 1), a2 + hstep, voffA);
;             PG8_WAIT_V(8); PG8_WAIT_L(0); PG8_BAR; PG8_MMA(0, 0, At, B0); PG8_MMA(0, 1, At, B1); PG8_BAR; PG8_SCHED;
;             PG8_LDA(At, 1, 1); PG8_STAGE(PG8_SB(1, 0), b3, voffB); PG8_STAGE(PG8_SB(1, 1), b3 + hstep, voffB); PG8_STAGE(PG8_SA(1, 0), a3, voffA);
;             PG8_WAIT_V(8); PG8_WAIT_L(0); PG8_BAR; PG8_MMA(1, 0, At, B0); PG8_MMA(1, 1, At, B1); PG8_BAR; PG8_SCHED;
;     ...
;         if constexpr (ALIGN_EPI) { if (wr == 0) PG8_BAR; }
	s_add_i32 s82, 0, 0x18000
	s_add_i32 s83, 0, 0x1c000
	v_add_u32_e32 v176, s82, v160
	v_add_u32_e32 v192, s83, v160
	ds_read_b128 v[164:167], v176
	ds_read_b128 v[168:171], v176 offset:1024
	ds_read_b128 v[172:175], v176 offset:2048
	ds_read_b128 v[176:179], v176 offset:3072
	ds_read_b128 v[180:183], v192
	ds_read_b128 v[184:187], v192 offset:1024
	ds_read_b128 v[188:191], v192 offset:2048
	ds_read_b128 v[192:195], v192 offset:3072
	s_add_u32 s24, s24, 0x40000
	s_addc_u32 s25, s25, 0
	s_mov_b32 m0, s37
	ds_read_b128 v[196:199], v163 offset:32768
	ds_read_b128 v[200:203], v163 offset:33792
	ds_read_b128 v[216:219], v163 offset:34816
	ds_read_b128 v[220:223], v163 offset:35840
	ds_read_b128 v[224:227], v163 offset:36864
	ds_read_b128 v[228:231], v163 offset:37888
	ds_read_b128 v[232:235], v163 offset:38912
	ds_read_b128 v[236:239], v163 offset:39936
	global_load_lds_dwordx4 v146, s[24:25]
	s_mov_b32 m0, s38
	s_nop 0
	global_load_lds_dwordx4 v150, s[24:25]
	s_waitcnt vmcnt(8) lgkmcnt(0)
	s_barrier
	s_setprio 1
	v_mfma_f32_16x16x32_bf16 v[142:145], v[164:167], v[196:199], v[142:145]
	v_mfma_f32_16x16x32_bf16 v[138:141], v[172:175], v[196:199], v[138:141]
	v_mfma_f32_16x16x32_bf16 v[126:129], v[164:167], v[216:219], v[126:129]
	v_mfma_f32_16x16x32_bf16 v[122:125], v[172:175], v[216:219], v[122:125]
	v_mfma_f32_16x16x32_bf16 v[110:113], v[164:167], v[224:227], v[110:113]
	v_mfma_f32_16x16x32_bf16 v[106:109], v[172:175], v[224:227], v[106:109]
	v_mfma_f32_16x16x32_bf16 v[94:97], v[164:167], v[232:235], v[94:97]
	v_mfma_f32_16x16x32_bf16 v[90:93], v[172:175], v[232:235], v[90:93]
	v_mfma_f32_16x16x32_bf16 v[142:145], v[168:171], v[200:203], v[142:145]
	v_mfma_f32_16x16x32_bf16 v[138:141], v[176:179], v[200:203], v[138:141]
	v_mfma_f32_16x16x32_bf16 v[126:129], v[168:171], v[220:223], v[126:129]
	v_mfma_f32_16x16x32_bf16 v[122:125], v[176:179], v[220:223], v[122:125]
	v_mfma_f32_16x16x32_bf16 v[110:113], v[168:171], v[228:231], v[110:113]
	v_mfma_f32_16x16x32_bf16 v[106:109], v[176:179], v[228:231], v[106:109]
	v_mfma_f32_16x16x32_bf16 v[94:97], v[168:171], v[236:239], v[94:97]
	v_mfma_f32_16x16x32_bf16 v[90:93], v[176:179], v[236:239], v[90:93]
	v_mfma_f32_16x16x32_bf16 v[134:137], v[180:183], v[196:199], v[134:137]
	v_mfma_f32_16x16x32_bf16 v[130:133], v[188:191], v[196:199], v[130:133]
	v_mfma_f32_16x16x32_bf16 v[118:121], v[180:183], v[216:219], v[118:121]
	v_mfma_f32_16x16x32_bf16 v[114:117], v[188:191], v[216:219], v[114:117]
	v_mfma_f32_16x16x32_bf16 v[102:105], v[180:183], v[224:227], v[102:105]
	v_mfma_f32_16x16x32_bf16 v[98:101], v[188:191], v[224:227], v[98:101]
	v_mfma_f32_16x16x32_bf16 v[86:89], v[180:183], v[232:235], v[86:89]
	v_mfma_f32_16x16x32_bf16 v[82:85], v[188:191], v[232:235], v[82:85]
	v_mfma_f32_16x16x32_bf16 v[134:137], v[184:187], v[200:203], v[134:137]
	v_mfma_f32_16x16x32_bf16 v[130:133], v[192:195], v[200:203], v[130:133]
	v_mfma_f32_16x16x32_bf16 v[118:121], v[184:187], v[220:223], v[118:121]
	v_mfma_f32_16x16x32_bf16 v[114:117], v[192:195], v[220:223], v[114:117]
	v_mfma_f32_16x16x32_bf16 v[102:105], v[184:187], v[228:231], v[102:105]
	v_mfma_f32_16x16x32_bf16 v[98:101], v[192:195], v[228:231], v[98:101]
	v_mfma_f32_16x16x32_bf16 v[86:89], v[184:187], v[236:239], v[86:89]
	v_mfma_f32_16x16x32_bf16 v[82:85], v[192:195], v[236:239], v[82:85]
	s_setprio 0
	s_barrier
	s_add_i32 s24, s82, s34
	s_mov_b32 m0, s24
	ds_read_b128 v[196:199], v163 offset:49152
	ds_read_b128 v[200:203], v163 offset:50176
	ds_read_b128 v[216:219], v163 offset:51200
	ds_read_b128 v[220:223], v163 offset:52224
	ds_read_b128 v[224:227], v163 offset:53248
	ds_read_b128 v[228:231], v163 offset:54272
	ds_read_b128 v[232:235], v163 offset:55296
	ds_read_b128 v[236:239], v163 offset:56320
	global_load_lds_dwordx4 v148, s[98:99]
	s_add_i32 m0, s24, 0x2000
	s_add_u32 s22, s22, 0x40080
	s_addc_u32 s23, s23, 0
	s_add_i32 s24, s83, s34
	global_load_lds_dwordx4 v152, s[98:99]
	s_mov_b32 m0, s24
	s_nop 0
	global_load_lds_dwordx4 v148, s[22:23]
	s_add_i32 m0, s24, 0x2000
	s_nop 0
	global_load_lds_dwordx4 v152, s[22:23]
	s_mov_b32 m0, s39
	s_nop 0
	global_load_lds_dwordx4 v146, s[100:101]
	s_mov_b32 m0, s42
	s_nop 0
	global_load_lds_dwordx4 v150, s[100:101]
	s_waitcnt vmcnt(8) lgkmcnt(0)
	s_barrier
	s_setprio 1
	v_mfma_f32_16x16x32_bf16 v[78:81], v[164:167], v[196:199], v[78:81]
	v_mfma_f32_16x16x32_bf16 v[74:77], v[172:175], v[196:199], v[74:77]
	v_mfma_f32_16x16x32_bf16 v[62:65], v[164:167], v[216:219], v[62:65]
	v_mfma_f32_16x16x32_bf16 v[58:61], v[172:175], v[216:219], v[58:61]
	v_mfma_f32_16x16x32_bf16 v[46:49], v[164:167], v[224:227], v[46:49]
	v_mfma_f32_16x16x32_bf16 v[42:45], v[172:175], v[224:227], v[42:45]
	v_mfma_f32_16x16x32_bf16 v[30:33], v[164:167], v[232:235], v[30:33]
	v_mfma_f32_16x16x32_bf16 v[26:29], v[172:175], v[232:235], v[26:29]
	v_mfma_f32_16x16x32_bf16 v[78:81], v[168:171], v[200:203], v[78:81]
	v_mfma_f32_16x16x32_bf16 v[74:77], v[176:179], v[200:203], v[74:77]
	v_mfma_f32_16x16x32_bf16 v[62:65], v[168:171], v[220:223], v[62:65]
	v_mfma_f32_16x16x32_bf16 v[58:61], v[176:179], v[220:223], v[58:61]
	v_mfma_f32_16x16x32_bf16 v[46:49], v[168:171], v[228:231], v[46:49]
	v_mfma_f32_16x16x32_bf16 v[42:45], v[176:179], v[228:231], v[42:45]
	v_mfma_f32_16x16x32_bf16 v[30:33], v[168:171], v[236:239], v[30:33]
	v_mfma_f32_16x16x32_bf16 v[26:29], v[176:179], v[236:239], v[26:29]
	v_mfma_f32_16x16x32_bf16 v[70:73], v[180:183], v[196:199], v[70:73]
	v_mfma_f32_16x16x32_bf16 v[66:69], v[188:191], v[196:199], v[66:69]
	v_mfma_f32_16x16x32_bf16 v[54:57], v[180:183], v[216:219], v[54:57]
	v_mfma_f32_16x16x32_bf16 v[50:53], v[188:191], v[216:219], v[50:53]
	v_mfma_f32_16x16x32_bf16 v[38:41], v[180:183], v[224:227], v[38:41]
	v_mfma_f32_16x16x32_bf16 v[34:37], v[188:191], v[224:227], v[34:37]
	v_mfma_f32_16x16x32_bf16 v[22:25], v[180:183], v[232:235], v[22:25]
	v_mfma_f32_16x16x32_bf16 v[18:21], v[188:191], v[232:235], v[18:21]
	v_mfma_f32_16x16x32_bf16 v[70:73], v[184:187], v[200:203], v[70:73]
	v_mfma_f32_16x16x32_bf16 v[66:69], v[192:195], v[200:203], v[66:69]
	v_mfma_f32_16x16x32_bf16 v[54:57], v[184:187], v[220:223], v[54:57]
	v_mfma_f32_16x16x32_bf16 v[50:53], v[192:195], v[220:223], v[50:53]
	v_mfma_f32_16x16x32_bf16 v[38:41], v[184:187], v[228:231], v[38:41]
	v_mfma_f32_16x16x32_bf16 v[34:37], v[192:195], v[228:231], v[34:37]
	v_mfma_f32_16x16x32_bf16 v[22:25], v[184:187], v[236:239], v[22:25]
	v_mfma_f32_16x16x32_bf16 v[18:21], v[192:195], v[236:239], v[18:21]
	s_setprio 0
	s_barrier
	s_add_i32 s64, s64, 2
	s_add_u32 s20, s20, 0x100
	s_addc_u32 s21, s21, 0
	s_add_u32 s62, s62, 0x100
	s_addc_u32 s63, s63, 0
	s_cmp_gt_u32 s64, 13
	s_cbranch_scc0 .LBB0_121
	s_and_b64 vcc, exec, s[10:11]
	s_cbranch_vccz .LBB0_124
	s_barrier

; #define PG8_STAGE(bufoff, gbase, voff) do { _Pragma("unroll") for (int _i = 0; _i < 2; ++_i) \
;         __builtin_amdgcn_global_load_lds((const unsigned*)((const char*)(gbase) + (voff)[_i]), (PG8_LAS unsigned*)(lds + (bufoff) + ldsw + _i * 8192), 16, 0, 0); } while (0)
; #define PG8_LDA(dst, b, h) do { _Pragma("unroll") for (int m = 0; m < 4; ++m) _Pragma("unroll") for (int k = 0; k < 2; ++k) dst[m][k] = *(const PG8_LAS bf16x8*)(lds + PG8_SA(b, h) + aoff + m * 2048 + k * 1024); } while (0)
; #define PG8_LDB(dst, b, h) do { _Pragma("unroll") for (int n = 0; n < 2; ++n) _Pragma("unroll") for (int k = 0; k < 2; ++k) dst[n][k] = *(const PG8_LAS bf16x8*)(lds + PG8_SB(b, h) + boff + n * 2048 + k * 1024); } while (0)
; #define PG8_MMA(ai, bj, At, Bt) do { __builtin_amdgcn_s_setprio(1); _Pragma("unroll") for (int m = 0; m < 4; ++m) _Pragma("unroll") for (int n = 0; n < 2; ++n) _Pragma("unroll") for (int k = 0; k < 2; ++k) \
;         acc[ai][bj][m][n] = __builtin_amdgcn_mfma_f32_16x16x32_bf16(Bt[n][k], At[m][k], acc[ai][bj][m][n], 0, 0, 0); __builtin_amdgcn_s_setprio(0); } while (0)
; #define PG8_WAIT_V(n) asm volatile("s_waitcnt vmcnt(" #n ")" ::: "memory")
; #define PG8_WAIT_L(n) asm volatile("s_waitcnt lgkmcnt(" #n ")" ::: "memory")
; #define PG8_BAR __builtin_amdgcn_s_barrier()
; #define PG8_SCHED __builtin_amdgcn_sched_barrier(0)
; template <class Epi, class Sched, bool ALIGN_EPI = false, bool SP2 = false>
; __device__ __forceinline__ void gemm_phase(PG8_LAS unsigned char* lds, const Gemm g, const Sched& S, const Epi& E) {
;     ...
;             const char* a2 = last ? nA : cA + (size_t)(t + 2) * kstep; const char* b2 = last ? nB : cB + (size_t)(t + 2) * kstep;
;             const char* a3 = a2 + kstep; const char* b3 = b2 + kstep;
;             if (last && has_next) S.a_ready_inloop(nxt, ui + 1);
;             if constexpr (SP2) {
;             PG8_LDB(B0, 0, 0); PG8_LDB(B1, 0, 1); PG8_SCHED; PG8_LDA(At, 0, 0); PG8_STAGE(PG8_SA(1, 1), a1 + hstep, voffA);
;             PG8_WAIT_V(8); PG8_WAIT_L(0); PG8_BAR; PG8_MMA(0, 0, At, B0); PG8_MMA(0, 1, At, B1); PG8_BAR; PG8_SCHED;
;             PG8_LDA(At, 0, 1); PG8_STAGE(PG8_SB(0, 0), b2, voffB); PG8_STAGE(PG8_SB(0, 1), b2 + hstep, voffB); PG8_STAGE(PG8_SA(0, 0), a2, voffA);
;             PG8_WAIT_V(8); PG8_WAIT_L(0); PG8_BAR; PG8_MMA(1, 0, At, B0); PG8_MMA(1, 1, At, B1); PG8_BAR; PG8_SCHED;
.LBB0_211:
	s_mov_b64 s[18:19], s[6:7]
	s_mov_b64 s[20:21], s[14:15]
	s_and_b64 s[6:7], s[16:17], exec
	s_cselect_b32 s7, s37, s19
	s_cselect_b32 s6, s36, s18
	s_cselect_b32 s15, s3, s21
	s_cselect_b32 s14, s2, s20
	s_add_u32 s39, s20, 0x100
	s_addc_u32 s42, s21, 0
	s_mov_b32 s44, -2
	v_add_u32_e32 v142, s90, v188
	v_add_u32_e32 v172, s81, v188
	ds_read_b128 v[130:133], v142
	ds_read_b128 v[134:137], v142 offset:1024
	ds_read_b128 v[138:141], v142 offset:2048
	ds_read_b128 v[142:145], v142 offset:3072
	ds_read_b128 v[146:149], v172
	ds_read_b128 v[150:153], v172 offset:1024
	ds_read_b128 v[154:157], v172 offset:2048
	ds_read_b128 v[172:175], v172 offset:3072
	s_add_u32 s20, s18, 0x100
	s_addc_u32 s21, s19, 0
	s_cmp_eq_u32 s44, 40
	s_cselect_b32 s25, s7, s21
	s_cselect_b32 s24, s6, s20
	s_cselect_b32 s23, s15, s42
	s_cselect_b32 s22, s14, s39
	s_add_u32 s98, s22, s46
	s_addc_u32 s99, s23, s47
	s_add_u32 s100, s24, s46
	s_addc_u32 s101, s25, s47
	s_add_i32 m0, s27, 0xc000
	ds_read_b128 v[176:179], v189
	ds_read_b128 v[180:183], v189 offset:1024
	ds_read_b128 v[184:187], v189 offset:2048
	ds_read_b128 v[190:193], v189 offset:3072
	ds_read_b128 v[194:197], v189 offset:4096
	ds_read_b128 v[198:201], v189 offset:5120
	ds_read_b128 v[216:219], v189 offset:6144
	ds_read_b128 v[220:223], v189 offset:7168
	global_load_lds_dwordx4 v168, s[18:19]
	s_add_i32 m0, s27, 0xe000
	s_nop 0
	global_load_lds_dwordx4 v170, s[18:19]
	s_waitcnt vmcnt(8) lgkmcnt(0)
	s_barrier
	s_setprio 1
	v_mfma_f32_16x16x32_bf16 v[126:129], v[130:133], v[176:179], 0
	v_mfma_f32_16x16x32_bf16 v[122:125], v[138:141], v[176:179], 0
	v_mfma_f32_16x16x32_bf16 v[110:113], v[130:133], v[184:187], 0
	v_mfma_f32_16x16x32_bf16 v[106:109], v[138:141], v[184:187], 0
	v_mfma_f32_16x16x32_bf16 v[94:97], v[130:133], v[194:197], 0
	v_mfma_f32_16x16x32_bf16 v[90:93], v[138:141], v[194:197], 0
	v_mfma_f32_16x16x32_bf16 v[78:81], v[130:133], v[216:219], 0
	v_mfma_f32_16x16x32_bf16 v[74:77], v[138:141], v[216:219], 0
	v_mfma_f32_16x16x32_bf16 v[126:129], v[134:137], v[180:183], v[126:129]
	v_mfma_f32_16x16x32_bf16 v[122:125], v[142:145], v[180:183], v[122:125]
	v_mfma_f32_16x16x32_bf16 v[110:113], v[134:137], v[190:193], v[110:113]
	v_mfma_f32_16x16x32_bf16 v[106:109], v[142:145], v[190:193], v[106:109]
	v_mfma_f32_16x16x32_bf16 v[94:97], v[134:137], v[198:201], v[94:97]
	v_mfma_f32_16x16x32_bf16 v[90:93], v[142:145], v[198:201], v[90:93]
	v_mfma_f32_16x16x32_bf16 v[78:81], v[134:137], v[220:223], v[78:81]
	v_mfma_f32_16x16x32_bf16 v[74:77], v[142:145], v[220:223], v[74:77]
	v_mfma_f32_16x16x32_bf16 v[118:121], v[146:149], v[176:179], 0
	v_mfma_f32_16x16x32_bf16 v[114:117], v[154:157], v[176:179], 0
	v_mfma_f32_16x16x32_bf16 v[102:105], v[146:149], v[184:187], 0
	v_mfma_f32_16x16x32_bf16 v[98:101], v[154:157], v[184:187], 0
	v_mfma_f32_16x16x32_bf16 v[86:89], v[146:149], v[194:197], 0
	v_mfma_f32_16x16x32_bf16 v[82:85], v[154:157], v[194:197], 0
	v_mfma_f32_16x16x32_bf16 v[70:73], v[146:149], v[216:219], 0
	v_mfma_f32_16x16x32_bf16 v[66:69], v[154:157], v[216:219], 0
	v_mfma_f32_16x16x32_bf16 v[118:121], v[150:153], v[180:183], v[118:121]
	v_mfma_f32_16x16x32_bf16 v[114:117], v[172:175], v[180:183], v[114:117]
	v_mfma_f32_16x16x32_bf16 v[102:105], v[150:153], v[190:193], v[102:105]
	v_mfma_f32_16x16x32_bf16 v[98:101], v[172:175], v[190:193], v[98:101]
	v_mfma_f32_16x16x32_bf16 v[86:89], v[150:153], v[198:201], v[86:89]
	v_mfma_f32_16x16x32_bf16 v[82:85], v[172:175], v[198:201], v[82:85]
	v_mfma_f32_16x16x32_bf16 v[70:73], v[150:153], v[220:223], v[70:73]
	v_mfma_f32_16x16x32_bf16 v[66:69], v[172:175], v[220:223], v[66:69]
	s_setprio 0
	s_barrier
	s_add_i32 s18, s90, s26
	s_mov_b32 m0, s18
	ds_read_b128 v[176:179], v189 offset:16384
	ds_read_b128 v[180:183], v189 offset:17408
	ds_read_b128 v[184:187], v189 offset:18432
	ds_read_b128 v[190:193], v189 offset:19456
	ds_read_b128 v[194:197], v189 offset:20480
	ds_read_b128 v[198:201], v189 offset:21504
	ds_read_b128 v[216:219], v189 offset:22528
	ds_read_b128 v[220:223], v189 offset:23552
	global_load_lds_dwordx4 v160, s[22:23]
	s_add_i32 m0, s18, 0x2000
	s_add_u32 s18, s22, 0xb0000
	s_addc_u32 s19, s23, 0
	s_add_i32 s45, s81, s26
	global_load_lds_dwordx4 v164, s[22:23]
	s_mov_b32 m0, s45
	s_nop 0
	global_load_lds_dwordx4 v160, s[18:19]
	s_add_i32 m0, s45, 0x2000
	s_nop 0
	global_load_lds_dwordx4 v164, s[18:19]
	s_mov_b32 m0, s27
	s_nop 0
	global_load_lds_dwordx4 v158, s[24:25]
	s_mov_b32 m0, s28
	s_nop 0
	global_load_lds_dwordx4 v162, s[24:25]
	s_waitcnt vmcnt(8) lgkmcnt(0)
	s_barrier
	s_setprio 1
	v_mfma_f32_16x16x32_bf16 v[62:65], v[130:133], v[176:179], 0
	v_mfma_f32_16x16x32_bf16 v[58:61], v[138:141], v[176:179], 0
	v_mfma_f32_16x16x32_bf16 v[46:49], v[130:133], v[184:187], 0
	v_mfma_f32_16x16x32_bf16 v[42:45], v[138:141], v[184:187], 0
	v_mfma_f32_16x16x32_bf16 v[30:33], v[130:133], v[194:197], 0
	v_mfma_f32_16x16x32_bf16 v[26:29], v[138:141], v[194:197], 0
	v_mfma_f32_16x16x32_bf16 v[14:17], v[130:133], v[216:219], 0
	v_mfma_f32_16x16x32_bf16 v[10:13], v[138:141], v[216:219], 0
	v_mfma_f32_16x16x32_bf16 v[62:65], v[134:137], v[180:183], v[62:65]
	v_mfma_f32_16x16x32_bf16 v[58:61], v[142:145], v[180:183], v[58:61]
	v_mfma_f32_16x16x32_bf16 v[46:49], v[134:137], v[190:193], v[46:49]
	v_mfma_f32_16x16x32_bf16 v[42:45], v[142:145], v[190:193], v[42:45]
	v_mfma_f32_16x16x32_bf16 v[30:33], v[134:137], v[198:201], v[30:33]
	v_mfma_f32_16x16x32_bf16 v[26:29], v[142:145], v[198:201], v[26:29]
	v_mfma_f32_16x16x32_bf16 v[14:17], v[134:137], v[220:223], v[14:17]
	v_mfma_f32_16x16x32_bf16 v[10:13], v[142:145], v[220:223], v[10:13]
	v_mfma_f32_16x16x32_bf16 v[54:57], v[146:149], v[176:179], 0
	v_mfma_f32_16x16x32_bf16 v[50:53], v[154:157], v[176:179], 0
	v_mfma_f32_16x16x32_bf16 v[38:41], v[146:149], v[184:187], 0
	v_mfma_f32_16x16x32_bf16 v[34:37], v[154:157], v[184:187], 0
	v_mfma_f32_16x16x32_bf16 v[22:25], v[146:149], v[194:197], 0
	v_mfma_f32_16x16x32_bf16 v[18:21], v[154:157], v[194:197], 0
	v_mfma_f32_16x16x32_bf16 v[6:9], v[146:149], v[216:219], 0
	v_mfma_f32_16x16x32_bf16 v[2:5], v[154:157], v[216:219], 0
	v_mfma_f32_16x16x32_bf16 v[54:57], v[150:153], v[180:183], v[54:57]
	v_mfma_f32_16x16x32_bf16 v[50:53], v[172:175], v[180:183], v[50:53]
	v_mfma_f32_16x16x32_bf16 v[38:41], v[150:153], v[190:193], v[38:41]
	v_mfma_f32_16x16x32_bf16 v[34:37], v[172:175], v[190:193], v[34:37]
	v_mfma_f32_16x16x32_bf16 v[22:25], v[150:153], v[198:201], v[22:25]
	v_mfma_f32_16x16x32_bf16 v[18:21], v[172:175], v[198:201], v[18:21]
	v_mfma_f32_16x16x32_bf16 v[6:9], v[150:153], v[220:223], v[6:9]
	v_mfma_f32_16x16x32_bf16 v[2:5], v[172:175], v[220:223], v[2:5]
	s_setprio 0
	s_barrier
; #define PG8_STAGE(bufoff, gbase, voff) do { _Pragma("unroll") for (int _i = 0; _i < 2; ++_i) \
;         __builtin_amdgcn_global_load_lds((const unsigned*)((const char*)(gbase) + (voff)[_i]), (PG8_LAS unsigned*)(lds + (bufoff) + ldsw + _i * 8192), 16, 0, 0); } while (0)
; #define PG8_LDA(dst, b, h) do { _Pragma("unroll") for (int m = 0; m < 4; ++m) _Pragma("unroll") for (int k = 0; k < 2; ++k) dst[m][k] = *(const PG8_LAS bf16x8*)(lds + PG8_SA(b, h) + aoff + m * 2048 + k * 1024); } while (0)
; #define PG8_LDB(dst, b, h) do { _Pragma("unroll") for (int n = 0; n < 2; ++n) _Pragma("unroll") for (int k = 0; k < 2; ++k) dst[n][k] = *(const PG8_LAS bf16x8*)(lds + PG8_SB(b, h) + boff + n * 2048 + k * 1024); } while (0)
; #define PG8_MMA(ai, bj, At, Bt) do { __builtin_amdgcn_s_setprio(1); _Pragma("unroll") for (int m = 0; m < 4; ++m) _Pragma("unroll") for (int n = 0; n < 2; ++n) _Pragma("unroll") for (int k = 0; k < 2; ++k) \
;         acc[ai][bj][m][n] = __builtin_amdgcn_mfma_f32_16x16x32_bf16(Bt[n][k], At[m][k], acc[ai][bj][m][n], 0, 0, 0); __builtin_amdgcn_s_setprio(0); } while (0)
; #define PG8_WAIT_V(n) asm volatile("s_waitcnt vmcnt(" #n ")" ::: "memory")
; #define PG8_WAIT_L(n) asm volatile("s_waitcnt lgkmcnt(" #n ")" ::: "memory")
; #define PG8_BAR __builtin_amdgcn_s_barrier()
; #define PG8_SCHED __builtin_amdgcn_sched_barrier(0)
; template <class Epi, class Sched, bool ALIGN_EPI = false, bool SP2 = false>
; __device__ __forceinline__ void gemm_phase(PG8_LAS unsigned char* lds, const Gemm g, const Sched& S, const Epi& E) {
;     ...
;             PG8_LDB(B0, 1, 0); PG8_LDB(B1, 1, 1); PG8_SCHED; PG8_LDA(At, 1, 0); PG8_STAGE(PG8_SA(0, 1), a2 + hstep, voffA);
;             PG8_WAIT_V(8); PG8_WAIT_L(0); PG8_BAR; PG8_MMA(0, 0, At, B0); PG8_MMA(0, 1, At, B1); PG8_BAR; PG8_SCHED;
;             PG8_LDA(At, 1, 1); PG8_STAGE(PG8_SB(1, 0), b3, voffB); PG8_STAGE(PG8_SB(1, 1), b3 + hstep, voffB); PG8_STAGE(PG8_SA(1, 0), a3, voffA);
;             PG8_WAIT_V(8); PG8_WAIT_L(0); PG8_BAR; PG8_MMA(1, 0, At, B0); PG8_MMA(1, 1, At, B1); PG8_BAR; PG8_SCHED;
	v_add_u32_e32 v142, s82, v188
	v_add_u32_e32 v172, s83, v188
	ds_read_b128 v[130:133], v142
	ds_read_b128 v[134:137], v142 offset:1024
	ds_read_b128 v[138:141], v142 offset:2048
	ds_read_b128 v[142:145], v142 offset:3072
	ds_read_b128 v[146:149], v172
	ds_read_b128 v[150:153], v172 offset:1024
	ds_read_b128 v[154:157], v172 offset:2048
	ds_read_b128 v[172:175], v172 offset:3072
	s_add_u32 s18, s24, 0xb0000
	s_addc_u32 s19, s25, 0
	s_mov_b32 m0, s29
	ds_read_b128 v[176:179], v189 offset:32768
	ds_read_b128 v[180:183], v189 offset:33792
	ds_read_b128 v[184:187], v189 offset:34816
	ds_read_b128 v[190:193], v189 offset:35840
	ds_read_b128 v[194:197], v189 offset:36864
	ds_read_b128 v[198:201], v189 offset:37888
	ds_read_b128 v[216:219], v189 offset:38912
	ds_read_b128 v[220:223], v189 offset:39936
	global_load_lds_dwordx4 v158, s[18:19]
	s_mov_b32 m0, s30
	s_nop 0
	global_load_lds_dwordx4 v162, s[18:19]
	s_waitcnt vmcnt(8) lgkmcnt(0)
	s_barrier
	s_setprio 1
	v_mfma_f32_16x16x32_bf16 v[126:129], v[130:133], v[176:179], v[126:129]
	v_mfma_f32_16x16x32_bf16 v[122:125], v[138:141], v[176:179], v[122:125]
	v_mfma_f32_16x16x32_bf16 v[110:113], v[130:133], v[184:187], v[110:113]
	v_mfma_f32_16x16x32_bf16 v[106:109], v[138:141], v[184:187], v[106:109]
	v_mfma_f32_16x16x32_bf16 v[94:97], v[130:133], v[194:197], v[94:97]
	v_mfma_f32_16x16x32_bf16 v[90:93], v[138:141], v[194:197], v[90:93]
	v_mfma_f32_16x16x32_bf16 v[78:81], v[130:133], v[216:219], v[78:81]
	v_mfma_f32_16x16x32_bf16 v[74:77], v[138:141], v[216:219], v[74:77]
	v_mfma_f32_16x16x32_bf16 v[126:129], v[134:137], v[180:183], v[126:129]
	v_mfma_f32_16x16x32_bf16 v[122:125], v[142:145], v[180:183], v[122:125]
	v_mfma_f32_16x16x32_bf16 v[110:113], v[134:137], v[190:193], v[110:113]
	v_mfma_f32_16x16x32_bf16 v[106:109], v[142:145], v[190:193], v[106:109]
	v_mfma_f32_16x16x32_bf16 v[94:97], v[134:137], v[198:201], v[94:97]
	v_mfma_f32_16x16x32_bf16 v[90:93], v[142:145], v[198:201], v[90:93]
	v_mfma_f32_16x16x32_bf16 v[78:81], v[134:137], v[220:223], v[78:81]
	v_mfma_f32_16x16x32_bf16 v[74:77], v[142:145], v[220:223], v[74:77]
	v_mfma_f32_16x16x32_bf16 v[118:121], v[146:149], v[176:179], v[118:121]
	v_mfma_f32_16x16x32_bf16 v[114:117], v[154:157], v[176:179], v[114:117]
	v_mfma_f32_16x16x32_bf16 v[102:105], v[146:149], v[184:187], v[102:105]
	v_mfma_f32_16x16x32_bf16 v[98:101], v[154:157], v[184:187], v[98:101]
	v_mfma_f32_16x16x32_bf16 v[86:89], v[146:149], v[194:197], v[86:89]
	v_mfma_f32_16x16x32_bf16 v[82:85], v[154:157], v[194:197], v[82:85]
	v_mfma_f32_16x16x32_bf16 v[70:73], v[146:149], v[216:219], v[70:73]
	v_mfma_f32_16x16x32_bf16 v[66:69], v[154:157], v[216:219], v[66:69]
	v_mfma_f32_16x16x32_bf16 v[118:121], v[150:153], v[180:183], v[118:121]
	v_mfma_f32_16x16x32_bf16 v[114:117], v[172:175], v[180:183], v[114:117]
	v_mfma_f32_16x16x32_bf16 v[102:105], v[150:153], v[190:193], v[102:105]
	v_mfma_f32_16x16x32_bf16 v[98:101], v[172:175], v[190:193], v[98:101]
	v_mfma_f32_16x16x32_bf16 v[86:89], v[150:153], v[198:201], v[86:89]
	v_mfma_f32_16x16x32_bf16 v[82:85], v[172:175], v[198:201], v[82:85]
	v_mfma_f32_16x16x32_bf16 v[70:73], v[150:153], v[220:223], v[70:73]
	v_mfma_f32_16x16x32_bf16 v[66:69], v[172:175], v[220:223], v[66:69]
	s_setprio 0
	s_barrier
	s_add_i32 s18, s82, s26
	s_mov_b32 m0, s18
	ds_read_b128 v[176:179], v189 offset:49152
	ds_read_b128 v[180:183], v189 offset:50176
	ds_read_b128 v[184:187], v189 offset:51200
	ds_read_b128 v[190:193], v189 offset:52224
	ds_read_b128 v[194:197], v189 offset:53248
	ds_read_b128 v[198:201], v189 offset:54272
	ds_read_b128 v[216:219], v189 offset:55296
	ds_read_b128 v[220:223], v189 offset:56320
	global_load_lds_dwordx4 v160, s[98:99]
	s_add_i32 m0, s18, 0x2000
	s_add_u32 s18, s22, 0xb0080
	s_addc_u32 s19, s23, 0
	s_add_i32 s22, s83, s26
	global_load_lds_dwordx4 v164, s[98:99]
	s_mov_b32 m0, s22
	s_nop 0
	global_load_lds_dwordx4 v160, s[18:19]
	s_add_i32 m0, s22, 0x2000
	s_nop 0
	global_load_lds_dwordx4 v164, s[18:19]
	s_mov_b32 m0, s31
	s_nop 0
	global_load_lds_dwordx4 v158, s[100:101]
	s_mov_b32 m0, s34
	s_nop 0
	global_load_lds_dwordx4 v162, s[100:101]
	s_waitcnt vmcnt(8) lgkmcnt(0)
	s_barrier
	s_setprio 1
	v_mfma_f32_16x16x32_bf16 v[62:65], v[130:133], v[176:179], v[62:65]
	v_mfma_f32_16x16x32_bf16 v[58:61], v[138:141], v[176:179], v[58:61]
	v_mfma_f32_16x16x32_bf16 v[46:49], v[130:133], v[184:187], v[46:49]
	v_mfma_f32_16x16x32_bf16 v[42:45], v[138:141], v[184:187], v[42:45]
	v_mfma_f32_16x16x32_bf16 v[30:33], v[130:133], v[194:197], v[30:33]
	v_mfma_f32_16x16x32_bf16 v[26:29], v[138:141], v[194:197], v[26:29]
	v_mfma_f32_16x16x32_bf16 v[14:17], v[130:133], v[216:219], v[14:17]
	v_mfma_f32_16x16x32_bf16 v[10:13], v[138:141], v[216:219], v[10:13]
	v_mfma_f32_16x16x32_bf16 v[62:65], v[134:137], v[180:183], v[62:65]
	v_mfma_f32_16x16x32_bf16 v[58:61], v[142:145], v[180:183], v[58:61]
	v_mfma_f32_16x16x32_bf16 v[46:49], v[134:137], v[190:193], v[46:49]
	v_mfma_f32_16x16x32_bf16 v[42:45], v[142:145], v[190:193], v[42:45]
	v_mfma_f32_16x16x32_bf16 v[30:33], v[134:137], v[198:201], v[30:33]
	v_mfma_f32_16x16x32_bf16 v[26:29], v[142:145], v[198:201], v[26:29]
	v_mfma_f32_16x16x32_bf16 v[14:17], v[134:137], v[220:223], v[14:17]
	v_mfma_f32_16x16x32_bf16 v[10:13], v[142:145], v[220:223], v[10:13]
	v_mfma_f32_16x16x32_bf16 v[54:57], v[146:149], v[176:179], v[54:57]
	v_mfma_f32_16x16x32_bf16 v[50:53], v[154:157], v[176:179], v[50:53]
	v_mfma_f32_16x16x32_bf16 v[38:41], v[146:149], v[184:187], v[38:41]
	v_mfma_f32_16x16x32_bf16 v[34:37], v[154:157], v[184:187], v[34:37]
	v_mfma_f32_16x16x32_bf16 v[22:25], v[146:149], v[194:197], v[22:25]
	v_mfma_f32_16x16x32_bf16 v[18:21], v[154:157], v[194:197], v[18:21]
	v_mfma_f32_16x16x32_bf16 v[6:9], v[146:149], v[216:219], v[6:9]
	v_mfma_f32_16x16x32_bf16 v[2:5], v[154:157], v[216:219], v[2:5]
	v_mfma_f32_16x16x32_bf16 v[54:57], v[150:153], v[180:183], v[54:57]
	v_mfma_f32_16x16x32_bf16 v[50:53], v[172:175], v[180:183], v[50:53]
	v_mfma_f32_16x16x32_bf16 v[38:41], v[150:153], v[190:193], v[38:41]
	v_mfma_f32_16x16x32_bf16 v[34:37], v[172:175], v[190:193], v[34:37]
	v_mfma_f32_16x16x32_bf16 v[22:25], v[150:153], v[198:201], v[22:25]
	v_mfma_f32_16x16x32_bf16 v[18:21], v[172:175], v[198:201], v[18:21]
	v_mfma_f32_16x16x32_bf16 v[6:9], v[150:153], v[220:223], v[6:9]
	v_mfma_f32_16x16x32_bf16 v[2:5], v[172:175], v[220:223], v[2:5]
	s_setprio 0
	s_barrier
	s_add_i32 s44, s44, 2
	s_add_u32 s39, s39, 0x100
	s_addc_u32 s42, s42, 0
	s_mov_b64 s[18:19], s[20:21]
; #define PG8_STAGE(bufoff, gbase, voff) do { _Pragma("unroll") for (int _i = 0; _i < 2; ++_i) \
;         __builtin_amdgcn_global_load_lds((const unsigned*)((const char*)(gbase) + (voff)[_i]), (PG8_LAS unsigned*)(lds + (bufoff) + ldsw + _i * 8192), 16, 0, 0); } while (0)
; #define PG8_LDA(dst, b, h) do { _Pragma("unroll") for (int m = 0; m < 4; ++m) _Pragma("unroll") for (int k = 0; k < 2; ++k) dst[m][k] = *(const PG8_LAS bf16x8*)(lds + PG8_SA(b, h) + aoff + m * 2048 + k * 1024); } while (0)
; #define PG8_LDB(dst, b, h) do { _Pragma("unroll") for (int n = 0; n < 2; ++n) _Pragma("unroll") for (int k = 0; k < 2; ++k) dst[n][k] = *(const PG8_LAS bf16x8*)(lds + PG8_SB(b, h) + boff + n * 2048 + k * 1024); } while (0)
; #define PG8_MMA(ai, bj, At, Bt) do { __builtin_amdgcn_s_setprio(1); _Pragma("unroll") for (int m = 0; m < 4; ++m) _Pragma("unroll") for (int n = 0; n < 2; ++n) _Pragma("unroll") for (int k = 0; k < 2; ++k) \
;         acc[ai][bj][m][n] = __builtin_amdgcn_mfma_f32_16x16x32_bf16(Bt[n][k], At[m][k], acc[ai][bj][m][n], 0, 0, 0); __builtin_amdgcn_s_setprio(0); } while (0)
; #define PG8_WAIT_V(n) asm volatile("s_waitcnt vmcnt(" #n ")" ::: "memory")
; #define PG8_WAIT_L(n) asm volatile("s_waitcnt lgkmcnt(" #n ")" ::: "memory")
; #define PG8_BAR __builtin_amdgcn_s_barrier()
; #define PG8_SCHED __builtin_amdgcn_sched_barrier(0)
; template <class Epi, class Sched, bool ALIGN_EPI = false, bool SP2 = false>
; __device__ __forceinline__ void gemm_phase(PG8_LAS unsigned char* lds, const Gemm g, const Sched& S, const Epi& E) {
;     ...
;             PG8_LDB(B0, 0, 0); PG8_LDB(B1, 0, 1); PG8_SCHED; PG8_LDA(At, 0, 0); PG8_STAGE(PG8_SA(1, 1), a1 + hstep, voffA);
;             PG8_WAIT_V(8); PG8_WAIT_L(0); PG8_BAR; PG8_MMA(0, 0, At, B0); PG8_MMA(0, 1, At, B1); PG8_BAR; PG8_SCHED;
;             PG8_LDA(At, 0, 1); PG8_STAGE(PG8_SB(0, 0), b2, voffB); PG8_STAGE(PG8_SB(0, 1), b2 + hstep, voffB); PG8_STAGE(PG8_SA(0, 0), a2, voffA);
;             PG8_WAIT_V(8); PG8_WAIT_L(0); PG8_BAR; PG8_MMA(1, 0, At, B0); PG8_MMA(1, 1, At, B1); PG8_BAR; PG8_SCHED;
.LBB0_212:
	v_add_u32_e32 v142, s90, v188
	v_add_u32_e32 v172, s81, v188
	ds_read_b128 v[130:133], v142
	ds_read_b128 v[134:137], v142 offset:1024
	ds_read_b128 v[138:141], v142 offset:2048
	ds_read_b128 v[142:145], v142 offset:3072
	ds_read_b128 v[146:149], v172
	ds_read_b128 v[150:153], v172 offset:1024
	ds_read_b128 v[154:157], v172 offset:2048
	ds_read_b128 v[172:175], v172 offset:3072
	s_add_u32 s20, s18, 0x100
	s_addc_u32 s21, s19, 0
	s_cmp_eq_u32 s44, 40
	s_cselect_b32 s25, s7, s21
	s_cselect_b32 s24, s6, s20
	s_cselect_b32 s23, s15, s42
	s_cselect_b32 s22, s14, s39
	s_add_u32 s98, s22, s46
	s_addc_u32 s99, s23, s47
	s_add_u32 s100, s24, s46
	s_addc_u32 s101, s25, s47
	s_add_i32 m0, s27, 0xc000
	ds_read_b128 v[176:179], v189
	ds_read_b128 v[180:183], v189 offset:1024
	ds_read_b128 v[184:187], v189 offset:2048
	ds_read_b128 v[190:193], v189 offset:3072
	ds_read_b128 v[194:197], v189 offset:4096
	ds_read_b128 v[198:201], v189 offset:5120
	ds_read_b128 v[216:219], v189 offset:6144
	ds_read_b128 v[220:223], v189 offset:7168
	global_load_lds_dwordx4 v168, s[18:19]
	s_add_i32 m0, s27, 0xe000
	s_nop 0
	global_load_lds_dwordx4 v170, s[18:19]
	s_waitcnt vmcnt(8) lgkmcnt(0)
	s_barrier
	s_setprio 1
	v_mfma_f32_16x16x32_bf16 v[126:129], v[130:133], v[176:179], v[126:129]
	v_mfma_f32_16x16x32_bf16 v[122:125], v[138:141], v[176:179], v[122:125]
	v_mfma_f32_16x16x32_bf16 v[110:113], v[130:133], v[184:187], v[110:113]
	v_mfma_f32_16x16x32_bf16 v[106:109], v[138:141], v[184:187], v[106:109]
	v_mfma_f32_16x16x32_bf16 v[94:97], v[130:133], v[194:197], v[94:97]
	v_mfma_f32_16x16x32_bf16 v[90:93], v[138:141], v[194:197], v[90:93]
	v_mfma_f32_16x16x32_bf16 v[78:81], v[130:133], v[216:219], v[78:81]
	v_mfma_f32_16x16x32_bf16 v[74:77], v[138:141], v[216:219], v[74:77]
	v_mfma_f32_16x16x32_bf16 v[126:129], v[134:137], v[180:183], v[126:129]
	v_mfma_f32_16x16x32_bf16 v[122:125], v[142:145], v[180:183], v[122:125]
	v_mfma_f32_16x16x32_bf16 v[110:113], v[134:137], v[190:193], v[110:113]
	v_mfma_f32_16x16x32_bf16 v[106:109], v[142:145], v[190:193], v[106:109]
	v_mfma_f32_16x16x32_bf16 v[94:97], v[134:137], v[198:201], v[94:97]
	v_mfma_f32_16x16x32_bf16 v[90:93], v[142:145], v[198:201], v[90:93]
	v_mfma_f32_16x16x32_bf16 v[78:81], v[134:137], v[220:223], v[78:81]
	v_mfma_f32_16x16x32_bf16 v[74:77], v[142:145], v[220:223], v[74:77]
	v_mfma_f32_16x16x32_bf16 v[118:121], v[146:149], v[176:179], v[118:121]
	v_mfma_f32_16x16x32_bf16 v[114:117], v[154:157], v[176:179], v[114:117]
	v_mfma_f32_16x16x32_bf16 v[102:105], v[146:149], v[184:187], v[102:105]
	v_mfma_f32_16x16x32_bf16 v[98:101], v[154:157], v[184:187], v[98:101]
	v_mfma_f32_16x16x32_bf16 v[86:89], v[146:149], v[194:197], v[86:89]
	v_mfma_f32_16x16x32_bf16 v[82:85], v[154:157], v[194:197], v[82:85]
	v_mfma_f32_16x16x32_bf16 v[70:73], v[146:149], v[216:219], v[70:73]
	v_mfma_f32_16x16x32_bf16 v[66:69], v[154:157], v[216:219], v[66:69]
	v_mfma_f32_16x16x32_bf16 v[118:121], v[150:153], v[180:183], v[118:121]
	v_mfma_f32_16x16x32_bf16 v[114:117], v[172:175], v[180:183], v[114:117]
	v_mfma_f32_16x16x32_bf16 v[102:105], v[150:153], v[190:193], v[102:105]
	v_mfma_f32_16x16x32_bf16 v[98:101], v[172:175], v[190:193], v[98:101]
	v_mfma_f32_16x16x32_bf16 v[86:89], v[150:153], v[198:201], v[86:89]
	v_mfma_f32_16x16x32_bf16 v[82:85], v[172:175], v[198:201], v[82:85]
	v_mfma_f32_16x16x32_bf16 v[70:73], v[150:153], v[220:223], v[70:73]
	v_mfma_f32_16x16x32_bf16 v[66:69], v[172:175], v[220:223], v[66:69]
	s_setprio 0
	s_barrier
	s_add_i32 s18, s90, s26
	s_mov_b32 m0, s18
	ds_read_b128 v[176:179], v189 offset:16384
	ds_read_b128 v[180:183], v189 offset:17408
	ds_read_b128 v[184:187], v189 offset:18432
	ds_read_b128 v[190:193], v189 offset:19456
	ds_read_b128 v[194:197], v189 offset:20480
	ds_read_b128 v[198:201], v189 offset:21504
	ds_read_b128 v[216:219], v189 offset:22528
	ds_read_b128 v[220:223], v189 offset:23552
	global_load_lds_dwordx4 v160, s[22:23]
	s_add_i32 m0, s18, 0x2000
	s_add_u32 s18, s22, 0xb0000
	s_addc_u32 s19, s23, 0
	s_add_i32 s45, s81, s26
	global_load_lds_dwordx4 v164, s[22:23]
	s_mov_b32 m0, s45
	s_nop 0
	global_load_lds_dwordx4 v160, s[18:19]
	s_add_i32 m0, s45, 0x2000
	s_nop 0
	global_load_lds_dwordx4 v164, s[18:19]
	s_mov_b32 m0, s27
	s_nop 0
	global_load_lds_dwordx4 v158, s[24:25]
	s_mov_b32 m0, s28
	s_nop 0
	global_load_lds_dwordx4 v162, s[24:25]
	s_waitcnt vmcnt(8) lgkmcnt(0)
	s_barrier
	s_setprio 1
	v_mfma_f32_16x16x32_bf16 v[62:65], v[130:133], v[176:179], v[62:65]
	v_mfma_f32_16x16x32_bf16 v[58:61], v[138:141], v[176:179], v[58:61]
	v_mfma_f32_16x16x32_bf16 v[46:49], v[130:133], v[184:187], v[46:49]
	v_mfma_f32_16x16x32_bf16 v[42:45], v[138:141], v[184:187], v[42:45]
	v_mfma_f32_16x16x32_bf16 v[30:33], v[130:133], v[194:197], v[30:33]
	v_mfma_f32_16x16x32_bf16 v[26:29], v[138:141], v[194:197], v[26:29]
	v_mfma_f32_16x16x32_bf16 v[14:17], v[130:133], v[216:219], v[14:17]
	v_mfma_f32_16x16x32_bf16 v[10:13], v[138:141], v[216:219], v[10:13]
	v_mfma_f32_16x16x32_bf16 v[62:65], v[134:137], v[180:183], v[62:65]
	v_mfma_f32_16x16x32_bf16 v[58:61], v[142:145], v[180:183], v[58:61]
	v_mfma_f32_16x16x32_bf16 v[46:49], v[134:137], v[190:193], v[46:49]
	v_mfma_f32_16x16x32_bf16 v[42:45], v[142:145], v[190:193], v[42:45]
	v_mfma_f32_16x16x32_bf16 v[30:33], v[134:137], v[198:201], v[30:33]
	v_mfma_f32_16x16x32_bf16 v[26:29], v[142:145], v[198:201], v[26:29]
	v_mfma_f32_16x16x32_bf16 v[14:17], v[134:137], v[220:223], v[14:17]
	v_mfma_f32_16x16x32_bf16 v[10:13], v[142:145], v[220:223], v[10:13]
	v_mfma_f32_16x16x32_bf16 v[54:57], v[146:149], v[176:179], v[54:57]
	v_mfma_f32_16x16x32_bf16 v[50:53], v[154:157], v[176:179], v[50:53]
	v_mfma_f32_16x16x32_bf16 v[38:41], v[146:149], v[184:187], v[38:41]
	v_mfma_f32_16x16x32_bf16 v[34:37], v[154:157], v[184:187], v[34:37]
	v_mfma_f32_16x16x32_bf16 v[22:25], v[146:149], v[194:197], v[22:25]
	v_mfma_f32_16x16x32_bf16 v[18:21], v[154:157], v[194:197], v[18:21]
	v_mfma_f32_16x16x32_bf16 v[6:9], v[146:149], v[216:219], v[6:9]
	v_mfma_f32_16x16x32_bf16 v[2:5], v[154:157], v[216:219], v[2:5]
	v_mfma_f32_16x16x32_bf16 v[54:57], v[150:153], v[180:183], v[54:57]
	v_mfma_f32_16x16x32_bf16 v[50:53], v[172:175], v[180:183], v[50:53]
	v_mfma_f32_16x16x32_bf16 v[38:41], v[150:153], v[190:193], v[38:41]
	v_mfma_f32_16x16x32_bf16 v[34:37], v[172:175], v[190:193], v[34:37]
	v_mfma_f32_16x16x32_bf16 v[22:25], v[150:153], v[198:201], v[22:25]
	v_mfma_f32_16x16x32_bf16 v[18:21], v[172:175], v[198:201], v[18:21]
	v_mfma_f32_16x16x32_bf16 v[6:9], v[150:153], v[220:223], v[6:9]
	v_mfma_f32_16x16x32_bf16 v[2:5], v[172:175], v[220:223], v[2:5]
	s_setprio 0
	s_barrier
; #define PG8_STAGE(bufoff, gbase, voff) do { _Pragma("unroll") for (int _i = 0; _i < 2; ++_i) \
;         __builtin_amdgcn_global_load_lds((const unsigned*)((const char*)(gbase) + (voff)[_i]), (PG8_LAS unsigned*)(lds + (bufoff) + ldsw + _i * 8192), 16, 0, 0); } while (0)
; #define PG8_LDA(dst, b, h) do { _Pragma("unroll") for (int m = 0; m < 4; ++m) _Pragma("unroll") for (int k = 0; k < 2; ++k) dst[m][k] = *(const PG8_LAS bf16x8*)(lds + PG8_SA(b, h) + aoff + m * 2048 + k * 1024); } while (0)
; #define PG8_LDB(dst, b, h) do { _Pragma("unroll") for (int n = 0; n < 2; ++n) _Pragma("unroll") for (int k = 0; k < 2; ++k) dst[n][k] = *(const PG8_LAS bf16x8*)(lds + PG8_SB(b, h) + boff + n * 2048 + k * 1024); } while (0)
; #define PG8_MMA(ai, bj, At, Bt) do { __builtin_amdgcn_s_setprio(1); _Pragma("unroll") for (int m = 0; m < 4; ++m) _Pragma("unroll") for (int n = 0; n < 2; ++n) _Pragma("unroll") for (int k = 0; k < 2; ++k) \
;         acc[ai][bj][m][n] = __builtin_amdgcn_mfma_f32_16x16x32_bf16(Bt[n][k], At[m][k], acc[ai][bj][m][n], 0, 0, 0); __builtin_amdgcn_s_setprio(0); } while (0)
; #define PG8_WAIT_V(n) asm volatile("s_waitcnt vmcnt(" #n ")" ::: "memory")
; #define PG8_WAIT_L(n) asm volatile("s_waitcnt lgkmcnt(" #n ")" ::: "memory")
; #define PG8_BAR __builtin_amdgcn_s_barrier()
; #define PG8_SCHED __builtin_amdgcn_sched_barrier(0)
; template <class Epi, class Sched, bool ALIGN_EPI = false, bool SP2 = false>
; __device__ __forceinline__ void gemm_phase(PG8_LAS unsigned char* lds, const Gemm g, const Sched& S, const Epi& E) {
;     ...
;             PG8_LDB(B0, 1, 0); PG8_LDB(B1, 1, 1); PG8_SCHED; PG8_LDA(At, 1, 0); PG8_STAGE(PG8_SA(0, 1), a2 + hstep, voffA);
;             PG8_WAIT_V(8); PG8_WAIT_L(0); PG8_BAR; PG8_MMA(0, 0, At, B0); PG8_MMA(0, 1, At, B1); PG8_BAR; PG8_SCHED;
;             PG8_LDA(At, 1, 1); PG8_STAGE(PG8_SB(1, 0), b3, voffB); PG8_STAGE(PG8_SB(1, 1), b3 + hstep, voffB); PG8_STAGE(PG8_SA(1, 0), a3, voffA);
;             PG8_WAIT_V(8); PG8_WAIT_L(0); PG8_BAR; PG8_MMA(1, 0, At, B0); PG8_MMA(1, 1, At, B1); PG8_BAR; PG8_SCHED;
	v_add_u32_e32 v142, s82, v188
	v_add_u32_e32 v172, s83, v188
	ds_read_b128 v[130:133], v142
	ds_read_b128 v[134:137], v142 offset:1024
	ds_read_b128 v[138:141], v142 offset:2048
	ds_read_b128 v[142:145], v142 offset:3072
	ds_read_b128 v[146:149], v172
	ds_read_b128 v[150:153], v172 offset:1024
	ds_read_b128 v[154:157], v172 offset:2048
	ds_read_b128 v[172:175], v172 offset:3072
	s_add_u32 s18, s24, 0xb0000
	s_addc_u32 s19, s25, 0
	s_mov_b32 m0, s29
	ds_read_b128 v[176:179], v189 offset:32768
	ds_read_b128 v[180:183], v189 offset:33792
	ds_read_b128 v[184:187], v189 offset:34816
	ds_read_b128 v[190:193], v189 offset:35840
	ds_read_b128 v[194:197], v189 offset:36864
	ds_read_b128 v[198:201], v189 offset:37888
	ds_read_b128 v[216:219], v189 offset:38912
	ds_read_b128 v[220:223], v189 offset:39936
	global_load_lds_dwordx4 v158, s[18:19]
	s_mov_b32 m0, s30
	s_nop 0
	global_load_lds_dwordx4 v162, s[18:19]
	s_waitcnt vmcnt(8) lgkmcnt(0)
	s_barrier
	s_setprio 1
	v_mfma_f32_16x16x32_bf16 v[126:129], v[130:133], v[176:179], v[126:129]
	v_mfma_f32_16x16x32_bf16 v[122:125], v[138:141], v[176:179], v[122:125]
	v_mfma_f32_16x16x32_bf16 v[110:113], v[130:133], v[184:187], v[110:113]
	v_mfma_f32_16x16x32_bf16 v[106:109], v[138:141], v[184:187], v[106:109]
	v_mfma_f32_16x16x32_bf16 v[94:97], v[130:133], v[194:197], v[94:97]
	v_mfma_f32_16x16x32_bf16 v[90:93], v[138:141], v[194:197], v[90:93]
	v_mfma_f32_16x16x32_bf16 v[78:81], v[130:133], v[216:219], v[78:81]
	v_mfma_f32_16x16x32_bf16 v[74:77], v[138:141], v[216:219], v[74:77]
	v_mfma_f32_16x16x32_bf16 v[126:129], v[134:137], v[180:183], v[126:129]
	v_mfma_f32_16x16x32_bf16 v[122:125], v[142:145], v[180:183], v[122:125]
	v_mfma_f32_16x16x32_bf16 v[110:113], v[134:137], v[190:193], v[110:113]
	v_mfma_f32_16x16x32_bf16 v[106:109], v[142:145], v[190:193], v[106:109]
	v_mfma_f32_16x16x32_bf16 v[94:97], v[134:137], v[198:201], v[94:97]
	v_mfma_f32_16x16x32_bf16 v[90:93], v[142:145], v[198:201], v[90:93]
	v_mfma_f32_16x16x32_bf16 v[78:81], v[134:137], v[220:223], v[78:81]
	v_mfma_f32_16x16x32_bf16 v[74:77], v[142:145], v[220:223], v[74:77]
	v_mfma_f32_16x16x32_bf16 v[118:121], v[146:149], v[176:179], v[118:121]
	v_mfma_f32_16x16x32_bf16 v[114:117], v[154:157], v[176:179], v[114:117]
	v_mfma_f32_16x16x32_bf16 v[102:105], v[146:149], v[184:187], v[102:105]
	v_mfma_f32_16x16x32_bf16 v[98:101], v[154:157], v[184:187], v[98:101]
	v_mfma_f32_16x16x32_bf16 v[86:89], v[146:149], v[194:197], v[86:89]
	v_mfma_f32_16x16x32_bf16 v[82:85], v[154:157], v[194:197], v[82:85]
	v_mfma_f32_16x16x32_bf16 v[70:73], v[146:149], v[216:219], v[70:73]
	v_mfma_f32_16x16x32_bf16 v[66:69], v[154:157], v[216:219], v[66:69]
	v_mfma_f32_16x16x32_bf16 v[118:121], v[150:153], v[180:183], v[118:121]
	v_mfma_f32_16x16x32_bf16 v[114:117], v[172:175], v[180:183], v[114:117]
	v_mfma_f32_16x16x32_bf16 v[102:105], v[150:153], v[190:193], v[102:105]
	v_mfma_f32_16x16x32_bf16 v[98:101], v[172:175], v[190:193], v[98:101]
	v_mfma_f32_16x16x32_bf16 v[86:89], v[150:153], v[198:201], v[86:89]
	v_mfma_f32_16x16x32_bf16 v[82:85], v[172:175], v[198:201], v[82:85]
	v_mfma_f32_16x16x32_bf16 v[70:73], v[150:153], v[220:223], v[70:73]
	v_mfma_f32_16x16x32_bf16 v[66:69], v[172:175], v[220:223], v[66:69]
	s_setprio 0
	s_barrier
	s_add_i32 s18, s82, s26
	s_mov_b32 m0, s18
	ds_read_b128 v[176:179], v189 offset:49152
	ds_read_b128 v[180:183], v189 offset:50176
	ds_read_b128 v[184:187], v189 offset:51200
	ds_read_b128 v[190:193], v189 offset:52224
	ds_read_b128 v[194:197], v189 offset:53248
	ds_read_b128 v[198:201], v189 offset:54272
	ds_read_b128 v[216:219], v189 offset:55296
	ds_read_b128 v[220:223], v189 offset:56320
	global_load_lds_dwordx4 v160, s[98:99]
	s_add_i32 m0, s18, 0x2000
	s_add_u32 s18, s22, 0xb0080
	s_addc_u32 s19, s23, 0
	s_add_i32 s22, s83, s26
	global_load_lds_dwordx4 v164, s[98:99]
	s_mov_b32 m0, s22
	s_nop 0
	global_load_lds_dwordx4 v160, s[18:19]
	s_add_i32 m0, s22, 0x2000
	s_nop 0
	global_load_lds_dwordx4 v164, s[18:19]
	s_mov_b32 m0, s31
	s_nop 0
	global_load_lds_dwordx4 v158, s[100:101]
	s_mov_b32 m0, s34
	s_nop 0
	global_load_lds_dwordx4 v162, s[100:101]
	s_waitcnt vmcnt(8) lgkmcnt(0)
	s_barrier
	s_setprio 1
	v_mfma_f32_16x16x32_bf16 v[62:65], v[130:133], v[176:179], v[62:65]
	v_mfma_f32_16x16x32_bf16 v[58:61], v[138:141], v[176:179], v[58:61]
	v_mfma_f32_16x16x32_bf16 v[46:49], v[130:133], v[184:187], v[46:49]
	v_mfma_f32_16x16x32_bf16 v[42:45], v[138:141], v[184:187], v[42:45]
	v_mfma_f32_16x16x32_bf16 v[30:33], v[130:133], v[194:197], v[30:33]
	v_mfma_f32_16x16x32_bf16 v[26:29], v[138:141], v[194:197], v[26:29]
	v_mfma_f32_16x16x32_bf16 v[14:17], v[130:133], v[216:219], v[14:17]
	v_mfma_f32_16x16x32_bf16 v[10:13], v[138:141], v[216:219], v[10:13]
	v_mfma_f32_16x16x32_bf16 v[62:65], v[134:137], v[180:183], v[62:65]
	v_mfma_f32_16x16x32_bf16 v[58:61], v[142:145], v[180:183], v[58:61]
	v_mfma_f32_16x16x32_bf16 v[46:49], v[134:137], v[190:193], v[46:49]
	v_mfma_f32_16x16x32_bf16 v[42:45], v[142:145], v[190:193], v[42:45]
	v_mfma_f32_16x16x32_bf16 v[30:33], v[134:137], v[198:201], v[30:33]
	v_mfma_f32_16x16x32_bf16 v[26:29], v[142:145], v[198:201], v[26:29]
	v_mfma_f32_16x16x32_bf16 v[14:17], v[134:137], v[220:223], v[14:17]
	v_mfma_f32_16x16x32_bf16 v[10:13], v[142:145], v[220:223], v[10:13]
	v_mfma_f32_16x16x32_bf16 v[54:57], v[146:149], v[176:179], v[54:57]
	v_mfma_f32_16x16x32_bf16 v[50:53], v[154:157], v[176:179], v[50:53]
	v_mfma_f32_16x16x32_bf16 v[38:41], v[146:149], v[184:187], v[38:41]
	v_mfma_f32_16x16x32_bf16 v[34:37], v[154:157], v[184:187], v[34:37]
	v_mfma_f32_16x16x32_bf16 v[22:25], v[146:149], v[194:197], v[22:25]
	v_mfma_f32_16x16x32_bf16 v[18:21], v[154:157], v[194:197], v[18:21]
	v_mfma_f32_16x16x32_bf16 v[6:9], v[146:149], v[216:219], v[6:9]
	v_mfma_f32_16x16x32_bf16 v[2:5], v[154:157], v[216:219], v[2:5]
	v_mfma_f32_16x16x32_bf16 v[54:57], v[150:153], v[180:183], v[54:57]
	v_mfma_f32_16x16x32_bf16 v[50:53], v[172:175], v[180:183], v[50:53]
	v_mfma_f32_16x16x32_bf16 v[38:41], v[150:153], v[190:193], v[38:41]
	v_mfma_f32_16x16x32_bf16 v[34:37], v[172:175], v[190:193], v[34:37]
	v_mfma_f32_16x16x32_bf16 v[22:25], v[150:153], v[198:201], v[22:25]
	v_mfma_f32_16x16x32_bf16 v[18:21], v[172:175], v[198:201], v[18:21]
	v_mfma_f32_16x16x32_bf16 v[6:9], v[150:153], v[220:223], v[6:9]
	v_mfma_f32_16x16x32_bf16 v[2:5], v[172:175], v[220:223], v[2:5]
	s_setprio 0
	s_barrier
	s_add_i32 s44, s44, 2
	s_add_u32 s39, s39, 0x100
	s_addc_u32 s42, s42, 0
	s_cmp_gt_u32 s44, 41
	s_mov_b64 s[18:19], s[20:21]
	s_cbranch_scc0 .LBB0_212
	s_and_b64 vcc, exec, s[10:11]
	s_cbranch_vccz .LBB0_215
	s_barrier

; #define PG8_STAGE(bufoff, gbase, voff) do { _Pragma("unroll") for (int _i = 0; _i < 2; ++_i) \
;         __builtin_amdgcn_global_load_lds((const unsigned*)((const char*)(gbase) + (voff)[_i]), (PG8_LAS unsigned*)(lds + (bufoff) + ldsw + _i * 8192), 16, 0, 0); } while (0)
; #define PG8_LDA(dst, b, h) do { _Pragma("unroll") for (int m = 0; m < 4; ++m) _Pragma("unroll") for (int k = 0; k < 2; ++k) dst[m][k] = *(const PG8_LAS bf16x8*)(lds + PG8_SA(b, h) + aoff + m * 2048 + k * 1024); } while (0)
; #define PG8_LDB(dst, b, h) do { _Pragma("unroll") for (int n = 0; n < 2; ++n) _Pragma("unroll") for (int k = 0; k < 2; ++k) dst[n][k] = *(const PG8_LAS bf16x8*)(lds + PG8_SB(b, h) + boff + n * 2048 + k * 1024); } while (0)
; #define PG8_MMA(ai, bj, At, Bt) do { __builtin_amdgcn_s_setprio(1); _Pragma("unroll") for (int m = 0; m < 4; ++m) _Pragma("unroll") for (int n = 0; n < 2; ++n) _Pragma("unroll") for (int k = 0; k < 2; ++k) \
;         acc[ai][bj][m][n] = __builtin_amdgcn_mfma_f32_16x16x32_bf16(Bt[n][k], At[m][k], acc[ai][bj][m][n], 0, 0, 0); __builtin_amdgcn_s_setprio(0); } while (0)
; #define PG8_WAIT_V(n) asm volatile("s_waitcnt vmcnt(" #n ")" ::: "memory")
; #define PG8_WAIT_L(n) asm volatile("s_waitcnt lgkmcnt(" #n ")" ::: "memory")
; #define PG8_BAR __builtin_amdgcn_s_barrier()
; #define PG8_SCHED __builtin_amdgcn_sched_barrier(0)
; template <class Epi, class Sched, bool ALIGN_EPI = false, bool SP2 = false>
; __device__ __forceinline__ void gemm_phase(PG8_LAS unsigned char* lds, const Gemm g, const Sched& S, const Epi& E) {
;     ...
;             const char* a2 = last ? nA : cA + (size_t)(t + 2) * kstep; const char* b2 = last ? nB : cB + (size_t)(t + 2) * kstep;
;             const char* a3 = a2 + kstep; const char* b3 = b2 + kstep;
;             if (last && has_next) S.a_ready_inloop(nxt, ui + 1);
;             if constexpr (SP2) {
;             PG8_LDB(B0, 0, 0); PG8_LDB(B1, 0, 1); PG8_SCHED; PG8_LDA(At, 0, 0); PG8_STAGE(PG8_SA(1, 1), a1 + hstep, voffA);
;             PG8_WAIT_V(8); PG8_WAIT_L(0); PG8_BAR; PG8_MMA(0, 0, At, B0); PG8_MMA(0, 1, At, B1); PG8_BAR; PG8_SCHED;
;             PG8_LDA(At, 0, 1); PG8_STAGE(PG8_SB(0, 0), b2, voffB); PG8_STAGE(PG8_SB(0, 1), b2 + hstep, voffB); PG8_STAGE(PG8_SA(0, 0), a2, voffA);
.LBB0_318:
	s_ashr_i32 s17, s16, 31
	s_lshl_b64 s[20:21], s[16:17], 19
	s_add_u32 s20, s34, s20
	s_addc_u32 s21, s35, s21
	s_and_b64 s[22:23], s[2:3], exec
	s_cselect_b32 s13, s21, s25
	s_cselect_b32 s17, s20, s24
	s_ashr_i32 s19, s18, 31
	s_lshl_b64 s[22:23], s[18:19], 19
	s_add_u32 s22, s36, s22
	s_addc_u32 s23, s37, s23
	s_and_b64 s[28:29], s[2:3], exec
	s_cselect_b32 s19, s23, s27
	s_cselect_b32 s42, s22, s26
	s_add_u32 s24, s24, 0x40080
	s_addc_u32 s25, s25, 0
	s_add_u32 s44, s26, 0x100
	s_addc_u32 s45, s27, 0
	s_mov_b32 s52, -2
	v_add_u32_e32 v158, s90, v200
	v_add_u32_e32 v174, s81, v200
	ds_read_b128 v[146:149], v158
	ds_read_b128 v[150:153], v158 offset:1024
	ds_read_b128 v[154:157], v158 offset:2048
	ds_read_b128 v[158:161], v158 offset:3072
	ds_read_b128 v[162:165], v174
	ds_read_b128 v[166:169], v174 offset:1024
	ds_read_b128 v[170:173], v174 offset:2048
	ds_read_b128 v[174:177], v174 offset:3072
	s_add_u32 s26, s24, 0xfffc0080
	s_addc_u32 s27, s25, -1
	s_cmp_eq_u32 s52, 12
	s_cselect_b32 s29, s13, s27
	s_cselect_b32 s28, s17, s26
	s_cselect_b32 s27, s19, s45
	s_cselect_b32 s26, s42, s44
	s_add_u32 s98, s26, s46
	s_addc_u32 s99, s27, s47
	s_add_u32 s100, s28, s46
	s_addc_u32 s101, s29, s47
	s_add_i32 m0, s39, 0xc000
	ds_read_b128 v[216:219], v202
	ds_read_b128 v[220:223], v202 offset:1024
	ds_read_b128 v[224:227], v202 offset:2048
	ds_read_b128 v[228:231], v202 offset:3072
	ds_read_b128 v[232:235], v202 offset:4096
	ds_read_b128 v[236:239], v202 offset:5120
	ds_read_b128 v[240:243], v202 offset:6144
	ds_read_b128 v[244:247], v202 offset:7168
	global_load_lds_dwordx4 v190, s[24:25]
	s_add_i32 m0, s39, 0xe000
	s_nop 0
	global_load_lds_dwordx4 v192, s[24:25]
	s_waitcnt vmcnt(8) lgkmcnt(0)
	s_barrier
	s_setprio 1
	v_mfma_f32_16x16x32_bf16 v[142:145], v[146:149], v[216:219], 0
	v_mfma_f32_16x16x32_bf16 v[138:141], v[154:157], v[216:219], 0
	v_mfma_f32_16x16x32_bf16 v[126:129], v[146:149], v[224:227], 0
	v_mfma_f32_16x16x32_bf16 v[122:125], v[154:157], v[224:227], 0
	v_mfma_f32_16x16x32_bf16 v[110:113], v[146:149], v[232:235], 0
	v_mfma_f32_16x16x32_bf16 v[106:109], v[154:157], v[232:235], 0
	v_mfma_f32_16x16x32_bf16 v[94:97], v[146:149], v[240:243], 0
	v_mfma_f32_16x16x32_bf16 v[90:93], v[154:157], v[240:243], 0
	v_mfma_f32_16x16x32_bf16 v[142:145], v[150:153], v[220:223], v[142:145]
	v_mfma_f32_16x16x32_bf16 v[138:141], v[158:161], v[220:223], v[138:141]
	v_mfma_f32_16x16x32_bf16 v[126:129], v[150:153], v[228:231], v[126:129]
	v_mfma_f32_16x16x32_bf16 v[122:125], v[158:161], v[228:231], v[122:125]
	v_mfma_f32_16x16x32_bf16 v[110:113], v[150:153], v[236:239], v[110:113]
	v_mfma_f32_16x16x32_bf16 v[106:109], v[158:161], v[236:239], v[106:109]
	v_mfma_f32_16x16x32_bf16 v[94:97], v[150:153], v[244:247], v[94:97]
	v_mfma_f32_16x16x32_bf16 v[90:93], v[158:161], v[244:247], v[90:93]
	v_mfma_f32_16x16x32_bf16 v[134:137], v[162:165], v[216:219], 0
	v_mfma_f32_16x16x32_bf16 v[130:133], v[170:173], v[216:219], 0
	v_mfma_f32_16x16x32_bf16 v[118:121], v[162:165], v[224:227], 0
	v_mfma_f32_16x16x32_bf16 v[114:117], v[170:173], v[224:227], 0
	v_mfma_f32_16x16x32_bf16 v[102:105], v[162:165], v[232:235], 0
	v_mfma_f32_16x16x32_bf16 v[98:101], v[170:173], v[232:235], 0
	v_mfma_f32_16x16x32_bf16 v[86:89], v[162:165], v[240:243], 0
	v_mfma_f32_16x16x32_bf16 v[82:85], v[170:173], v[240:243], 0
	v_mfma_f32_16x16x32_bf16 v[134:137], v[166:169], v[220:223], v[134:137]
	v_mfma_f32_16x16x32_bf16 v[130:133], v[174:177], v[220:223], v[130:133]
	v_mfma_f32_16x16x32_bf16 v[118:121], v[166:169], v[228:231], v[118:121]
	v_mfma_f32_16x16x32_bf16 v[114:117], v[174:177], v[228:231], v[114:117]
	v_mfma_f32_16x16x32_bf16 v[102:105], v[166:169], v[236:239], v[102:105]
	v_mfma_f32_16x16x32_bf16 v[98:101], v[174:177], v[236:239], v[98:101]
	v_mfma_f32_16x16x32_bf16 v[86:89], v[166:169], v[244:247], v[86:89]
	v_mfma_f32_16x16x32_bf16 v[82:85], v[174:177], v[244:247], v[82:85]
	s_setprio 0
	s_barrier
	s_add_i32 s53, s90, s38
	s_mov_b32 m0, s53
	ds_read_b128 v[216:219], v202 offset:16384
	ds_read_b128 v[220:223], v202 offset:17408
	ds_read_b128 v[224:227], v202 offset:18432
	ds_read_b128 v[228:231], v202 offset:19456
	ds_read_b128 v[232:235], v202 offset:20480
	ds_read_b128 v[236:239], v202 offset:21504
	ds_read_b128 v[240:243], v202 offset:22528
	ds_read_b128 v[244:247], v202 offset:23552
	global_load_lds_dwordx4 v180, s[26:27]
	s_add_i32 m0, s53, 0x2000
	s_add_u32 vcc_lo, s26, 0x40000
	s_addc_u32 vcc_hi, s27, 0
	s_add_i32 s53, s81, s38
	global_load_lds_dwordx4 v184, s[26:27]
	s_mov_b32 m0, s53
	s_nop 0
	global_load_lds_dwordx4 v180, vcc
	s_add_i32 m0, s53, 0x2000
	s_nop 0
	global_load_lds_dwordx4 v184, vcc
	s_mov_b32 m0, s39
	s_nop 0
	global_load_lds_dwordx4 v178, s[28:29]
	s_mov_b32 m0, s60
	s_nop 0
	global_load_lds_dwordx4 v182, s[28:29]
	s_waitcnt vmcnt(8) lgkmcnt(0)
	s_barrier
; #define PG8_STAGE(bufoff, gbase, voff) do { _Pragma("unroll") for (int _i = 0; _i < 2; ++_i) \
;         __builtin_amdgcn_global_load_lds((const unsigned*)((const char*)(gbase) + (voff)[_i]), (PG8_LAS unsigned*)(lds + (bufoff) + ldsw + _i * 8192), 16, 0, 0); } while (0)
; #define PG8_LDA(dst, b, h) do { _Pragma("unroll") for (int m = 0; m < 4; ++m) _Pragma("unroll") for (int k = 0; k < 2; ++k) dst[m][k] = *(const PG8_LAS bf16x8*)(lds + PG8_SA(b, h) + aoff + m * 2048 + k * 1024); } while (0)
; #define PG8_LDB(dst, b, h) do { _Pragma("unroll") for (int n = 0; n < 2; ++n) _Pragma("unroll") for (int k = 0; k < 2; ++k) dst[n][k] = *(const PG8_LAS bf16x8*)(lds + PG8_SB(b, h) + boff + n * 2048 + k * 1024); } while (0)
; #define PG8_MMA(ai, bj, At, Bt) do { __builtin_amdgcn_s_setprio(1); _Pragma("unroll") for (int m = 0; m < 4; ++m) _Pragma("unroll") for (int n = 0; n < 2; ++n) _Pragma("unroll") for (int k = 0; k < 2; ++k) \
;         acc[ai][bj][m][n] = __builtin_amdgcn_mfma_f32_16x16x32_bf16(Bt[n][k], At[m][k], acc[ai][bj][m][n], 0, 0, 0); __builtin_amdgcn_s_setprio(0); } while (0)
; #define PG8_WAIT_V(n) asm volatile("s_waitcnt vmcnt(" #n ")" ::: "memory")
; #define PG8_WAIT_L(n) asm volatile("s_waitcnt lgkmcnt(" #n ")" ::: "memory")
; #define PG8_BAR __builtin_amdgcn_s_barrier()
; #define PG8_SCHED __builtin_amdgcn_sched_barrier(0)
; template <class Epi, class Sched, bool ALIGN_EPI = false, bool SP2 = false>
; __device__ __forceinline__ void gemm_phase(PG8_LAS unsigned char* lds, const Gemm g, const Sched& S, const Epi& E) {
;     ...
;             PG8_WAIT_V(8); PG8_WAIT_L(0); PG8_BAR; PG8_MMA(1, 0, At, B0); PG8_MMA(1, 1, At, B1); PG8_BAR; PG8_SCHED;
;             PG8_LDB(B0, 1, 0); PG8_LDB(B1, 1, 1); PG8_SCHED; PG8_LDA(At, 1, 0); PG8_STAGE(PG8_SA(0, 1), a2 + hstep, voffA);
;             PG8_WAIT_V(8); PG8_WAIT_L(0); PG8_BAR; PG8_MMA(0, 0, At, B0); PG8_MMA(0, 1, At, B1); PG8_BAR; PG8_SCHED;
	s_setprio 1
	v_mfma_f32_16x16x32_bf16 v[78:81], v[146:149], v[216:219], 0
	v_mfma_f32_16x16x32_bf16 v[74:77], v[154:157], v[216:219], 0
	v_mfma_f32_16x16x32_bf16 v[62:65], v[146:149], v[224:227], 0
	v_mfma_f32_16x16x32_bf16 v[58:61], v[154:157], v[224:227], 0
	v_mfma_f32_16x16x32_bf16 v[46:49], v[146:149], v[232:235], 0
	v_mfma_f32_16x16x32_bf16 v[42:45], v[154:157], v[232:235], 0
	v_mfma_f32_16x16x32_bf16 v[30:33], v[146:149], v[240:243], 0
	v_mfma_f32_16x16x32_bf16 v[26:29], v[154:157], v[240:243], 0
	v_mfma_f32_16x16x32_bf16 v[78:81], v[150:153], v[220:223], v[78:81]
	v_mfma_f32_16x16x32_bf16 v[74:77], v[158:161], v[220:223], v[74:77]
	v_mfma_f32_16x16x32_bf16 v[62:65], v[150:153], v[228:231], v[62:65]
	v_mfma_f32_16x16x32_bf16 v[58:61], v[158:161], v[228:231], v[58:61]
	v_mfma_f32_16x16x32_bf16 v[46:49], v[150:153], v[236:239], v[46:49]
	v_mfma_f32_16x16x32_bf16 v[42:45], v[158:161], v[236:239], v[42:45]
	v_mfma_f32_16x16x32_bf16 v[30:33], v[150:153], v[244:247], v[30:33]
	v_mfma_f32_16x16x32_bf16 v[26:29], v[158:161], v[244:247], v[26:29]
	v_mfma_f32_16x16x32_bf16 v[70:73], v[162:165], v[216:219], 0
	v_mfma_f32_16x16x32_bf16 v[66:69], v[170:173], v[216:219], 0
	v_mfma_f32_16x16x32_bf16 v[54:57], v[162:165], v[224:227], 0
	v_mfma_f32_16x16x32_bf16 v[50:53], v[170:173], v[224:227], 0
	v_mfma_f32_16x16x32_bf16 v[38:41], v[162:165], v[232:235], 0
	v_mfma_f32_16x16x32_bf16 v[34:37], v[170:173], v[232:235], 0
	v_mfma_f32_16x16x32_bf16 v[22:25], v[162:165], v[240:243], 0
	v_mfma_f32_16x16x32_bf16 v[18:21], v[170:173], v[240:243], 0
	v_mfma_f32_16x16x32_bf16 v[70:73], v[166:169], v[220:223], v[70:73]
	v_mfma_f32_16x16x32_bf16 v[66:69], v[174:177], v[220:223], v[66:69]
	v_mfma_f32_16x16x32_bf16 v[54:57], v[166:169], v[228:231], v[54:57]
	v_mfma_f32_16x16x32_bf16 v[50:53], v[174:177], v[228:231], v[50:53]
	v_mfma_f32_16x16x32_bf16 v[38:41], v[166:169], v[236:239], v[38:41]
	v_mfma_f32_16x16x32_bf16 v[34:37], v[174:177], v[236:239], v[34:37]
	v_mfma_f32_16x16x32_bf16 v[22:25], v[166:169], v[244:247], v[22:25]
	v_mfma_f32_16x16x32_bf16 v[18:21], v[174:177], v[244:247], v[18:21]
	s_setprio 0
	s_barrier
	v_add_u32_e32 v158, s82, v200
	v_add_u32_e32 v174, s83, v200
	ds_read_b128 v[146:149], v158
	ds_read_b128 v[150:153], v158 offset:1024
	ds_read_b128 v[154:157], v158 offset:2048
	ds_read_b128 v[158:161], v158 offset:3072
	ds_read_b128 v[162:165], v174
	ds_read_b128 v[166:169], v174 offset:1024
	ds_read_b128 v[170:173], v174 offset:2048
	ds_read_b128 v[174:177], v174 offset:3072
	s_add_u32 s28, s28, 0x40000
	s_addc_u32 s29, s29, 0
	s_mov_b32 m0, s61
	ds_read_b128 v[216:219], v202 offset:32768
	ds_read_b128 v[220:223], v202 offset:33792
	ds_read_b128 v[224:227], v202 offset:34816
	ds_read_b128 v[228:231], v202 offset:35840
	ds_read_b128 v[232:235], v202 offset:36864
	ds_read_b128 v[236:239], v202 offset:37888
	ds_read_b128 v[240:243], v202 offset:38912
	ds_read_b128 v[244:247], v202 offset:39936
	global_load_lds_dwordx4 v178, s[28:29]
	s_mov_b32 m0, s62
	s_nop 0
	global_load_lds_dwordx4 v182, s[28:29]
	s_waitcnt vmcnt(8) lgkmcnt(0)
	s_barrier
	s_setprio 1
	v_mfma_f32_16x16x32_bf16 v[142:145], v[146:149], v[216:219], v[142:145]
	v_mfma_f32_16x16x32_bf16 v[138:141], v[154:157], v[216:219], v[138:141]
	v_mfma_f32_16x16x32_bf16 v[126:129], v[146:149], v[224:227], v[126:129]
	v_mfma_f32_16x16x32_bf16 v[122:125], v[154:157], v[224:227], v[122:125]
	v_mfma_f32_16x16x32_bf16 v[110:113], v[146:149], v[232:235], v[110:113]
	v_mfma_f32_16x16x32_bf16 v[106:109], v[154:157], v[232:235], v[106:109]
	v_mfma_f32_16x16x32_bf16 v[94:97], v[146:149], v[240:243], v[94:97]
	v_mfma_f32_16x16x32_bf16 v[90:93], v[154:157], v[240:243], v[90:93]
	v_mfma_f32_16x16x32_bf16 v[142:145], v[150:153], v[220:223], v[142:145]
	v_mfma_f32_16x16x32_bf16 v[138:141], v[158:161], v[220:223], v[138:141]
	v_mfma_f32_16x16x32_bf16 v[126:129], v[150:153], v[228:231], v[126:129]
	v_mfma_f32_16x16x32_bf16 v[122:125], v[158:161], v[228:231], v[122:125]
	v_mfma_f32_16x16x32_bf16 v[110:113], v[150:153], v[236:239], v[110:113]
	v_mfma_f32_16x16x32_bf16 v[106:109], v[158:161], v[236:239], v[106:109]
	v_mfma_f32_16x16x32_bf16 v[94:97], v[150:153], v[244:247], v[94:97]
	v_mfma_f32_16x16x32_bf16 v[90:93], v[158:161], v[244:247], v[90:93]
	v_mfma_f32_16x16x32_bf16 v[134:137], v[162:165], v[216:219], v[134:137]
	v_mfma_f32_16x16x32_bf16 v[130:133], v[170:173], v[216:219], v[130:133]
	v_mfma_f32_16x16x32_bf16 v[118:121], v[162:165], v[224:227], v[118:121]
	v_mfma_f32_16x16x32_bf16 v[114:117], v[170:173], v[224:227], v[114:117]
	v_mfma_f32_16x16x32_bf16 v[102:105], v[162:165], v[232:235], v[102:105]
	v_mfma_f32_16x16x32_bf16 v[98:101], v[170:173], v[232:235], v[98:101]
	v_mfma_f32_16x16x32_bf16 v[86:89], v[162:165], v[240:243], v[86:89]
	v_mfma_f32_16x16x32_bf16 v[82:85], v[170:173], v[240:243], v[82:85]
	v_mfma_f32_16x16x32_bf16 v[134:137], v[166:169], v[220:223], v[134:137]
	v_mfma_f32_16x16x32_bf16 v[130:133], v[174:177], v[220:223], v[130:133]
	v_mfma_f32_16x16x32_bf16 v[118:121], v[166:169], v[228:231], v[118:121]
	v_mfma_f32_16x16x32_bf16 v[114:117], v[174:177], v[228:231], v[114:117]
	v_mfma_f32_16x16x32_bf16 v[102:105], v[166:169], v[236:239], v[102:105]
	v_mfma_f32_16x16x32_bf16 v[98:101], v[174:177], v[236:239], v[98:101]
	v_mfma_f32_16x16x32_bf16 v[86:89], v[166:169], v[244:247], v[86:89]
	v_mfma_f32_16x16x32_bf16 v[82:85], v[174:177], v[244:247], v[82:85]
	s_setprio 0
	s_barrier
; #define PG8_STAGE(bufoff, gbase, voff) do { _Pragma("unroll") for (int _i = 0; _i < 2; ++_i) \
;         __builtin_amdgcn_global_load_lds((const unsigned*)((const char*)(gbase) + (voff)[_i]), (PG8_LAS unsigned*)(lds + (bufoff) + ldsw + _i * 8192), 16, 0, 0); } while (0)
; #define PG8_LDA(dst, b, h) do { _Pragma("unroll") for (int m = 0; m < 4; ++m) _Pragma("unroll") for (int k = 0; k < 2; ++k) dst[m][k] = *(const PG8_LAS bf16x8*)(lds + PG8_SA(b, h) + aoff + m * 2048 + k * 1024); } while (0)
; #define PG8_LDB(dst, b, h) do { _Pragma("unroll") for (int n = 0; n < 2; ++n) _Pragma("unroll") for (int k = 0; k < 2; ++k) dst[n][k] = *(const PG8_LAS bf16x8*)(lds + PG8_SB(b, h) + boff + n * 2048 + k * 1024); } while (0)
; #define PG8_MMA(ai, bj, At, Bt) do { __builtin_amdgcn_s_setprio(1); _Pragma("unroll") for (int m = 0; m < 4; ++m) _Pragma("unroll") for (int n = 0; n < 2; ++n) _Pragma("unroll") for (int k = 0; k < 2; ++k) \
;         acc[ai][bj][m][n] = __builtin_amdgcn_mfma_f32_16x16x32_bf16(Bt[n][k], At[m][k], acc[ai][bj][m][n], 0, 0, 0); __builtin_amdgcn_s_setprio(0); } while (0)
; #define PG8_WAIT_V(n) asm volatile("s_waitcnt vmcnt(" #n ")" ::: "memory")
; template <class Epi, class Sched, bool ALIGN_EPI = false, bool SP2 = false>
; __device__ __forceinline__ void gemm_phase(PG8_LAS unsigned char* lds, const Gemm g, const Sched& S, const Epi& E) {
;     ...
;             PG8_LDB(B0, 0, 0); PG8_LDB(B1, 0, 1); PG8_SCHED; PG8_LDA(At, 0, 0); PG8_STAGE(PG8_SA(1, 1), a1 + hstep, voffA);
;             PG8_WAIT_V(8); PG8_WAIT_L(0); PG8_BAR; PG8_MMA(0, 0, At, B0); PG8_MMA(0, 1, At, B1); PG8_BAR; PG8_SCHED;
;             PG8_LDA(At, 0, 1); PG8_STAGE(PG8_SB(0, 0), b2, voffB); PG8_STAGE(PG8_SB(0, 1), b2 + hstep, voffB); PG8_STAGE(PG8_SA(0, 0), a2, voffA);
;             PG8_WAIT_V(8); PG8_WAIT_L(0); PG8_BAR; PG8_MMA(1, 0, At, B0); PG8_MMA(1, 1, At, B1); PG8_BAR; PG8_SCHED;
;             PG8_LDB(B0, 1, 0); PG8_LDB(B1, 1, 1); PG8_SCHED; PG8_LDA(At, 1, 0); PG8_STAGE(PG8_SA(0, 1), a2 + hstep, voffA);
;             PG8_WAIT_V(8); PG8_WAIT_L(0); PG8_BAR; PG8_MMA(0, 0, At, B0); PG8_MMA(0, 1, At, B1); PG8_BAR; PG8_SCHED;
;             PG8_LDA(At, 1, 1); PG8_STAGE(PG8_SB(1, 0), b3, voffB); PG8_STAGE(PG8_SB(1, 1), b3 + hstep, voffB); PG8_STAGE(PG8_SA(1, 0), a3, voffA);
;             PG8_WAIT_V(8); PG8_WAIT_L(0); PG8_BAR; PG8_MMA(1, 0, At, B0); PG8_MMA(1, 1, At, B1); PG8_BAR; PG8_SCHED;
	s_add_i32 s28, s82, s38
	s_mov_b32 m0, s28
	ds_read_b128 v[216:219], v202 offset:49152
	ds_read_b128 v[220:223], v202 offset:50176
	ds_read_b128 v[224:227], v202 offset:51200
	ds_read_b128 v[228:231], v202 offset:52224
	ds_read_b128 v[232:235], v202 offset:53248
	ds_read_b128 v[236:239], v202 offset:54272
	ds_read_b128 v[240:243], v202 offset:55296
	ds_read_b128 v[244:247], v202 offset:56320
	global_load_lds_dwordx4 v180, s[98:99]
	s_add_i32 m0, s28, 0x2000
	s_add_u32 s26, s26, 0x40080
	s_addc_u32 s27, s27, 0
	s_add_i32 s28, s83, s38
	global_load_lds_dwordx4 v184, s[98:99]
	s_mov_b32 m0, s28
	s_nop 0
	global_load_lds_dwordx4 v180, s[26:27]
	s_add_i32 m0, s28, 0x2000
	s_nop 0
	global_load_lds_dwordx4 v184, s[26:27]
	s_mov_b32 m0, s63
	s_nop 0
	global_load_lds_dwordx4 v178, s[100:101]
	s_mov_b32 m0, s64
	s_nop 0
	global_load_lds_dwordx4 v182, s[100:101]
	s_waitcnt vmcnt(8) lgkmcnt(0)
	s_barrier
	s_setprio 1
	v_mfma_f32_16x16x32_bf16 v[78:81], v[146:149], v[216:219], v[78:81]
	v_mfma_f32_16x16x32_bf16 v[74:77], v[154:157], v[216:219], v[74:77]
	v_mfma_f32_16x16x32_bf16 v[62:65], v[146:149], v[224:227], v[62:65]
	v_mfma_f32_16x16x32_bf16 v[58:61], v[154:157], v[224:227], v[58:61]
	v_mfma_f32_16x16x32_bf16 v[46:49], v[146:149], v[232:235], v[46:49]
	v_mfma_f32_16x16x32_bf16 v[42:45], v[154:157], v[232:235], v[42:45]
	v_mfma_f32_16x16x32_bf16 v[30:33], v[146:149], v[240:243], v[30:33]
	v_mfma_f32_16x16x32_bf16 v[26:29], v[154:157], v[240:243], v[26:29]
	v_mfma_f32_16x16x32_bf16 v[78:81], v[150:153], v[220:223], v[78:81]
	v_mfma_f32_16x16x32_bf16 v[74:77], v[158:161], v[220:223], v[74:77]
	v_mfma_f32_16x16x32_bf16 v[62:65], v[150:153], v[228:231], v[62:65]
	v_mfma_f32_16x16x32_bf16 v[58:61], v[158:161], v[228:231], v[58:61]
	v_mfma_f32_16x16x32_bf16 v[46:49], v[150:153], v[236:239], v[46:49]
	v_mfma_f32_16x16x32_bf16 v[42:45], v[158:161], v[236:239], v[42:45]
	v_mfma_f32_16x16x32_bf16 v[30:33], v[150:153], v[244:247], v[30:33]
	v_mfma_f32_16x16x32_bf16 v[26:29], v[158:161], v[244:247], v[26:29]
	v_mfma_f32_16x16x32_bf16 v[70:73], v[162:165], v[216:219], v[70:73]
	v_mfma_f32_16x16x32_bf16 v[66:69], v[170:173], v[216:219], v[66:69]
	v_mfma_f32_16x16x32_bf16 v[54:57], v[162:165], v[224:227], v[54:57]
	v_mfma_f32_16x16x32_bf16 v[50:53], v[170:173], v[224:227], v[50:53]
	v_mfma_f32_16x16x32_bf16 v[38:41], v[162:165], v[232:235], v[38:41]
	v_mfma_f32_16x16x32_bf16 v[34:37], v[170:173], v[232:235], v[34:37]
	v_mfma_f32_16x16x32_bf16 v[22:25], v[162:165], v[240:243], v[22:25]
	v_mfma_f32_16x16x32_bf16 v[18:21], v[170:173], v[240:243], v[18:21]
	v_mfma_f32_16x16x32_bf16 v[70:73], v[166:169], v[220:223], v[70:73]
	v_mfma_f32_16x16x32_bf16 v[66:69], v[174:177], v[220:223], v[66:69]
	v_mfma_f32_16x16x32_bf16 v[54:57], v[166:169], v[228:231], v[54:57]
	v_mfma_f32_16x16x32_bf16 v[50:53], v[174:177], v[228:231], v[50:53]
	v_mfma_f32_16x16x32_bf16 v[38:41], v[166:169], v[236:239], v[38:41]
	v_mfma_f32_16x16x32_bf16 v[34:37], v[174:177], v[236:239], v[34:37]
	v_mfma_f32_16x16x32_bf16 v[22:25], v[166:169], v[244:247], v[22:25]
	v_mfma_f32_16x16x32_bf16 v[18:21], v[174:177], v[244:247], v[18:21]
	s_setprio 0
	s_barrier
	s_add_i32 s52, s52, 2
	s_add_u32 s24, s24, 0x100
	s_addc_u32 s25, s25, 0
	s_add_u32 s44, s44, 0x100
	s_addc_u32 s45, s45, 0
.LBB0_319:
	v_add_u32_e32 v158, s90, v200
	v_add_u32_e32 v174, s81, v200
	ds_read_b128 v[146:149], v158
	ds_read_b128 v[150:153], v158 offset:1024
	ds_read_b128 v[154:157], v158 offset:2048
	ds_read_b128 v[158:161], v158 offset:3072
	ds_read_b128 v[162:165], v174
	ds_read_b128 v[166:169], v174 offset:1024
	ds_read_b128 v[170:173], v174 offset:2048
	ds_read_b128 v[174:177], v174 offset:3072
	s_add_u32 s26, s24, 0xfffc0080
	s_addc_u32 s27, s25, -1
	s_cmp_eq_u32 s52, 12
	s_cselect_b32 s29, s13, s27
	s_cselect_b32 s28, s17, s26
	s_cselect_b32 s27, s19, s45
	s_cselect_b32 s26, s42, s44
	s_add_u32 s98, s26, s46
	s_addc_u32 s99, s27, s47
	s_add_u32 s100, s28, s46
	s_addc_u32 s101, s29, s47
	s_add_i32 m0, s39, 0xc000
	ds_read_b128 v[216:219], v202
	ds_read_b128 v[220:223], v202 offset:1024
	ds_read_b128 v[224:227], v202 offset:2048
	ds_read_b128 v[228:231], v202 offset:3072
	ds_read_b128 v[232:235], v202 offset:4096
	ds_read_b128 v[236:239], v202 offset:5120
	ds_read_b128 v[240:243], v202 offset:6144
	ds_read_b128 v[244:247], v202 offset:7168
	global_load_lds_dwordx4 v190, s[24:25]
	s_add_i32 m0, s39, 0xe000
	s_nop 0
	global_load_lds_dwordx4 v192, s[24:25]
	s_waitcnt vmcnt(8) lgkmcnt(0)
	s_barrier
; #define PG8_STAGE(bufoff, gbase, voff) do { _Pragma("unroll") for (int _i = 0; _i < 2; ++_i) \
;         __builtin_amdgcn_global_load_lds((const unsigned*)((const char*)(gbase) + (voff)[_i]), (PG8_LAS unsigned*)(lds + (bufoff) + ldsw + _i * 8192), 16, 0, 0); } while (0)
; #define PG8_LDA(dst, b, h) do { _Pragma("unroll") for (int m = 0; m < 4; ++m) _Pragma("unroll") for (int k = 0; k < 2; ++k) dst[m][k] = *(const PG8_LAS bf16x8*)(lds + PG8_SA(b, h) + aoff + m * 2048 + k * 1024); } while (0)
; #define PG8_LDB(dst, b, h) do { _Pragma("unroll") for (int n = 0; n < 2; ++n) _Pragma("unroll") for (int k = 0; k < 2; ++k) dst[n][k] = *(const PG8_LAS bf16x8*)(lds + PG8_SB(b, h) + boff + n * 2048 + k * 1024); } while (0)
; #define PG8_MMA(ai, bj, At, Bt) do { __builtin_amdgcn_s_setprio(1); _Pragma("unroll") for (int m = 0; m < 4; ++m) _Pragma("unroll") for (int n = 0; n < 2; ++n) _Pragma("unroll") for (int k = 0; k < 2; ++k) \
;         acc[ai][bj][m][n] = __builtin_amdgcn_mfma_f32_16x16x32_bf16(Bt[n][k], At[m][k], acc[ai][bj][m][n], 0, 0, 0); __builtin_amdgcn_s_setprio(0); } while (0)
; #define PG8_WAIT_V(n) asm volatile("s_waitcnt vmcnt(" #n ")" ::: "memory")
; template <class Epi, class Sched, bool ALIGN_EPI = false, bool SP2 = false>
; __device__ __forceinline__ void gemm_phase(PG8_LAS unsigned char* lds, const Gemm g, const Sched& S, const Epi& E) {
;     ...
;             PG8_LDB(B0, 0, 0); PG8_LDB(B1, 0, 1); PG8_SCHED; PG8_LDA(At, 0, 0); PG8_STAGE(PG8_SA(1, 1), a1 + hstep, voffA);
;             PG8_WAIT_V(8); PG8_WAIT_L(0); PG8_BAR; PG8_MMA(0, 0, At, B0); PG8_MMA(0, 1, At, B1); PG8_BAR; PG8_SCHED;
;             PG8_LDA(At, 0, 1); PG8_STAGE(PG8_SB(0, 0), b2, voffB); PG8_STAGE(PG8_SB(0, 1), b2 + hstep, voffB); PG8_STAGE(PG8_SA(0, 0), a2, voffA);
;             PG8_WAIT_V(8); PG8_WAIT_L(0); PG8_BAR; PG8_MMA(1, 0, At, B0); PG8_MMA(1, 1, At, B1); PG8_BAR; PG8_SCHED;
;             PG8_LDB(B0, 1, 0); PG8_LDB(B1, 1, 1); PG8_SCHED; PG8_LDA(At, 1, 0); PG8_STAGE(PG8_SA(0, 1), a2 + hstep, voffA);
;             PG8_WAIT_V(8); PG8_WAIT_L(0); PG8_BAR; PG8_MMA(0, 0, At, B0); PG8_MMA(0, 1, At, B1); PG8_BAR; PG8_SCHED;
;             PG8_LDA(At, 1, 1); PG8_STAGE(PG8_SB(1, 0), b3, voffB); PG8_STAGE(PG8_SB(1, 1), b3 + hstep, voffB); PG8_STAGE(PG8_SA(1, 0), a3, voffA);
;             PG8_WAIT_V(8); PG8_WAIT_L(0); PG8_BAR; PG8_MMA(1, 0, At, B0); PG8_MMA(1, 1, At, B1); PG8_BAR; PG8_SCHED;
	s_setprio 1
	v_mfma_f32_16x16x32_bf16 v[142:145], v[146:149], v[216:219], v[142:145]
	v_mfma_f32_16x16x32_bf16 v[138:141], v[154:157], v[216:219], v[138:141]
	v_mfma_f32_16x16x32_bf16 v[126:129], v[146:149], v[224:227], v[126:129]
	v_mfma_f32_16x16x32_bf16 v[122:125], v[154:157], v[224:227], v[122:125]
	v_mfma_f32_16x16x32_bf16 v[110:113], v[146:149], v[232:235], v[110:113]
	v_mfma_f32_16x16x32_bf16 v[106:109], v[154:157], v[232:235], v[106:109]
	v_mfma_f32_16x16x32_bf16 v[94:97], v[146:149], v[240:243], v[94:97]
	v_mfma_f32_16x16x32_bf16 v[90:93], v[154:157], v[240:243], v[90:93]
	v_mfma_f32_16x16x32_bf16 v[142:145], v[150:153], v[220:223], v[142:145]
	v_mfma_f32_16x16x32_bf16 v[138:141], v[158:161], v[220:223], v[138:141]
	v_mfma_f32_16x16x32_bf16 v[126:129], v[150:153], v[228:231], v[126:129]
	v_mfma_f32_16x16x32_bf16 v[122:125], v[158:161], v[228:231], v[122:125]
	v_mfma_f32_16x16x32_bf16 v[110:113], v[150:153], v[236:239], v[110:113]
	v_mfma_f32_16x16x32_bf16 v[106:109], v[158:161], v[236:239], v[106:109]
	v_mfma_f32_16x16x32_bf16 v[94:97], v[150:153], v[244:247], v[94:97]
	v_mfma_f32_16x16x32_bf16 v[90:93], v[158:161], v[244:247], v[90:93]
	v_mfma_f32_16x16x32_bf16 v[134:137], v[162:165], v[216:219], v[134:137]
	v_mfma_f32_16x16x32_bf16 v[130:133], v[170:173], v[216:219], v[130:133]
	v_mfma_f32_16x16x32_bf16 v[118:121], v[162:165], v[224:227], v[118:121]
	v_mfma_f32_16x16x32_bf16 v[114:117], v[170:173], v[224:227], v[114:117]
	v_mfma_f32_16x16x32_bf16 v[102:105], v[162:165], v[232:235], v[102:105]
	v_mfma_f32_16x16x32_bf16 v[98:101], v[170:173], v[232:235], v[98:101]
	v_mfma_f32_16x16x32_bf16 v[86:89], v[162:165], v[240:243], v[86:89]
	v_mfma_f32_16x16x32_bf16 v[82:85], v[170:173], v[240:243], v[82:85]
	v_mfma_f32_16x16x32_bf16 v[134:137], v[166:169], v[220:223], v[134:137]
	v_mfma_f32_16x16x32_bf16 v[130:133], v[174:177], v[220:223], v[130:133]
	v_mfma_f32_16x16x32_bf16 v[118:121], v[166:169], v[228:231], v[118:121]
	v_mfma_f32_16x16x32_bf16 v[114:117], v[174:177], v[228:231], v[114:117]
	v_mfma_f32_16x16x32_bf16 v[102:105], v[166:169], v[236:239], v[102:105]
	v_mfma_f32_16x16x32_bf16 v[98:101], v[174:177], v[236:239], v[98:101]
	v_mfma_f32_16x16x32_bf16 v[86:89], v[166:169], v[244:247], v[86:89]
	v_mfma_f32_16x16x32_bf16 v[82:85], v[174:177], v[244:247], v[82:85]
	s_setprio 0
	s_barrier
	s_add_i32 s53, s90, s38
	s_mov_b32 m0, s53
	ds_read_b128 v[216:219], v202 offset:16384
	ds_read_b128 v[220:223], v202 offset:17408
	ds_read_b128 v[224:227], v202 offset:18432
	ds_read_b128 v[228:231], v202 offset:19456
	ds_read_b128 v[232:235], v202 offset:20480
	ds_read_b128 v[236:239], v202 offset:21504
	ds_read_b128 v[240:243], v202 offset:22528
	ds_read_b128 v[244:247], v202 offset:23552
	global_load_lds_dwordx4 v180, s[26:27]
	s_add_i32 m0, s53, 0x2000
	s_add_u32 vcc_lo, s26, 0x40000
	s_addc_u32 vcc_hi, s27, 0
	s_add_i32 s53, s81, s38
	global_load_lds_dwordx4 v184, s[26:27]
	s_mov_b32 m0, s53
	s_nop 0
	global_load_lds_dwordx4 v180, vcc
	s_add_i32 m0, s53, 0x2000
	s_nop 0
	global_load_lds_dwordx4 v184, vcc
	s_mov_b32 m0, s39
	s_nop 0
	global_load_lds_dwordx4 v178, s[28:29]
	s_mov_b32 m0, s60
	s_nop 0
	global_load_lds_dwordx4 v182, s[28:29]
	s_waitcnt vmcnt(8) lgkmcnt(0)
	s_barrier
	s_setprio 1
	v_mfma_f32_16x16x32_bf16 v[78:81], v[146:149], v[216:219], v[78:81]
	v_mfma_f32_16x16x32_bf16 v[74:77], v[154:157], v[216:219], v[74:77]
	v_mfma_f32_16x16x32_bf16 v[62:65], v[146:149], v[224:227], v[62:65]
	v_mfma_f32_16x16x32_bf16 v[58:61], v[154:157], v[224:227], v[58:61]
	v_mfma_f32_16x16x32_bf16 v[46:49], v[146:149], v[232:235], v[46:49]
	v_mfma_f32_16x16x32_bf16 v[42:45], v[154:157], v[232:235], v[42:45]
	v_mfma_f32_16x16x32_bf16 v[30:33], v[146:149], v[240:243], v[30:33]
	v_mfma_f32_16x16x32_bf16 v[26:29], v[154:157], v[240:243], v[26:29]
	v_mfma_f32_16x16x32_bf16 v[78:81], v[150:153], v[220:223], v[78:81]
	v_mfma_f32_16x16x32_bf16 v[74:77], v[158:161], v[220:223], v[74:77]
	v_mfma_f32_16x16x32_bf16 v[62:65], v[150:153], v[228:231], v[62:65]
	v_mfma_f32_16x16x32_bf16 v[58:61], v[158:161], v[228:231], v[58:61]
	v_mfma_f32_16x16x32_bf16 v[46:49], v[150:153], v[236:239], v[46:49]
	v_mfma_f32_16x16x32_bf16 v[42:45], v[158:161], v[236:239], v[42:45]
	v_mfma_f32_16x16x32_bf16 v[30:33], v[150:153], v[244:247], v[30:33]
	v_mfma_f32_16x16x32_bf16 v[26:29], v[158:161], v[244:247], v[26:29]
	v_mfma_f32_16x16x32_bf16 v[70:73], v[162:165], v[216:219], v[70:73]
	v_mfma_f32_16x16x32_bf16 v[66:69], v[170:173], v[216:219], v[66:69]
	v_mfma_f32_16x16x32_bf16 v[54:57], v[162:165], v[224:227], v[54:57]
	v_mfma_f32_16x16x32_bf16 v[50:53], v[170:173], v[224:227], v[50:53]
	v_mfma_f32_16x16x32_bf16 v[38:41], v[162:165], v[232:235], v[38:41]
	v_mfma_f32_16x16x32_bf16 v[34:37], v[170:173], v[232:235], v[34:37]
	v_mfma_f32_16x16x32_bf16 v[22:25], v[162:165], v[240:243], v[22:25]
	v_mfma_f32_16x16x32_bf16 v[18:21], v[170:173], v[240:243], v[18:21]
	v_mfma_f32_16x16x32_bf16 v[70:73], v[166:169], v[220:223], v[70:73]
	v_mfma_f32_16x16x32_bf16 v[66:69], v[174:177], v[220:223], v[66:69]
	v_mfma_f32_16x16x32_bf16 v[54:57], v[166:169], v[228:231], v[54:57]
	v_mfma_f32_16x16x32_bf16 v[50:53], v[174:177], v[228:231], v[50:53]
	v_mfma_f32_16x16x32_bf16 v[38:41], v[166:169], v[236:239], v[38:41]
	v_mfma_f32_16x16x32_bf16 v[34:37], v[174:177], v[236:239], v[34:37]
	v_mfma_f32_16x16x32_bf16 v[22:25], v[166:169], v[244:247], v[22:25]
	v_mfma_f32_16x16x32_bf16 v[18:21], v[174:177], v[244:247], v[18:21]
	s_setprio 0
	s_barrier
; #define PG8_STAGE(bufoff, gbase, voff) do { _Pragma("unroll") for (int _i = 0; _i < 2; ++_i) \
;         __builtin_amdgcn_global_load_lds((const unsigned*)((const char*)(gbase) + (voff)[_i]), (PG8_LAS unsigned*)(lds + (bufoff) + ldsw + _i * 8192), 16, 0, 0); } while (0)
; #define PG8_LDA(dst, b, h) do { _Pragma("unroll") for (int m = 0; m < 4; ++m) _Pragma("unroll") for (int k = 0; k < 2; ++k) dst[m][k] = *(const PG8_LAS bf16x8*)(lds + PG8_SA(b, h) + aoff + m * 2048 + k * 1024); } while (0)
; #define PG8_LDB(dst, b, h) do { _Pragma("unroll") for (int n = 0; n < 2; ++n) _Pragma("unroll") for (int k = 0; k < 2; ++k) dst[n][k] = *(const PG8_LAS bf16x8*)(lds + PG8_SB(b, h) + boff + n * 2048 + k * 1024); } while (0)
; #define PG8_MMA(ai, bj, At, Bt) do { __builtin_amdgcn_s_setprio(1); _Pragma("unroll") for (int m = 0; m < 4; ++m) _Pragma("unroll") for (int n = 0; n < 2; ++n) _Pragma("unroll") for (int k = 0; k < 2; ++k) \
;         acc[ai][bj][m][n] = __builtin_amdgcn_mfma_f32_16x16x32_bf16(Bt[n][k], At[m][k], acc[ai][bj][m][n], 0, 0, 0); __builtin_amdgcn_s_setprio(0); } while (0)
; #define PG8_WAIT_V(n) asm volatile("s_waitcnt vmcnt(" #n ")" ::: "memory")
; template <class Epi, class Sched, bool ALIGN_EPI = false, bool SP2 = false>
; __device__ __forceinline__ void gemm_phase(PG8_LAS unsigned char* lds, const Gemm g, const Sched& S, const Epi& E) {
;     ...
;             PG8_LDB(B0, 0, 0); PG8_LDB(B1, 0, 1); PG8_SCHED; PG8_LDA(At, 0, 0); PG8_STAGE(PG8_SA(1, 1), a1 + hstep, voffA);
;             PG8_WAIT_V(8); PG8_WAIT_L(0); PG8_BAR; PG8_MMA(0, 0, At, B0); PG8_MMA(0, 1, At, B1); PG8_BAR; PG8_SCHED;
;             PG8_LDA(At, 0, 1); PG8_STAGE(PG8_SB(0, 0), b2, voffB); PG8_STAGE(PG8_SB(0, 1), b2 + hstep, voffB); PG8_STAGE(PG8_SA(0, 0), a2, voffA);
;             PG8_WAIT_V(8); PG8_WAIT_L(0); PG8_BAR; PG8_MMA(1, 0, At, B0); PG8_MMA(1, 1, At, B1); PG8_BAR; PG8_SCHED;
;             PG8_LDB(B0, 1, 0); PG8_LDB(B1, 1, 1); PG8_SCHED; PG8_LDA(At, 1, 0); PG8_STAGE(PG8_SA(0, 1), a2 + hstep, voffA);
;             PG8_WAIT_V(8); PG8_WAIT_L(0); PG8_BAR; PG8_MMA(0, 0, At, B0); PG8_MMA(0, 1, At, B1); PG8_BAR; PG8_SCHED;
;             PG8_LDA(At, 1, 1); PG8_STAGE(PG8_SB(1, 0), b3, voffB); PG8_STAGE(PG8_SB(1, 1), b3 + hstep, voffB); PG8_STAGE(PG8_SA(1, 0), a3, voffA);
;             PG8_WAIT_V(8); PG8_WAIT_L(0); PG8_BAR; PG8_MMA(1, 0, At, B0); PG8_MMA(1, 1, At, B1); PG8_BAR; PG8_SCHED;
	v_add_u32_e32 v158, s82, v200
	v_add_u32_e32 v174, s83, v200
	ds_read_b128 v[146:149], v158
	ds_read_b128 v[150:153], v158 offset:1024
	ds_read_b128 v[154:157], v158 offset:2048
	ds_read_b128 v[158:161], v158 offset:3072
	ds_read_b128 v[162:165], v174
	ds_read_b128 v[166:169], v174 offset:1024
	ds_read_b128 v[170:173], v174 offset:2048
	ds_read_b128 v[174:177], v174 offset:3072
	s_add_u32 s28, s28, 0x40000
	s_addc_u32 s29, s29, 0
	s_mov_b32 m0, s61
	ds_read_b128 v[216:219], v202 offset:32768
	ds_read_b128 v[220:223], v202 offset:33792
	ds_read_b128 v[224:227], v202 offset:34816
	ds_read_b128 v[228:231], v202 offset:35840
	ds_read_b128 v[232:235], v202 offset:36864
	ds_read_b128 v[236:239], v202 offset:37888
	ds_read_b128 v[240:243], v202 offset:38912
	ds_read_b128 v[244:247], v202 offset:39936
	global_load_lds_dwordx4 v178, s[28:29]
	s_mov_b32 m0, s62
	s_nop 0
	global_load_lds_dwordx4 v182, s[28:29]
	s_waitcnt vmcnt(8) lgkmcnt(0)
	s_barrier
	s_setprio 1
	v_mfma_f32_16x16x32_bf16 v[142:145], v[146:149], v[216:219], v[142:145]
	v_mfma_f32_16x16x32_bf16 v[138:141], v[154:157], v[216:219], v[138:141]
	v_mfma_f32_16x16x32_bf16 v[126:129], v[146:149], v[224:227], v[126:129]
	v_mfma_f32_16x16x32_bf16 v[122:125], v[154:157], v[224:227], v[122:125]
	v_mfma_f32_16x16x32_bf16 v[110:113], v[146:149], v[232:235], v[110:113]
	v_mfma_f32_16x16x32_bf16 v[106:109], v[154:157], v[232:235], v[106:109]
	v_mfma_f32_16x16x32_bf16 v[94:97], v[146:149], v[240:243], v[94:97]
	v_mfma_f32_16x16x32_bf16 v[90:93], v[154:157], v[240:243], v[90:93]
	v_mfma_f32_16x16x32_bf16 v[142:145], v[150:153], v[220:223], v[142:145]
	v_mfma_f32_16x16x32_bf16 v[138:141], v[158:161], v[220:223], v[138:141]
	v_mfma_f32_16x16x32_bf16 v[126:129], v[150:153], v[228:231], v[126:129]
	v_mfma_f32_16x16x32_bf16 v[122:125], v[158:161], v[228:231], v[122:125]
	v_mfma_f32_16x16x32_bf16 v[110:113], v[150:153], v[236:239], v[110:113]
	v_mfma_f32_16x16x32_bf16 v[106:109], v[158:161], v[236:239], v[106:109]
	v_mfma_f32_16x16x32_bf16 v[94:97], v[150:153], v[244:247], v[94:97]
	v_mfma_f32_16x16x32_bf16 v[90:93], v[158:161], v[244:247], v[90:93]
	v_mfma_f32_16x16x32_bf16 v[134:137], v[162:165], v[216:219], v[134:137]
	v_mfma_f32_16x16x32_bf16 v[130:133], v[170:173], v[216:219], v[130:133]
	v_mfma_f32_16x16x32_bf16 v[118:121], v[162:165], v[224:227], v[118:121]
	v_mfma_f32_16x16x32_bf16 v[114:117], v[170:173], v[224:227], v[114:117]
	v_mfma_f32_16x16x32_bf16 v[102:105], v[162:165], v[232:235], v[102:105]
	v_mfma_f32_16x16x32_bf16 v[98:101], v[170:173], v[232:235], v[98:101]
	v_mfma_f32_16x16x32_bf16 v[86:89], v[162:165], v[240:243], v[86:89]
	v_mfma_f32_16x16x32_bf16 v[82:85], v[170:173], v[240:243], v[82:85]
	v_mfma_f32_16x16x32_bf16 v[134:137], v[166:169], v[220:223], v[134:137]
	v_mfma_f32_16x16x32_bf16 v[130:133], v[174:177], v[220:223], v[130:133]
	v_mfma_f32_16x16x32_bf16 v[118:121], v[166:169], v[228:231], v[118:121]
	v_mfma_f32_16x16x32_bf16 v[114:117], v[174:177], v[228:231], v[114:117]
	v_mfma_f32_16x16x32_bf16 v[102:105], v[166:169], v[236:239], v[102:105]
	v_mfma_f32_16x16x32_bf16 v[98:101], v[174:177], v[236:239], v[98:101]
	v_mfma_f32_16x16x32_bf16 v[86:89], v[166:169], v[244:247], v[86:89]
	v_mfma_f32_16x16x32_bf16 v[82:85], v[174:177], v[244:247], v[82:85]
	s_setprio 0
	s_barrier
	s_add_i32 s28, s82, s38
	s_mov_b32 m0, s28
	ds_read_b128 v[216:219], v202 offset:49152
	ds_read_b128 v[220:223], v202 offset:50176
	ds_read_b128 v[224:227], v202 offset:51200
	ds_read_b128 v[228:231], v202 offset:52224
	ds_read_b128 v[232:235], v202 offset:53248
	ds_read_b128 v[236:239], v202 offset:54272
	ds_read_b128 v[240:243], v202 offset:55296
	ds_read_b128 v[244:247], v202 offset:56320
	global_load_lds_dwordx4 v180, s[98:99]
	s_add_i32 m0, s28, 0x2000
	s_add_u32 s26, s26, 0x40080
	s_addc_u32 s27, s27, 0
	s_add_i32 s28, s83, s38
	global_load_lds_dwordx4 v184, s[98:99]
	s_mov_b32 m0, s28
	s_nop 0
	global_load_lds_dwordx4 v180, s[26:27]
	s_add_i32 m0, s28, 0x2000
	s_nop 0
	global_load_lds_dwordx4 v184, s[26:27]
	s_mov_b32 m0, s63
	s_nop 0
	global_load_lds_dwordx4 v178, s[100:101]
	s_mov_b32 m0, s64
	s_nop 0
	global_load_lds_dwordx4 v182, s[100:101]
	s_waitcnt vmcnt(8) lgkmcnt(0)
	s_barrier
	s_setprio 1
	v_mfma_f32_16x16x32_bf16 v[78:81], v[146:149], v[216:219], v[78:81]
	v_mfma_f32_16x16x32_bf16 v[74:77], v[154:157], v[216:219], v[74:77]
	v_mfma_f32_16x16x32_bf16 v[62:65], v[146:149], v[224:227], v[62:65]
	v_mfma_f32_16x16x32_bf16 v[58:61], v[154:157], v[224:227], v[58:61]
	v_mfma_f32_16x16x32_bf16 v[46:49], v[146:149], v[232:235], v[46:49]
	v_mfma_f32_16x16x32_bf16 v[42:45], v[154:157], v[232:235], v[42:45]
	v_mfma_f32_16x16x32_bf16 v[30:33], v[146:149], v[240:243], v[30:33]
	v_mfma_f32_16x16x32_bf16 v[26:29], v[154:157], v[240:243], v[26:29]
	v_mfma_f32_16x16x32_bf16 v[78:81], v[150:153], v[220:223], v[78:81]
	v_mfma_f32_16x16x32_bf16 v[74:77], v[158:161], v[220:223], v[74:77]
	v_mfma_f32_16x16x32_bf16 v[62:65], v[150:153], v[228:231], v[62:65]
	v_mfma_f32_16x16x32_bf16 v[58:61], v[158:161], v[228:231], v[58:61]
	v_mfma_f32_16x16x32_bf16 v[46:49], v[150:153], v[236:239], v[46:49]
	v_mfma_f32_16x16x32_bf16 v[42:45], v[158:161], v[236:239], v[42:45]
	v_mfma_f32_16x16x32_bf16 v[30:33], v[150:153], v[244:247], v[30:33]
	v_mfma_f32_16x16x32_bf16 v[26:29], v[158:161], v[244:247], v[26:29]
	v_mfma_f32_16x16x32_bf16 v[70:73], v[162:165], v[216:219], v[70:73]
	v_mfma_f32_16x16x32_bf16 v[66:69], v[170:173], v[216:219], v[66:69]
	v_mfma_f32_16x16x32_bf16 v[54:57], v[162:165], v[224:227], v[54:57]
	v_mfma_f32_16x16x32_bf16 v[50:53], v[170:173], v[224:227], v[50:53]
	v_mfma_f32_16x16x32_bf16 v[38:41], v[162:165], v[232:235], v[38:41]
	v_mfma_f32_16x16x32_bf16 v[34:37], v[170:173], v[232:235], v[34:37]
	v_mfma_f32_16x16x32_bf16 v[22:25], v[162:165], v[240:243], v[22:25]
	v_mfma_f32_16x16x32_bf16 v[18:21], v[170:173], v[240:243], v[18:21]
	v_mfma_f32_16x16x32_bf16 v[70:73], v[166:169], v[220:223], v[70:73]
	v_mfma_f32_16x16x32_bf16 v[66:69], v[174:177], v[220:223], v[66:69]
	v_mfma_f32_16x16x32_bf16 v[54:57], v[166:169], v[228:231], v[54:57]
	v_mfma_f32_16x16x32_bf16 v[50:53], v[174:177], v[228:231], v[50:53]
	v_mfma_f32_16x16x32_bf16 v[38:41], v[166:169], v[236:239], v[38:41]
	v_mfma_f32_16x16x32_bf16 v[34:37], v[174:177], v[236:239], v[34:37]
	v_mfma_f32_16x16x32_bf16 v[22:25], v[166:169], v[244:247], v[22:25]
	v_mfma_f32_16x16x32_bf16 v[18:21], v[174:177], v[244:247], v[18:21]
	s_setprio 0
	s_barrier
	s_add_i32 s52, s52, 2
	s_add_u32 s24, s24, 0x100
	s_addc_u32 s25, s25, 0
	s_add_u32 s44, s44, 0x100
	s_addc_u32 s45, s45, 0
	s_cmp_gt_u32 s52, 13
	s_cbranch_scc0 .LBB0_319
	s_and_b64 vcc, exec, s[10:11]
	s_cbranch_vccz .LBB0_322
	s_barrier

; #define PG8_STAGE(bufoff, gbase, voff) do { _Pragma("unroll") for (int _i = 0; _i < 2; ++_i) \
;         __builtin_amdgcn_global_load_lds((const unsigned*)((const char*)(gbase) + (voff)[_i]), (PG8_LAS unsigned*)(lds + (bufoff) + ldsw + _i * 8192), 16, 0, 0); } while (0)
; #define PG8_LDA(dst, b, h) do { _Pragma("unroll") for (int m = 0; m < 4; ++m) _Pragma("unroll") for (int k = 0; k < 2; ++k) dst[m][k] = *(const PG8_LAS bf16x8*)(lds + PG8_SA(b, h) + aoff + m * 2048 + k * 1024); } while (0)
; #define PG8_LDB(dst, b, h) do { _Pragma("unroll") for (int n = 0; n < 2; ++n) _Pragma("unroll") for (int k = 0; k < 2; ++k) dst[n][k] = *(const PG8_LAS bf16x8*)(lds + PG8_SB(b, h) + boff + n * 2048 + k * 1024); } while (0)
; #define PG8_MMA(ai, bj, At, Bt) do { __builtin_amdgcn_s_setprio(1); _Pragma("unroll") for (int m = 0; m < 4; ++m) _Pragma("unroll") for (int n = 0; n < 2; ++n) _Pragma("unroll") for (int k = 0; k < 2; ++k) \
;         acc[ai][bj][m][n] = __builtin_amdgcn_mfma_f32_16x16x32_bf16(Bt[n][k], At[m][k], acc[ai][bj][m][n], 0, 0, 0); __builtin_amdgcn_s_setprio(0); } while (0)
; #define PG8_WAIT_V(n) asm volatile("s_waitcnt vmcnt(" #n ")" ::: "memory")
; template <class Epi, class Sched, bool ALIGN_EPI = false, bool SP2 = false>
; __device__ __forceinline__ void gemm_phase(PG8_LAS unsigned char* lds, const Gemm g, const Sched& S, const Epi& E) {
;     ...
;             PG8_LDB(B0, 0, 0); PG8_LDB(B1, 0, 1); PG8_SCHED; PG8_LDA(At, 0, 0); PG8_STAGE(PG8_SA(1, 1), a1 + hstep, voffA);
;             PG8_WAIT_V(8); PG8_WAIT_L(0); PG8_BAR; PG8_MMA(0, 0, At, B0); PG8_MMA(0, 1, At, B1); PG8_BAR; PG8_SCHED;
;             PG8_LDA(At, 0, 1); PG8_STAGE(PG8_SB(0, 0), b2, voffB); PG8_STAGE(PG8_SB(0, 1), b2 + hstep, voffB); PG8_STAGE(PG8_SA(0, 0), a2, voffA);
;             PG8_WAIT_V(8); PG8_WAIT_L(0); PG8_BAR; PG8_MMA(1, 0, At, B0); PG8_MMA(1, 1, At, B1); PG8_BAR; PG8_SCHED;
;             PG8_LDB(B0, 1, 0); PG8_LDB(B1, 1, 1); PG8_SCHED; PG8_LDA(At, 1, 0); PG8_STAGE(PG8_SA(0, 1), a2 + hstep, voffA);
;             PG8_WAIT_V(8); PG8_WAIT_L(0); PG8_BAR; PG8_MMA(0, 0, At, B0); PG8_MMA(0, 1, At, B1); PG8_BAR; PG8_SCHED;
;             PG8_LDA(At, 1, 1); PG8_STAGE(PG8_SB(1, 0), b3, voffB); PG8_STAGE(PG8_SB(1, 1), b3 + hstep, voffB); PG8_STAGE(PG8_SA(1, 0), a3, voffA);
;             PG8_WAIT_V(8); PG8_WAIT_L(0); PG8_BAR; PG8_MMA(1, 0, At, B0); PG8_MMA(1, 1, At, B1); PG8_BAR; PG8_SCHED;
.LBB0_648:
	v_add_u32_e32 v1, s90, v216
	ds_read_b128 v[156:159], v1
	ds_read_b128 v[160:163], v1 offset:1024
	ds_read_b128 v[164:167], v1 offset:2048
	ds_read_b128 v[168:171], v1 offset:3072
	v_add_u32_e32 v1, s81, v216
	ds_read_b128 v[172:175], v1
	ds_read_b128 v[190:193], v1 offset:1024
	ds_read_b128 v[194:197], v1 offset:2048
	ds_read_b128 v[198:201], v1 offset:3072
	s_add_i32 s53, s53, 2
	s_add_u32 s34, s30, s42
	s_addc_u32 s35, s31, 0
	s_add_u32 s74, s28, s42
	s_addc_u32 s75, s29, 0
	s_cmp_eq_u32 s42, s24
	s_cselect_b32 s37, s77, s35
	s_cselect_b32 s36, s52, s34
	s_cselect_b32 s35, s13, s75
	s_cselect_b32 s34, s12, s74
	v_lshl_add_u64 v[202:203], v[152:153], 0, s[42:43]
	s_add_i32 m0, s61, 0xc000
	ds_read_b128 v[218:221], v217
	ds_read_b128 v[222:225], v217 offset:1024
	ds_read_b128 v[226:229], v217 offset:2048
	ds_read_b128 v[230:233], v217 offset:3072
	ds_read_b128 v[234:237], v217 offset:4096
	ds_read_b128 v[238:241], v217 offset:5120
	ds_read_b128 v[242:245], v217 offset:6144
	ds_read_b128 v[246:249], v217 offset:7168
	global_load_lds_dwordx4 v[202:203], off
	v_lshl_add_u64 v[202:203], v[2:3], 0, s[42:43]
	s_add_i32 m0, s61, 0xe000
	s_nop 0
	global_load_lds_dwordx4 v[202:203], off
	s_waitcnt vmcnt(8) lgkmcnt(0)
	s_barrier
	s_setprio 1
	v_mfma_f32_16x16x32_bf16 v[144:147], v[156:159], v[218:221], v[144:147]
	v_mfma_f32_16x16x32_bf16 v[140:143], v[164:167], v[218:221], v[140:143]
	v_mfma_f32_16x16x32_bf16 v[128:131], v[156:159], v[226:229], v[128:131]
	v_mfma_f32_16x16x32_bf16 v[124:127], v[164:167], v[226:229], v[124:127]
	v_mfma_f32_16x16x32_bf16 v[112:115], v[156:159], v[234:237], v[112:115]
	v_mfma_f32_16x16x32_bf16 v[108:111], v[164:167], v[234:237], v[108:111]
	v_mfma_f32_16x16x32_bf16 v[96:99], v[156:159], v[242:245], v[96:99]
	v_mfma_f32_16x16x32_bf16 v[92:95], v[164:167], v[242:245], v[92:95]
	v_mfma_f32_16x16x32_bf16 v[144:147], v[160:163], v[222:225], v[144:147]
	v_mfma_f32_16x16x32_bf16 v[140:143], v[168:171], v[222:225], v[140:143]
	v_mfma_f32_16x16x32_bf16 v[128:131], v[160:163], v[230:233], v[128:131]
	v_mfma_f32_16x16x32_bf16 v[124:127], v[168:171], v[230:233], v[124:127]
	v_mfma_f32_16x16x32_bf16 v[112:115], v[160:163], v[238:241], v[112:115]
	v_mfma_f32_16x16x32_bf16 v[108:111], v[168:171], v[238:241], v[108:111]
	v_mfma_f32_16x16x32_bf16 v[96:99], v[160:163], v[246:249], v[96:99]
	v_mfma_f32_16x16x32_bf16 v[92:95], v[168:171], v[246:249], v[92:95]
	v_mfma_f32_16x16x32_bf16 v[136:139], v[172:175], v[218:221], v[136:139]
	v_mfma_f32_16x16x32_bf16 v[132:135], v[194:197], v[218:221], v[132:135]
	v_mfma_f32_16x16x32_bf16 v[120:123], v[172:175], v[226:229], v[120:123]
	v_mfma_f32_16x16x32_bf16 v[116:119], v[194:197], v[226:229], v[116:119]
	v_mfma_f32_16x16x32_bf16 v[104:107], v[172:175], v[234:237], v[104:107]
	v_mfma_f32_16x16x32_bf16 v[100:103], v[194:197], v[234:237], v[100:103]
	v_mfma_f32_16x16x32_bf16 v[88:91], v[172:175], v[242:245], v[88:91]
	v_mfma_f32_16x16x32_bf16 v[84:87], v[194:197], v[242:245], v[84:87]
	v_mfma_f32_16x16x32_bf16 v[136:139], v[190:193], v[222:225], v[136:139]
	v_mfma_f32_16x16x32_bf16 v[132:135], v[198:201], v[222:225], v[132:135]
	v_mfma_f32_16x16x32_bf16 v[120:123], v[190:193], v[230:233], v[120:123]
	v_mfma_f32_16x16x32_bf16 v[116:119], v[198:201], v[230:233], v[116:119]
	v_mfma_f32_16x16x32_bf16 v[104:107], v[190:193], v[238:241], v[104:107]
	v_mfma_f32_16x16x32_bf16 v[100:103], v[198:201], v[238:241], v[100:103]
	v_mfma_f32_16x16x32_bf16 v[88:91], v[190:193], v[246:249], v[88:91]
	v_mfma_f32_16x16x32_bf16 v[84:87], v[198:201], v[246:249], v[84:87]
	s_setprio 0
	s_barrier
	s_add_i32 s74, s90, s60
	v_lshl_add_u64 v[202:203], s[34:35], 0, v[178:179]
	s_mov_b32 m0, s74
	ds_read_b128 v[218:221], v217 offset:16384
	ds_read_b128 v[222:225], v217 offset:17408
	ds_read_b128 v[226:229], v217 offset:18432
	ds_read_b128 v[230:233], v217 offset:19456
	ds_read_b128 v[234:237], v217 offset:20480
	ds_read_b128 v[238:241], v217 offset:21504
	ds_read_b128 v[242:245], v217 offset:22528
	ds_read_b128 v[246:249], v217 offset:23552
	global_load_lds_dwordx4 v[202:203], off
	s_add_i32 m0, s74, 0x2000
	s_add_u32 s74, s34, 0x40000
	v_lshl_add_u64 v[208:209], s[34:35], 0, v[182:183]
	s_addc_u32 s75, s35, 0
	s_add_i32 vcc_hi, s81, s60
	global_load_lds_dwordx4 v[208:209], off
	v_lshl_add_u64 v[250:251], s[74:75], 0, v[178:179]
	s_mov_b32 m0, vcc_hi
	v_lshl_add_u64 v[252:253], s[36:37], 0, v[180:181]
	global_load_lds_dwordx4 v[250:251], off
	v_lshl_add_u64 v[250:251], s[74:75], 0, v[182:183]
	s_add_i32 m0, vcc_hi, 0x2000
	s_nop 0
	global_load_lds_dwordx4 v[250:251], off
	v_lshl_add_u64 v[250:251], s[36:37], 0, v[176:177]
	s_mov_b32 m0, s61
	s_nop 0
	global_load_lds_dwordx4 v[250:251], off
	s_mov_b32 m0, s62
	s_nop 0
	global_load_lds_dwordx4 v[252:253], off
	s_waitcnt vmcnt(8) lgkmcnt(0)
	s_barrier
; #define PG8_STAGE(bufoff, gbase, voff) do { _Pragma("unroll") for (int _i = 0; _i < 2; ++_i) \
;         __builtin_amdgcn_global_load_lds((const unsigned*)((const char*)(gbase) + (voff)[_i]), (PG8_LAS unsigned*)(lds + (bufoff) + ldsw + _i * 8192), 16, 0, 0); } while (0)
; #define PG8_LDA(dst, b, h) do { _Pragma("unroll") for (int m = 0; m < 4; ++m) _Pragma("unroll") for (int k = 0; k < 2; ++k) dst[m][k] = *(const PG8_LAS bf16x8*)(lds + PG8_SA(b, h) + aoff + m * 2048 + k * 1024); } while (0)
; #define PG8_LDB(dst, b, h) do { _Pragma("unroll") for (int n = 0; n < 2; ++n) _Pragma("unroll") for (int k = 0; k < 2; ++k) dst[n][k] = *(const PG8_LAS bf16x8*)(lds + PG8_SB(b, h) + boff + n * 2048 + k * 1024); } while (0)
; #define PG8_MMA(ai, bj, At, Bt) do { __builtin_amdgcn_s_setprio(1); _Pragma("unroll") for (int m = 0; m < 4; ++m) _Pragma("unroll") for (int n = 0; n < 2; ++n) _Pragma("unroll") for (int k = 0; k < 2; ++k) \
;         acc[ai][bj][m][n] = __builtin_amdgcn_mfma_f32_16x16x32_bf16(Bt[n][k], At[m][k], acc[ai][bj][m][n], 0, 0, 0); __builtin_amdgcn_s_setprio(0); } while (0)
; #define PG8_WAIT_V(n) asm volatile("s_waitcnt vmcnt(" #n ")" ::: "memory")
; template <class Epi, class Sched, bool ALIGN_EPI = false, bool SP2 = false>
; __device__ __forceinline__ void gemm_phase(PG8_LAS unsigned char* lds, const Gemm g, const Sched& S, const Epi& E) {
;     ...
;             PG8_LDB(B0, 0, 0); PG8_LDB(B1, 0, 1); PG8_SCHED; PG8_LDA(At, 0, 0); PG8_STAGE(PG8_SA(1, 1), a1 + hstep, voffA);
;             PG8_WAIT_V(8); PG8_WAIT_L(0); PG8_BAR; PG8_MMA(0, 0, At, B0); PG8_MMA(0, 1, At, B1); PG8_BAR; PG8_SCHED;
;             PG8_LDA(At, 0, 1); PG8_STAGE(PG8_SB(0, 0), b2, voffB); PG8_STAGE(PG8_SB(0, 1), b2 + hstep, voffB); PG8_STAGE(PG8_SA(0, 0), a2, voffA);
;             PG8_WAIT_V(8); PG8_WAIT_L(0); PG8_BAR; PG8_MMA(1, 0, At, B0); PG8_MMA(1, 1, At, B1); PG8_BAR; PG8_SCHED;
;             PG8_LDB(B0, 1, 0); PG8_LDB(B1, 1, 1); PG8_SCHED; PG8_LDA(At, 1, 0); PG8_STAGE(PG8_SA(0, 1), a2 + hstep, voffA);
;             PG8_WAIT_V(8); PG8_WAIT_L(0); PG8_BAR; PG8_MMA(0, 0, At, B0); PG8_MMA(0, 1, At, B1); PG8_BAR; PG8_SCHED;
;             PG8_LDA(At, 1, 1); PG8_STAGE(PG8_SB(1, 0), b3, voffB); PG8_STAGE(PG8_SB(1, 1), b3 + hstep, voffB); PG8_STAGE(PG8_SA(1, 0), a3, voffA);
;             PG8_WAIT_V(8); PG8_WAIT_L(0); PG8_BAR; PG8_MMA(1, 0, At, B0); PG8_MMA(1, 1, At, B1); PG8_BAR; PG8_SCHED;
	s_setprio 1
	v_mfma_f32_16x16x32_bf16 v[80:83], v[156:159], v[218:221], v[80:83]
	v_mfma_f32_16x16x32_bf16 v[76:79], v[164:167], v[218:221], v[76:79]
	v_mfma_f32_16x16x32_bf16 v[64:67], v[156:159], v[226:229], v[64:67]
	v_mfma_f32_16x16x32_bf16 v[60:63], v[164:167], v[226:229], v[60:63]
	v_mfma_f32_16x16x32_bf16 v[48:51], v[156:159], v[234:237], v[48:51]
	v_mfma_f32_16x16x32_bf16 v[44:47], v[164:167], v[234:237], v[44:47]
	v_mfma_f32_16x16x32_bf16 v[32:35], v[156:159], v[242:245], v[32:35]
	v_mfma_f32_16x16x32_bf16 v[28:31], v[164:167], v[242:245], v[28:31]
	v_mfma_f32_16x16x32_bf16 v[80:83], v[160:163], v[222:225], v[80:83]
	v_mfma_f32_16x16x32_bf16 v[76:79], v[168:171], v[222:225], v[76:79]
	v_mfma_f32_16x16x32_bf16 v[64:67], v[160:163], v[230:233], v[64:67]
	v_mfma_f32_16x16x32_bf16 v[60:63], v[168:171], v[230:233], v[60:63]
	v_mfma_f32_16x16x32_bf16 v[48:51], v[160:163], v[238:241], v[48:51]
	v_mfma_f32_16x16x32_bf16 v[44:47], v[168:171], v[238:241], v[44:47]
	v_mfma_f32_16x16x32_bf16 v[32:35], v[160:163], v[246:249], v[32:35]
	v_mfma_f32_16x16x32_bf16 v[28:31], v[168:171], v[246:249], v[28:31]
	v_mfma_f32_16x16x32_bf16 v[72:75], v[172:175], v[218:221], v[72:75]
	v_mfma_f32_16x16x32_bf16 v[68:71], v[194:197], v[218:221], v[68:71]
	v_mfma_f32_16x16x32_bf16 v[56:59], v[172:175], v[226:229], v[56:59]
	v_mfma_f32_16x16x32_bf16 v[52:55], v[194:197], v[226:229], v[52:55]
	v_mfma_f32_16x16x32_bf16 v[40:43], v[172:175], v[234:237], v[40:43]
	v_mfma_f32_16x16x32_bf16 v[36:39], v[194:197], v[234:237], v[36:39]
	v_mfma_f32_16x16x32_bf16 v[24:27], v[172:175], v[242:245], v[24:27]
	v_mfma_f32_16x16x32_bf16 v[20:23], v[194:197], v[242:245], v[20:23]
	v_mfma_f32_16x16x32_bf16 v[72:75], v[190:193], v[222:225], v[72:75]
	v_mfma_f32_16x16x32_bf16 v[68:71], v[198:201], v[222:225], v[68:71]
	v_mfma_f32_16x16x32_bf16 v[56:59], v[190:193], v[230:233], v[56:59]
	v_mfma_f32_16x16x32_bf16 v[52:55], v[198:201], v[230:233], v[52:55]
	v_mfma_f32_16x16x32_bf16 v[40:43], v[190:193], v[238:241], v[40:43]
	v_mfma_f32_16x16x32_bf16 v[36:39], v[198:201], v[238:241], v[36:39]
	v_mfma_f32_16x16x32_bf16 v[24:27], v[190:193], v[246:249], v[24:27]
	v_mfma_f32_16x16x32_bf16 v[20:23], v[198:201], v[246:249], v[20:23]
	s_setprio 0
	s_barrier
	v_add_u32_e32 v1, s82, v216
	ds_read_b128 v[156:159], v1
	ds_read_b128 v[160:163], v1 offset:1024
	ds_read_b128 v[164:167], v1 offset:2048
	ds_read_b128 v[168:171], v1 offset:3072
	v_add_u32_e32 v1, s83, v216
	ds_read_b128 v[172:175], v1
	ds_read_b128 v[190:193], v1 offset:1024
	ds_read_b128 v[194:197], v1 offset:2048
	ds_read_b128 v[198:201], v1 offset:3072
	s_add_u32 s36, s36, 0x40000
	s_addc_u32 s37, s37, 0
	s_mov_b32 m0, s63
	v_lshl_add_u64 v[210:211], s[36:37], 0, v[176:177]
	ds_read_b128 v[218:221], v217 offset:32768
	ds_read_b128 v[222:225], v217 offset:33792
	ds_read_b128 v[226:229], v217 offset:34816
	ds_read_b128 v[230:233], v217 offset:35840
	ds_read_b128 v[234:237], v217 offset:36864
	ds_read_b128 v[238:241], v217 offset:37888
	ds_read_b128 v[242:245], v217 offset:38912
	ds_read_b128 v[246:249], v217 offset:39936
	global_load_lds_dwordx4 v[210:211], off
	v_lshl_add_u64 v[210:211], s[36:37], 0, v[180:181]
	s_mov_b32 m0, s64
	s_nop 0
	global_load_lds_dwordx4 v[210:211], off
	s_waitcnt vmcnt(8) lgkmcnt(0)
	s_barrier
	s_setprio 1
	v_mfma_f32_16x16x32_bf16 v[144:147], v[156:159], v[218:221], v[144:147]
	v_mfma_f32_16x16x32_bf16 v[140:143], v[164:167], v[218:221], v[140:143]
	v_mfma_f32_16x16x32_bf16 v[128:131], v[156:159], v[226:229], v[128:131]
	v_mfma_f32_16x16x32_bf16 v[124:127], v[164:167], v[226:229], v[124:127]
	v_mfma_f32_16x16x32_bf16 v[112:115], v[156:159], v[234:237], v[112:115]
	v_mfma_f32_16x16x32_bf16 v[108:111], v[164:167], v[234:237], v[108:111]
	v_mfma_f32_16x16x32_bf16 v[96:99], v[156:159], v[242:245], v[96:99]
	v_mfma_f32_16x16x32_bf16 v[92:95], v[164:167], v[242:245], v[92:95]
	v_mfma_f32_16x16x32_bf16 v[144:147], v[160:163], v[222:225], v[144:147]
	v_mfma_f32_16x16x32_bf16 v[140:143], v[168:171], v[222:225], v[140:143]
	v_mfma_f32_16x16x32_bf16 v[128:131], v[160:163], v[230:233], v[128:131]
	v_mfma_f32_16x16x32_bf16 v[124:127], v[168:171], v[230:233], v[124:127]
	v_mfma_f32_16x16x32_bf16 v[112:115], v[160:163], v[238:241], v[112:115]
	v_mfma_f32_16x16x32_bf16 v[108:111], v[168:171], v[238:241], v[108:111]
	v_mfma_f32_16x16x32_bf16 v[96:99], v[160:163], v[246:249], v[96:99]
	v_mfma_f32_16x16x32_bf16 v[92:95], v[168:171], v[246:249], v[92:95]
	v_mfma_f32_16x16x32_bf16 v[136:139], v[172:175], v[218:221], v[136:139]
	v_mfma_f32_16x16x32_bf16 v[132:135], v[194:197], v[218:221], v[132:135]
	v_mfma_f32_16x16x32_bf16 v[120:123], v[172:175], v[226:229], v[120:123]
	v_mfma_f32_16x16x32_bf16 v[116:119], v[194:197], v[226:229], v[116:119]
	v_mfma_f32_16x16x32_bf16 v[104:107], v[172:175], v[234:237], v[104:107]
	v_mfma_f32_16x16x32_bf16 v[100:103], v[194:197], v[234:237], v[100:103]
	v_mfma_f32_16x16x32_bf16 v[88:91], v[172:175], v[242:245], v[88:91]
	v_mfma_f32_16x16x32_bf16 v[84:87], v[194:197], v[242:245], v[84:87]
	v_mfma_f32_16x16x32_bf16 v[136:139], v[190:193], v[222:225], v[136:139]
	v_mfma_f32_16x16x32_bf16 v[132:135], v[198:201], v[222:225], v[132:135]
	v_mfma_f32_16x16x32_bf16 v[120:123], v[190:193], v[230:233], v[120:123]
	v_mfma_f32_16x16x32_bf16 v[116:119], v[198:201], v[230:233], v[116:119]
	v_mfma_f32_16x16x32_bf16 v[104:107], v[190:193], v[238:241], v[104:107]
	v_mfma_f32_16x16x32_bf16 v[100:103], v[198:201], v[238:241], v[100:103]
	v_mfma_f32_16x16x32_bf16 v[88:91], v[190:193], v[246:249], v[88:91]
	v_mfma_f32_16x16x32_bf16 v[84:87], v[198:201], v[246:249], v[84:87]
	s_setprio 0
	s_barrier
; #define PG8_STAGE(bufoff, gbase, voff) do { _Pragma("unroll") for (int _i = 0; _i < 2; ++_i) \
;         __builtin_amdgcn_global_load_lds((const unsigned*)((const char*)(gbase) + (voff)[_i]), (PG8_LAS unsigned*)(lds + (bufoff) + ldsw + _i * 8192), 16, 0, 0); } while (0)
; #define PG8_LDA(dst, b, h) do { _Pragma("unroll") for (int m = 0; m < 4; ++m) _Pragma("unroll") for (int k = 0; k < 2; ++k) dst[m][k] = *(const PG8_LAS bf16x8*)(lds + PG8_SA(b, h) + aoff + m * 2048 + k * 1024); } while (0)
; #define PG8_LDB(dst, b, h) do { _Pragma("unroll") for (int n = 0; n < 2; ++n) _Pragma("unroll") for (int k = 0; k < 2; ++k) dst[n][k] = *(const PG8_LAS bf16x8*)(lds + PG8_SB(b, h) + boff + n * 2048 + k * 1024); } while (0)
; #define PG8_MMA(ai, bj, At, Bt) do { __builtin_amdgcn_s_setprio(1); _Pragma("unroll") for (int m = 0; m < 4; ++m) _Pragma("unroll") for (int n = 0; n < 2; ++n) _Pragma("unroll") for (int k = 0; k < 2; ++k) \
;         acc[ai][bj][m][n] = __builtin_amdgcn_mfma_f32_16x16x32_bf16(Bt[n][k], At[m][k], acc[ai][bj][m][n], 0, 0, 0); __builtin_amdgcn_s_setprio(0); } while (0)
; #define PG8_WAIT_V(n) asm volatile("s_waitcnt vmcnt(" #n ")" ::: "memory")
; template <class Epi, class Sched, bool ALIGN_EPI = false, bool SP2 = false>
; __device__ __forceinline__ void gemm_phase(PG8_LAS unsigned char* lds, const Gemm g, const Sched& S, const Epi& E) {
;     ...
;             PG8_LDB(B0, 0, 0); PG8_LDB(B1, 0, 1); PG8_SCHED; PG8_LDA(At, 0, 0); PG8_STAGE(PG8_SA(1, 1), a1 + hstep, voffA);
;             PG8_WAIT_V(8); PG8_WAIT_L(0); PG8_BAR; PG8_MMA(0, 0, At, B0); PG8_MMA(0, 1, At, B1); PG8_BAR; PG8_SCHED;
;             PG8_LDA(At, 0, 1); PG8_STAGE(PG8_SB(0, 0), b2, voffB); PG8_STAGE(PG8_SB(0, 1), b2 + hstep, voffB); PG8_STAGE(PG8_SA(0, 0), a2, voffA);
;             PG8_WAIT_V(8); PG8_WAIT_L(0); PG8_BAR; PG8_MMA(1, 0, At, B0); PG8_MMA(1, 1, At, B1); PG8_BAR; PG8_SCHED;
;             PG8_LDB(B0, 1, 0); PG8_LDB(B1, 1, 1); PG8_SCHED; PG8_LDA(At, 1, 0); PG8_STAGE(PG8_SA(0, 1), a2 + hstep, voffA);
;             PG8_WAIT_V(8); PG8_WAIT_L(0); PG8_BAR; PG8_MMA(0, 0, At, B0); PG8_MMA(0, 1, At, B1); PG8_BAR; PG8_SCHED;
;             PG8_LDA(At, 1, 1); PG8_STAGE(PG8_SB(1, 0), b3, voffB); PG8_STAGE(PG8_SB(1, 1), b3 + hstep, voffB); PG8_STAGE(PG8_SA(1, 0), a3, voffA);
;             PG8_WAIT_V(8); PG8_WAIT_L(0); PG8_BAR; PG8_MMA(1, 0, At, B0); PG8_MMA(1, 1, At, B1); PG8_BAR; PG8_SCHED;
	s_add_i32 s36, s82, s60
	v_lshl_add_u64 v[202:203], v[202:203], 0, s[46:47]
	s_mov_b32 m0, s36
	ds_read_b128 v[218:221], v217 offset:49152
	ds_read_b128 v[222:225], v217 offset:50176
	ds_read_b128 v[226:229], v217 offset:51200
	ds_read_b128 v[230:233], v217 offset:52224
	ds_read_b128 v[234:237], v217 offset:53248
	ds_read_b128 v[238:241], v217 offset:54272
	ds_read_b128 v[242:245], v217 offset:55296
	ds_read_b128 v[246:249], v217 offset:56320
	global_load_lds_dwordx4 v[202:203], off
	s_add_i32 m0, s36, 0x2000
	s_add_u32 s34, s34, 0x40080
	v_lshl_add_u64 v[202:203], v[208:209], 0, s[46:47]
	s_addc_u32 s35, s35, 0
	s_add_i32 s36, s83, s60
	global_load_lds_dwordx4 v[202:203], off
	v_lshl_add_u64 v[202:203], s[34:35], 0, v[178:179]
	s_mov_b32 m0, s36
	s_nop 0
	global_load_lds_dwordx4 v[202:203], off
	v_lshl_add_u64 v[202:203], s[34:35], 0, v[182:183]
	s_add_i32 m0, s36, 0x2000
	s_nop 0
	global_load_lds_dwordx4 v[202:203], off
	v_lshl_add_u64 v[202:203], v[250:251], 0, s[46:47]
	s_mov_b32 m0, s66
	s_nop 0
	global_load_lds_dwordx4 v[202:203], off
	v_lshl_add_u64 v[202:203], v[252:253], 0, s[46:47]
	s_mov_b32 m0, s67
	s_nop 0
	global_load_lds_dwordx4 v[202:203], off
	s_waitcnt vmcnt(8) lgkmcnt(0)
	s_barrier
	s_setprio 1
	v_mfma_f32_16x16x32_bf16 v[80:83], v[156:159], v[218:221], v[80:83]
	v_mfma_f32_16x16x32_bf16 v[76:79], v[164:167], v[218:221], v[76:79]
	v_mfma_f32_16x16x32_bf16 v[64:67], v[156:159], v[226:229], v[64:67]
	v_mfma_f32_16x16x32_bf16 v[60:63], v[164:167], v[226:229], v[60:63]
	v_mfma_f32_16x16x32_bf16 v[48:51], v[156:159], v[234:237], v[48:51]
	v_mfma_f32_16x16x32_bf16 v[44:47], v[164:167], v[234:237], v[44:47]
	v_mfma_f32_16x16x32_bf16 v[32:35], v[156:159], v[242:245], v[32:35]
	v_mfma_f32_16x16x32_bf16 v[28:31], v[164:167], v[242:245], v[28:31]
	v_mfma_f32_16x16x32_bf16 v[80:83], v[160:163], v[222:225], v[80:83]
	v_mfma_f32_16x16x32_bf16 v[76:79], v[168:171], v[222:225], v[76:79]
	v_mfma_f32_16x16x32_bf16 v[64:67], v[160:163], v[230:233], v[64:67]
	v_mfma_f32_16x16x32_bf16 v[60:63], v[168:171], v[230:233], v[60:63]
	v_mfma_f32_16x16x32_bf16 v[48:51], v[160:163], v[238:241], v[48:51]
	v_mfma_f32_16x16x32_bf16 v[44:47], v[168:171], v[238:241], v[44:47]
	v_mfma_f32_16x16x32_bf16 v[32:35], v[160:163], v[246:249], v[32:35]
	v_mfma_f32_16x16x32_bf16 v[28:31], v[168:171], v[246:249], v[28:31]
	v_mfma_f32_16x16x32_bf16 v[72:75], v[172:175], v[218:221], v[72:75]
	v_mfma_f32_16x16x32_bf16 v[68:71], v[194:197], v[218:221], v[68:71]
	v_mfma_f32_16x16x32_bf16 v[56:59], v[172:175], v[226:229], v[56:59]
	v_mfma_f32_16x16x32_bf16 v[52:55], v[194:197], v[226:229], v[52:55]
	v_mfma_f32_16x16x32_bf16 v[40:43], v[172:175], v[234:237], v[40:43]
	v_mfma_f32_16x16x32_bf16 v[36:39], v[194:197], v[234:237], v[36:39]
	v_mfma_f32_16x16x32_bf16 v[24:27], v[172:175], v[242:245], v[24:27]
	v_mfma_f32_16x16x32_bf16 v[20:23], v[194:197], v[242:245], v[20:23]
	v_mfma_f32_16x16x32_bf16 v[72:75], v[190:193], v[222:225], v[72:75]
	v_mfma_f32_16x16x32_bf16 v[68:71], v[198:201], v[222:225], v[68:71]
	v_mfma_f32_16x16x32_bf16 v[56:59], v[190:193], v[230:233], v[56:59]
	v_mfma_f32_16x16x32_bf16 v[52:55], v[198:201], v[230:233], v[52:55]
	v_mfma_f32_16x16x32_bf16 v[40:43], v[190:193], v[238:241], v[40:43]
	v_mfma_f32_16x16x32_bf16 v[36:39], v[198:201], v[238:241], v[36:39]
	v_mfma_f32_16x16x32_bf16 v[24:27], v[190:193], v[246:249], v[24:27]
	v_mfma_f32_16x16x32_bf16 v[20:23], v[198:201], v[246:249], v[20:23]
	s_setprio 0
	s_barrier
	s_add_u32 s30, s30, 0x100
	s_addc_u32 s31, s31, 0
	s_add_u32 s28, s28, 0x100
	s_addc_u32 s29, s29, 0
	s_add_u32 s24, s24, 0xffffff00
	s_addc_u32 s25, s25, -1
	v_lshl_add_u64 v[152:153], v[152:153], 0, s[48:49]
	s_cmp_ge_u32 s53, vcc_lo
	v_lshl_add_u64 v[2:3], v[2:3], 0, s[48:49]
	s_cbranch_scc0 .LBB0_648
	s_mov_b64 s[28:29], -1
	s_mov_b64 s[24:25], 0
	s_and_b64 vcc, exec, s[26:27]
	s_cbranch_vccz .LBB0_645
	s_and_b64 vcc, exec, s[18:19]
	s_cbranch_vccz .LBB0_652
	s_barrier

; #define PG8_WAIT_V(n) asm volatile("s_waitcnt vmcnt(" #n ")" ::: "memory")
; #define PG8_WAIT_L(n) asm volatile("s_waitcnt lgkmcnt(" #n ")" ::: "memory")
; template <class Epi, class Sched, bool ALIGN_EPI = false, bool SP2 = false>
; __device__ __forceinline__ void gemm_phase(PG8_LAS unsigned char* lds, const Gemm g, const Sched& S, const Epi& E) {
;     ...
;         const bool has_next = S.next(ui + 1, nxt);
;         const char* nA = has_next ? (const char*)g.A + (size_t)nxt.pm * tstep : cA; const char* nB = has_next ? (const char*)g.Bt + (size_t)nxt.pn * tstep : cB;
;         constexpr int NSEG = (Epi::MID_T >= 0) ? 2 : 1;
; #pragma unroll 1
;         for (int seg = 0; seg < NSEG; ++seg) {
;         const int t_lo = (seg == 0) ? 0 : Epi::MID_T, t_hi = (NSEG == 2 && seg == 0) ? Epi::MID_T : nt;
;         if constexpr (Epi::MID_T >= 0) { if (seg == 1) E.mid(acc, ui, wr, fr); }
;         for (int t = t_lo; t < t_hi; t += 2) {
;             const bool last = (t == nt - 2);
;             const char* a1 = cA + (size_t)(t + 1) * kstep;
;             const char* a2 = last ? nA : cA + (size_t)(t + 2) * kstep; const char* b2 = last ? nB : cB + (size_t)(t + 2) * kstep;
;             const char* a3 = a2 + kstep; const char* b3 = b2 + kstep;
;             if (last && has_next) S.a_ready_inloop(nxt, ui + 1);
;             if constexpr (SP2) {
;             PG8_LDB(B0, 0, 0); PG8_LDB(B1, 0, 1); PG8_SCHED; PG8_LDA(At, 0, 0); PG8_STAGE(PG8_SA(1, 1), a1 + hstep, voffA);
;             PG8_WAIT_V(8); PG8_WAIT_L(0); PG8_BAR; PG8_MMA(0, 0, At, B0); PG8_MMA(0, 1, At, B1); PG8_BAR; PG8_SCHED;
;             PG8_LDA(At, 0, 1); PG8_STAGE(PG8_SB(0, 0), b2, voffB); PG8_STAGE(PG8_SB(0, 1), b2 + hstep, voffB); PG8_STAGE(PG8_SA(0, 0), a2, voffA);
;             PG8_WAIT_V(8); PG8_WAIT_L(0); PG8_BAR; PG8_MMA(1, 0, At, B0); PG8_MMA(1, 1, At, B1); PG8_BAR; PG8_SCHED;
;             PG8_LDB(B0, 1, 0); PG8_LDB(B1, 1, 1); PG8_SCHED; PG8_LDA(At, 1, 0); PG8_STAGE(PG8_SA(0, 1), a2 + hstep, voffA);
;             PG8_WAIT_V(8); PG8_WAIT_L(0); PG8_BAR; PG8_MMA(0, 0, At, B0); PG8_MMA(0, 1, At, B1); PG8_BAR; PG8_SCHED;
;             PG8_LDA(At, 1, 1); PG8_STAGE(PG8_SB(1, 0), b3, voffB); PG8_STAGE(PG8_SB(1, 1), b3 + hstep, voffB); PG8_STAGE(PG8_SA(1, 0), a3, voffA);
;             PG8_WAIT_V(8); PG8_WAIT_L(0); PG8_BAR; PG8_MMA(1, 0, At, B0); PG8_MMA(1, 1, At, B1); PG8_BAR; PG8_SCHED;
.LBB0_761:
	s_ashr_i32 s13, s12, 31
	s_lshl_b64 s[16:17], s[12:13], 19
	s_add_u32 s16, s28, s16
	s_addc_u32 s17, s29, s17
	s_and_b64 s[18:19], s[2:3], exec
	s_cselect_b32 s13, s17, s21
	s_cselect_b32 s52, s16, s20
	s_ashr_i32 s15, s14, 31
	s_lshl_b64 s[18:19], s[14:15], 19
	s_add_u32 s18, s30, s18
	s_addc_u32 s19, s31, s19
	s_and_b64 s[24:25], s[2:3], exec
	s_cselect_b32 s15, s19, s23
	s_cselect_b32 s53, s18, s22
	s_add_u32 s20, s20, 0x40080
	s_addc_u32 s21, s21, 0
	s_add_u32 s62, s22, 0x100
	s_addc_u32 s63, s23, 0
	s_mov_b32 s64, -2
	v_add_u32_e32 v158, s90, v160
	ds_read_b128 v[164:167], v158
	ds_read_b128 v[168:171], v158 offset:1024
	ds_read_b128 v[172:175], v158 offset:2048
	ds_read_b128 v[176:179], v158 offset:3072
	v_add_u32_e32 v158, s81, v160
	ds_read_b128 v[180:183], v158
	ds_read_b128 v[184:187], v158 offset:1024
	ds_read_b128 v[188:191], v158 offset:2048
	ds_read_b128 v[192:195], v158 offset:3072
	s_add_u32 s22, s20, 0xfffc0080
	s_addc_u32 s23, s21, -1
	s_cmp_eq_u32 s64, 12
	s_cselect_b32 s25, s13, s23
	s_cselect_b32 s24, s52, s22
	s_cselect_b32 s23, s15, s63
	s_cselect_b32 s22, s53, s62
	s_add_u32 s98, s22, s46
	s_addc_u32 s99, s23, s47
	s_add_u32 s100, s24, s46
	s_addc_u32 s101, s25, s47
	s_add_i32 m0, s35, 0xc000
	ds_read_b128 v[196:199], v163
	ds_read_b128 v[200:203], v163 offset:1024
	ds_read_b128 v[216:219], v163 offset:2048
	ds_read_b128 v[220:223], v163 offset:3072
	ds_read_b128 v[224:227], v163 offset:4096
	ds_read_b128 v[228:231], v163 offset:5120
	ds_read_b128 v[232:235], v163 offset:6144
	ds_read_b128 v[236:239], v163 offset:7168
	global_load_lds_dwordx4 v154, s[20:21]
	s_add_i32 m0, s35, 0xe000
	s_nop 0
	global_load_lds_dwordx4 v156, s[20:21]
	s_waitcnt vmcnt(8) lgkmcnt(0)
	s_barrier
	s_setprio 1
	v_mfma_f32_16x16x32_bf16 v[142:145], v[164:167], v[196:199], 0
	v_mfma_f32_16x16x32_bf16 v[138:141], v[172:175], v[196:199], 0
	v_mfma_f32_16x16x32_bf16 v[126:129], v[164:167], v[216:219], 0
	v_mfma_f32_16x16x32_bf16 v[122:125], v[172:175], v[216:219], 0
	v_mfma_f32_16x16x32_bf16 v[110:113], v[164:167], v[224:227], 0
	v_mfma_f32_16x16x32_bf16 v[106:109], v[172:175], v[224:227], 0
	v_mfma_f32_16x16x32_bf16 v[94:97], v[164:167], v[232:235], 0
	v_mfma_f32_16x16x32_bf16 v[90:93], v[172:175], v[232:235], 0
	v_mfma_f32_16x16x32_bf16 v[142:145], v[168:171], v[200:203], v[142:145]
	v_mfma_f32_16x16x32_bf16 v[138:141], v[176:179], v[200:203], v[138:141]
	v_mfma_f32_16x16x32_bf16 v[126:129], v[168:171], v[220:223], v[126:129]
	v_mfma_f32_16x16x32_bf16 v[122:125], v[176:179], v[220:223], v[122:125]
	v_mfma_f32_16x16x32_bf16 v[110:113], v[168:171], v[228:231], v[110:113]
	v_mfma_f32_16x16x32_bf16 v[106:109], v[176:179], v[228:231], v[106:109]
	v_mfma_f32_16x16x32_bf16 v[94:97], v[168:171], v[236:239], v[94:97]
	v_mfma_f32_16x16x32_bf16 v[90:93], v[176:179], v[236:239], v[90:93]
	v_mfma_f32_16x16x32_bf16 v[134:137], v[180:183], v[196:199], 0
	v_mfma_f32_16x16x32_bf16 v[130:133], v[188:191], v[196:199], 0
	v_mfma_f32_16x16x32_bf16 v[118:121], v[180:183], v[216:219], 0
	v_mfma_f32_16x16x32_bf16 v[114:117], v[188:191], v[216:219], 0
	v_mfma_f32_16x16x32_bf16 v[102:105], v[180:183], v[224:227], 0
	v_mfma_f32_16x16x32_bf16 v[98:101], v[188:191], v[224:227], 0
	v_mfma_f32_16x16x32_bf16 v[86:89], v[180:183], v[232:235], 0
	v_mfma_f32_16x16x32_bf16 v[82:85], v[188:191], v[232:235], 0
	v_mfma_f32_16x16x32_bf16 v[134:137], v[184:187], v[200:203], v[134:137]
	v_mfma_f32_16x16x32_bf16 v[130:133], v[192:195], v[200:203], v[130:133]
	v_mfma_f32_16x16x32_bf16 v[118:121], v[184:187], v[220:223], v[118:121]
	v_mfma_f32_16x16x32_bf16 v[114:117], v[192:195], v[220:223], v[114:117]
	v_mfma_f32_16x16x32_bf16 v[102:105], v[184:187], v[228:231], v[102:105]
	v_mfma_f32_16x16x32_bf16 v[98:101], v[192:195], v[228:231], v[98:101]
	v_mfma_f32_16x16x32_bf16 v[86:89], v[184:187], v[236:239], v[86:89]
	v_mfma_f32_16x16x32_bf16 v[82:85], v[192:195], v[236:239], v[82:85]
	s_setprio 0
	s_barrier
	s_add_i32 s65, s90, s34
	s_mov_b32 m0, s65
	ds_read_b128 v[196:199], v163 offset:16384
	ds_read_b128 v[200:203], v163 offset:17408
	ds_read_b128 v[216:219], v163 offset:18432
	ds_read_b128 v[220:223], v163 offset:19456
	ds_read_b128 v[224:227], v163 offset:20480
	ds_read_b128 v[228:231], v163 offset:21504
	ds_read_b128 v[232:235], v163 offset:22528
	ds_read_b128 v[236:239], v163 offset:23552
	global_load_lds_dwordx4 v148, s[22:23]
	s_add_i32 m0, s65, 0x2000
	s_add_u32 s66, s22, 0x40000
	s_addc_u32 s67, s23, 0
	s_add_i32 s65, s81, s34
	global_load_lds_dwordx4 v152, s[22:23]
	s_mov_b32 m0, s65
	s_nop 0
	global_load_lds_dwordx4 v148, s[66:67]
	s_add_i32 m0, s65, 0x2000
	s_nop 0
	global_load_lds_dwordx4 v152, s[66:67]
	s_mov_b32 m0, s35
	s_nop 0
	global_load_lds_dwordx4 v146, s[24:25]
	s_mov_b32 m0, s36
	s_nop 0
	global_load_lds_dwordx4 v150, s[24:25]
	s_waitcnt vmcnt(8) lgkmcnt(0)
	s_barrier
; #define PG8_STAGE(bufoff, gbase, voff) do { _Pragma("unroll") for (int _i = 0; _i < 2; ++_i) \
;         __builtin_amdgcn_global_load_lds((const unsigned*)((const char*)(gbase) + (voff)[_i]), (PG8_LAS unsigned*)(lds + (bufoff) + ldsw + _i * 8192), 16, 0, 0); } while (0)
; #define PG8_LDA(dst, b, h) do { _Pragma("unroll") for (int m = 0; m < 4; ++m) _Pragma("unroll") for (int k = 0; k < 2; ++k) dst[m][k] = *(const PG8_LAS bf16x8*)(lds + PG8_SA(b, h) + aoff + m * 2048 + k * 1024); } while (0)
; #define PG8_LDB(dst, b, h) do { _Pragma("unroll") for (int n = 0; n < 2; ++n) _Pragma("unroll") for (int k = 0; k < 2; ++k) dst[n][k] = *(const PG8_LAS bf16x8*)(lds + PG8_SB(b, h) + boff + n * 2048 + k * 1024); } while (0)
; #define PG8_MMA(ai, bj, At, Bt) do { __builtin_amdgcn_s_setprio(1); _Pragma("unroll") for (int m = 0; m < 4; ++m) _Pragma("unroll") for (int n = 0; n < 2; ++n) _Pragma("unroll") for (int k = 0; k < 2; ++k) \
;         acc[ai][bj][m][n] = __builtin_amdgcn_mfma_f32_16x16x32_bf16(Bt[n][k], At[m][k], acc[ai][bj][m][n], 0, 0, 0); __builtin_amdgcn_s_setprio(0); } while (0)
; #define PG8_WAIT_V(n) asm volatile("s_waitcnt vmcnt(" #n ")" ::: "memory")
; template <class Epi, class Sched, bool ALIGN_EPI = false, bool SP2 = false>
; __device__ __forceinline__ void gemm_phase(PG8_LAS unsigned char* lds, const Gemm g, const Sched& S, const Epi& E) {
;     ...
;             PG8_LDB(B0, 0, 0); PG8_LDB(B1, 0, 1); PG8_SCHED; PG8_LDA(At, 0, 0); PG8_STAGE(PG8_SA(1, 1), a1 + hstep, voffA);
;             PG8_WAIT_V(8); PG8_WAIT_L(0); PG8_BAR; PG8_MMA(0, 0, At, B0); PG8_MMA(0, 1, At, B1); PG8_BAR; PG8_SCHED;
;             PG8_LDA(At, 0, 1); PG8_STAGE(PG8_SB(0, 0), b2, voffB); PG8_STAGE(PG8_SB(0, 1), b2 + hstep, voffB); PG8_STAGE(PG8_SA(0, 0), a2, voffA);
;             PG8_WAIT_V(8); PG8_WAIT_L(0); PG8_BAR; PG8_MMA(1, 0, At, B0); PG8_MMA(1, 1, At, B1); PG8_BAR; PG8_SCHED;
;             PG8_LDB(B0, 1, 0); PG8_LDB(B1, 1, 1); PG8_SCHED; PG8_LDA(At, 1, 0); PG8_STAGE(PG8_SA(0, 1), a2 + hstep, voffA);
;             PG8_WAIT_V(8); PG8_WAIT_L(0); PG8_BAR; PG8_MMA(0, 0, At, B0); PG8_MMA(0, 1, At, B1); PG8_BAR; PG8_SCHED;
;             PG8_LDA(At, 1, 1); PG8_STAGE(PG8_SB(1, 0), b3, voffB); PG8_STAGE(PG8_SB(1, 1), b3 + hstep, voffB); PG8_STAGE(PG8_SA(1, 0), a3, voffA);
;             PG8_WAIT_V(8); PG8_WAIT_L(0); PG8_BAR; PG8_MMA(1, 0, At, B0); PG8_MMA(1, 1, At, B1); PG8_BAR; PG8_SCHED;
	s_setprio 1
	v_mfma_f32_16x16x32_bf16 v[78:81], v[164:167], v[196:199], 0
	v_mfma_f32_16x16x32_bf16 v[74:77], v[172:175], v[196:199], 0
	v_mfma_f32_16x16x32_bf16 v[62:65], v[164:167], v[216:219], 0
	v_mfma_f32_16x16x32_bf16 v[58:61], v[172:175], v[216:219], 0
	v_mfma_f32_16x16x32_bf16 v[46:49], v[164:167], v[224:227], 0
	v_mfma_f32_16x16x32_bf16 v[42:45], v[172:175], v[224:227], 0
	v_mfma_f32_16x16x32_bf16 v[30:33], v[164:167], v[232:235], 0
	v_mfma_f32_16x16x32_bf16 v[26:29], v[172:175], v[232:235], 0
	v_mfma_f32_16x16x32_bf16 v[78:81], v[168:171], v[200:203], v[78:81]
	v_mfma_f32_16x16x32_bf16 v[74:77], v[176:179], v[200:203], v[74:77]
	v_mfma_f32_16x16x32_bf16 v[62:65], v[168:171], v[220:223], v[62:65]
	v_mfma_f32_16x16x32_bf16 v[58:61], v[176:179], v[220:223], v[58:61]
	v_mfma_f32_16x16x32_bf16 v[46:49], v[168:171], v[228:231], v[46:49]
	v_mfma_f32_16x16x32_bf16 v[42:45], v[176:179], v[228:231], v[42:45]
	v_mfma_f32_16x16x32_bf16 v[30:33], v[168:171], v[236:239], v[30:33]
	v_mfma_f32_16x16x32_bf16 v[26:29], v[176:179], v[236:239], v[26:29]
	v_mfma_f32_16x16x32_bf16 v[70:73], v[180:183], v[196:199], 0
	v_mfma_f32_16x16x32_bf16 v[66:69], v[188:191], v[196:199], 0
	v_mfma_f32_16x16x32_bf16 v[54:57], v[180:183], v[216:219], 0
	v_mfma_f32_16x16x32_bf16 v[50:53], v[188:191], v[216:219], 0
	v_mfma_f32_16x16x32_bf16 v[38:41], v[180:183], v[224:227], 0
	v_mfma_f32_16x16x32_bf16 v[34:37], v[188:191], v[224:227], 0
	v_mfma_f32_16x16x32_bf16 v[22:25], v[180:183], v[232:235], 0
	v_mfma_f32_16x16x32_bf16 v[18:21], v[188:191], v[232:235], 0
	v_mfma_f32_16x16x32_bf16 v[70:73], v[184:187], v[200:203], v[70:73]
	v_mfma_f32_16x16x32_bf16 v[66:69], v[192:195], v[200:203], v[66:69]
	v_mfma_f32_16x16x32_bf16 v[54:57], v[184:187], v[220:223], v[54:57]
	v_mfma_f32_16x16x32_bf16 v[50:53], v[192:195], v[220:223], v[50:53]
	v_mfma_f32_16x16x32_bf16 v[38:41], v[184:187], v[228:231], v[38:41]
	v_mfma_f32_16x16x32_bf16 v[34:37], v[192:195], v[228:231], v[34:37]
	v_mfma_f32_16x16x32_bf16 v[22:25], v[184:187], v[236:239], v[22:25]
	v_mfma_f32_16x16x32_bf16 v[18:21], v[192:195], v[236:239], v[18:21]
	s_setprio 0
	s_barrier
	v_add_u32_e32 v176, s82, v160
	v_add_u32_e32 v192, s83, v160
	ds_read_b128 v[164:167], v176
	ds_read_b128 v[168:171], v176 offset:1024
	ds_read_b128 v[172:175], v176 offset:2048
	ds_read_b128 v[176:179], v176 offset:3072
	ds_read_b128 v[180:183], v192
	ds_read_b128 v[184:187], v192 offset:1024
	ds_read_b128 v[188:191], v192 offset:2048
	ds_read_b128 v[192:195], v192 offset:3072
	s_add_u32 s24, s24, 0x40000
	s_addc_u32 s25, s25, 0
	s_mov_b32 m0, s37
	ds_read_b128 v[196:199], v163 offset:32768
	ds_read_b128 v[200:203], v163 offset:33792
	ds_read_b128 v[216:219], v163 offset:34816
	ds_read_b128 v[220:223], v163 offset:35840
	ds_read_b128 v[224:227], v163 offset:36864
	ds_read_b128 v[228:231], v163 offset:37888
	ds_read_b128 v[232:235], v163 offset:38912
	ds_read_b128 v[236:239], v163 offset:39936
	global_load_lds_dwordx4 v146, s[24:25]
	s_mov_b32 m0, s38
	s_nop 0
	global_load_lds_dwordx4 v150, s[24:25]
	s_waitcnt vmcnt(8) lgkmcnt(0)
	s_barrier
	s_setprio 1
	v_mfma_f32_16x16x32_bf16 v[142:145], v[164:167], v[196:199], v[142:145]
	v_mfma_f32_16x16x32_bf16 v[138:141], v[172:175], v[196:199], v[138:141]
	v_mfma_f32_16x16x32_bf16 v[126:129], v[164:167], v[216:219], v[126:129]
	v_mfma_f32_16x16x32_bf16 v[122:125], v[172:175], v[216:219], v[122:125]
	v_mfma_f32_16x16x32_bf16 v[110:113], v[164:167], v[224:227], v[110:113]
	v_mfma_f32_16x16x32_bf16 v[106:109], v[172:175], v[224:227], v[106:109]
	v_mfma_f32_16x16x32_bf16 v[94:97], v[164:167], v[232:235], v[94:97]
	v_mfma_f32_16x16x32_bf16 v[90:93], v[172:175], v[232:235], v[90:93]
	v_mfma_f32_16x16x32_bf16 v[142:145], v[168:171], v[200:203], v[142:145]
	v_mfma_f32_16x16x32_bf16 v[138:141], v[176:179], v[200:203], v[138:141]
	v_mfma_f32_16x16x32_bf16 v[126:129], v[168:171], v[220:223], v[126:129]
	v_mfma_f32_16x16x32_bf16 v[122:125], v[176:179], v[220:223], v[122:125]
	v_mfma_f32_16x16x32_bf16 v[110:113], v[168:171], v[228:231], v[110:113]
	v_mfma_f32_16x16x32_bf16 v[106:109], v[176:179], v[228:231], v[106:109]
	v_mfma_f32_16x16x32_bf16 v[94:97], v[168:171], v[236:239], v[94:97]
	v_mfma_f32_16x16x32_bf16 v[90:93], v[176:179], v[236:239], v[90:93]
	v_mfma_f32_16x16x32_bf16 v[134:137], v[180:183], v[196:199], v[134:137]
	v_mfma_f32_16x16x32_bf16 v[130:133], v[188:191], v[196:199], v[130:133]
	v_mfma_f32_16x16x32_bf16 v[118:121], v[180:183], v[216:219], v[118:121]
	v_mfma_f32_16x16x32_bf16 v[114:117], v[188:191], v[216:219], v[114:117]
	v_mfma_f32_16x16x32_bf16 v[102:105], v[180:183], v[224:227], v[102:105]
	v_mfma_f32_16x16x32_bf16 v[98:101], v[188:191], v[224:227], v[98:101]
	v_mfma_f32_16x16x32_bf16 v[86:89], v[180:183], v[232:235], v[86:89]
	v_mfma_f32_16x16x32_bf16 v[82:85], v[188:191], v[232:235], v[82:85]
	v_mfma_f32_16x16x32_bf16 v[134:137], v[184:187], v[200:203], v[134:137]
	v_mfma_f32_16x16x32_bf16 v[130:133], v[192:195], v[200:203], v[130:133]
	v_mfma_f32_16x16x32_bf16 v[118:121], v[184:187], v[220:223], v[118:121]
	v_mfma_f32_16x16x32_bf16 v[114:117], v[192:195], v[220:223], v[114:117]
	v_mfma_f32_16x16x32_bf16 v[102:105], v[184:187], v[228:231], v[102:105]
	v_mfma_f32_16x16x32_bf16 v[98:101], v[192:195], v[228:231], v[98:101]
	v_mfma_f32_16x16x32_bf16 v[86:89], v[184:187], v[236:239], v[86:89]
	v_mfma_f32_16x16x32_bf16 v[82:85], v[192:195], v[236:239], v[82:85]
	s_setprio 0
	s_barrier
; #define PG8_STAGE(bufoff, gbase, voff) do { _Pragma("unroll") for (int _i = 0; _i < 2; ++_i) \
;         __builtin_amdgcn_global_load_lds((const unsigned*)((const char*)(gbase) + (voff)[_i]), (PG8_LAS unsigned*)(lds + (bufoff) + ldsw + _i * 8192), 16, 0, 0); } while (0)
; #define PG8_LDA(dst, b, h) do { _Pragma("unroll") for (int m = 0; m < 4; ++m) _Pragma("unroll") for (int k = 0; k < 2; ++k) dst[m][k] = *(const PG8_LAS bf16x8*)(lds + PG8_SA(b, h) + aoff + m * 2048 + k * 1024); } while (0)
; #define PG8_WAIT_V(n) asm volatile("s_waitcnt vmcnt(" #n ")" ::: "memory")
; #define PG8_WAIT_L(n) asm volatile("s_waitcnt lgkmcnt(" #n ")" ::: "memory")
; #define PG8_BAR __builtin_amdgcn_s_barrier()
; template <class Epi, class Sched, bool ALIGN_EPI = false, bool SP2 = false>
; __device__ __forceinline__ void gemm_phase(PG8_LAS unsigned char* lds, const Gemm g, const Sched& S, const Epi& E) {
;     ...
;         for (int t = t_lo; t < t_hi; t += 2) {
;             const bool last = (t == nt - 2);
;             const char* a1 = cA + (size_t)(t + 1) * kstep;
;             const char* a2 = last ? nA : cA + (size_t)(t + 2) * kstep; const char* b2 = last ? nB : cB + (size_t)(t + 2) * kstep;
;             const char* a3 = a2 + kstep; const char* b3 = b2 + kstep;
;             if (last && has_next) S.a_ready_inloop(nxt, ui + 1);
;             if constexpr (SP2) {
;             PG8_LDB(B0, 0, 0); PG8_LDB(B1, 0, 1); PG8_SCHED; PG8_LDA(At, 0, 0); PG8_STAGE(PG8_SA(1, 1), a1 + hstep, voffA);
;             PG8_WAIT_V(8); PG8_WAIT_L(0); PG8_BAR; PG8_MMA(0, 0, At, B0); PG8_MMA(0, 1, At, B1); PG8_BAR; PG8_SCHED;
;             PG8_LDA(At, 0, 1); PG8_STAGE(PG8_SB(0, 0), b2, voffB); PG8_STAGE(PG8_SB(0, 1), b2 + hstep, voffB); PG8_STAGE(PG8_SA(0, 0), a2, voffA);
;             PG8_WAIT_V(8); PG8_WAIT_L(0); PG8_BAR; PG8_MMA(1, 0, At, B0); PG8_MMA(1, 1, At, B1); PG8_BAR; PG8_SCHED;
;             PG8_LDB(B0, 1, 0); PG8_LDB(B1, 1, 1); PG8_SCHED; PG8_LDA(At, 1, 0); PG8_STAGE(PG8_SA(0, 1), a2 + hstep, voffA);
;             PG8_WAIT_V(8); PG8_WAIT_L(0); PG8_BAR; PG8_MMA(0, 0, At, B0); PG8_MMA(0, 1, At, B1); PG8_BAR; PG8_SCHED;
;             PG8_LDA(At, 1, 1); PG8_STAGE(PG8_SB(1, 0), b3, voffB); PG8_STAGE(PG8_SB(1, 1), b3 + hstep, voffB); PG8_STAGE(PG8_SA(1, 0), a3, voffA);
;             PG8_WAIT_V(8); PG8_WAIT_L(0); PG8_BAR; PG8_MMA(1, 0, At, B0); PG8_MMA(1, 1, At, B1); PG8_BAR; PG8_SCHED;
	s_add_i32 s24, s82, s34
	s_mov_b32 m0, s24
	ds_read_b128 v[196:199], v163 offset:49152
	ds_read_b128 v[200:203], v163 offset:50176
	ds_read_b128 v[216:219], v163 offset:51200
	ds_read_b128 v[220:223], v163 offset:52224
	ds_read_b128 v[224:227], v163 offset:53248
	ds_read_b128 v[228:231], v163 offset:54272
	ds_read_b128 v[232:235], v163 offset:55296
	ds_read_b128 v[236:239], v163 offset:56320
	global_load_lds_dwordx4 v148, s[98:99]
	s_add_i32 m0, s24, 0x2000
	s_add_u32 s22, s22, 0x40080
	s_addc_u32 s23, s23, 0
	s_add_i32 s24, s83, s34
	global_load_lds_dwordx4 v152, s[98:99]
	s_mov_b32 m0, s24
	s_nop 0
	global_load_lds_dwordx4 v148, s[22:23]
	s_add_i32 m0, s24, 0x2000
	s_nop 0
	global_load_lds_dwordx4 v152, s[22:23]
	s_mov_b32 m0, s39
	s_nop 0
	global_load_lds_dwordx4 v146, s[100:101]
	s_mov_b32 m0, s42
	s_nop 0
	global_load_lds_dwordx4 v150, s[100:101]
	s_waitcnt vmcnt(8) lgkmcnt(0)
	s_barrier
	s_setprio 1
	v_mfma_f32_16x16x32_bf16 v[78:81], v[164:167], v[196:199], v[78:81]
	v_mfma_f32_16x16x32_bf16 v[74:77], v[172:175], v[196:199], v[74:77]
	v_mfma_f32_16x16x32_bf16 v[62:65], v[164:167], v[216:219], v[62:65]
	v_mfma_f32_16x16x32_bf16 v[58:61], v[172:175], v[216:219], v[58:61]
	v_mfma_f32_16x16x32_bf16 v[46:49], v[164:167], v[224:227], v[46:49]
	v_mfma_f32_16x16x32_bf16 v[42:45], v[172:175], v[224:227], v[42:45]
	v_mfma_f32_16x16x32_bf16 v[30:33], v[164:167], v[232:235], v[30:33]
	v_mfma_f32_16x16x32_bf16 v[26:29], v[172:175], v[232:235], v[26:29]
	v_mfma_f32_16x16x32_bf16 v[78:81], v[168:171], v[200:203], v[78:81]
	v_mfma_f32_16x16x32_bf16 v[74:77], v[176:179], v[200:203], v[74:77]
	v_mfma_f32_16x16x32_bf16 v[62:65], v[168:171], v[220:223], v[62:65]
	v_mfma_f32_16x16x32_bf16 v[58:61], v[176:179], v[220:223], v[58:61]
	v_mfma_f32_16x16x32_bf16 v[46:49], v[168:171], v[228:231], v[46:49]
	v_mfma_f32_16x16x32_bf16 v[42:45], v[176:179], v[228:231], v[42:45]
	v_mfma_f32_16x16x32_bf16 v[30:33], v[168:171], v[236:239], v[30:33]
	v_mfma_f32_16x16x32_bf16 v[26:29], v[176:179], v[236:239], v[26:29]
	v_mfma_f32_16x16x32_bf16 v[70:73], v[180:183], v[196:199], v[70:73]
	v_mfma_f32_16x16x32_bf16 v[66:69], v[188:191], v[196:199], v[66:69]
	v_mfma_f32_16x16x32_bf16 v[54:57], v[180:183], v[216:219], v[54:57]
	v_mfma_f32_16x16x32_bf16 v[50:53], v[188:191], v[216:219], v[50:53]
	v_mfma_f32_16x16x32_bf16 v[38:41], v[180:183], v[224:227], v[38:41]
	v_mfma_f32_16x16x32_bf16 v[34:37], v[188:191], v[224:227], v[34:37]
	v_mfma_f32_16x16x32_bf16 v[22:25], v[180:183], v[232:235], v[22:25]
	v_mfma_f32_16x16x32_bf16 v[18:21], v[188:191], v[232:235], v[18:21]
	v_mfma_f32_16x16x32_bf16 v[70:73], v[184:187], v[200:203], v[70:73]
	v_mfma_f32_16x16x32_bf16 v[66:69], v[192:195], v[200:203], v[66:69]
	v_mfma_f32_16x16x32_bf16 v[54:57], v[184:187], v[220:223], v[54:57]
	v_mfma_f32_16x16x32_bf16 v[50:53], v[192:195], v[220:223], v[50:53]
	v_mfma_f32_16x16x32_bf16 v[38:41], v[184:187], v[228:231], v[38:41]
	v_mfma_f32_16x16x32_bf16 v[34:37], v[192:195], v[228:231], v[34:37]
	v_mfma_f32_16x16x32_bf16 v[22:25], v[184:187], v[236:239], v[22:25]
	v_mfma_f32_16x16x32_bf16 v[18:21], v[192:195], v[236:239], v[18:21]
	s_setprio 0
	s_barrier
	s_add_i32 s64, s64, 2
	s_add_u32 s20, s20, 0x100
	s_addc_u32 s21, s21, 0
	s_add_u32 s62, s62, 0x100
	s_addc_u32 s63, s63, 0
.LBB0_762:
	v_add_u32_e32 v158, s90, v160
	ds_read_b128 v[164:167], v158
	ds_read_b128 v[168:171], v158 offset:1024
	ds_read_b128 v[172:175], v158 offset:2048
	ds_read_b128 v[176:179], v158 offset:3072
	v_add_u32_e32 v158, s81, v160
	ds_read_b128 v[180:183], v158
	ds_read_b128 v[184:187], v158 offset:1024
	ds_read_b128 v[188:191], v158 offset:2048
	ds_read_b128 v[192:195], v158 offset:3072
	s_add_u32 s22, s20, 0xfffc0080
	s_addc_u32 s23, s21, -1
	s_cmp_eq_u32 s64, 12
	s_cselect_b32 s25, s13, s23
	s_cselect_b32 s24, s52, s22
	s_cselect_b32 s23, s15, s63
	s_cselect_b32 s22, s53, s62
	s_add_u32 s98, s22, s46
	s_addc_u32 s99, s23, s47
	s_add_u32 s100, s24, s46
	s_addc_u32 s101, s25, s47
	s_add_i32 m0, s35, 0xc000
	ds_read_b128 v[196:199], v163
	ds_read_b128 v[200:203], v163 offset:1024
	ds_read_b128 v[216:219], v163 offset:2048
	ds_read_b128 v[220:223], v163 offset:3072
	ds_read_b128 v[224:227], v163 offset:4096
	ds_read_b128 v[228:231], v163 offset:5120
	ds_read_b128 v[232:235], v163 offset:6144
	ds_read_b128 v[236:239], v163 offset:7168
	global_load_lds_dwordx4 v154, s[20:21]
	s_add_i32 m0, s35, 0xe000
	s_nop 0
	global_load_lds_dwordx4 v156, s[20:21]
	s_waitcnt vmcnt(8) lgkmcnt(0)
	s_barrier
; #define PG8_STAGE(bufoff, gbase, voff) do { _Pragma("unroll") for (int _i = 0; _i < 2; ++_i) \
;         __builtin_amdgcn_global_load_lds((const unsigned*)((const char*)(gbase) + (voff)[_i]), (PG8_LAS unsigned*)(lds + (bufoff) + ldsw + _i * 8192), 16, 0, 0); } while (0)
; #define PG8_LDA(dst, b, h) do { _Pragma("unroll") for (int m = 0; m < 4; ++m) _Pragma("unroll") for (int k = 0; k < 2; ++k) dst[m][k] = *(const PG8_LAS bf16x8*)(lds + PG8_SA(b, h) + aoff + m * 2048 + k * 1024); } while (0)
; #define PG8_LDB(dst, b, h) do { _Pragma("unroll") for (int n = 0; n < 2; ++n) _Pragma("unroll") for (int k = 0; k < 2; ++k) dst[n][k] = *(const PG8_LAS bf16x8*)(lds + PG8_SB(b, h) + boff + n * 2048 + k * 1024); } while (0)
; #define PG8_MMA(ai, bj, At, Bt) do { __builtin_amdgcn_s_setprio(1); _Pragma("unroll") for (int m = 0; m < 4; ++m) _Pragma("unroll") for (int n = 0; n < 2; ++n) _Pragma("unroll") for (int k = 0; k < 2; ++k) \
;         acc[ai][bj][m][n] = __builtin_amdgcn_mfma_f32_16x16x32_bf16(Bt[n][k], At[m][k], acc[ai][bj][m][n], 0, 0, 0); __builtin_amdgcn_s_setprio(0); } while (0)
; #define PG8_WAIT_V(n) asm volatile("s_waitcnt vmcnt(" #n ")" ::: "memory")
; template <class Epi, class Sched, bool ALIGN_EPI = false, bool SP2 = false>
; __device__ __forceinline__ void gemm_phase(PG8_LAS unsigned char* lds, const Gemm g, const Sched& S, const Epi& E) {
;     ...
;             PG8_LDB(B0, 0, 0); PG8_LDB(B1, 0, 1); PG8_SCHED; PG8_LDA(At, 0, 0); PG8_STAGE(PG8_SA(1, 1), a1 + hstep, voffA);
;             PG8_WAIT_V(8); PG8_WAIT_L(0); PG8_BAR; PG8_MMA(0, 0, At, B0); PG8_MMA(0, 1, At, B1); PG8_BAR; PG8_SCHED;
;             PG8_LDA(At, 0, 1); PG8_STAGE(PG8_SB(0, 0), b2, voffB); PG8_STAGE(PG8_SB(0, 1), b2 + hstep, voffB); PG8_STAGE(PG8_SA(0, 0), a2, voffA);
;             PG8_WAIT_V(8); PG8_WAIT_L(0); PG8_BAR; PG8_MMA(1, 0, At, B0); PG8_MMA(1, 1, At, B1); PG8_BAR; PG8_SCHED;
;             PG8_LDB(B0, 1, 0); PG8_LDB(B1, 1, 1); PG8_SCHED; PG8_LDA(At, 1, 0); PG8_STAGE(PG8_SA(0, 1), a2 + hstep, voffA);
;             PG8_WAIT_V(8); PG8_WAIT_L(0); PG8_BAR; PG8_MMA(0, 0, At, B0); PG8_MMA(0, 1, At, B1); PG8_BAR; PG8_SCHED;
;             PG8_LDA(At, 1, 1); PG8_STAGE(PG8_SB(1, 0), b3, voffB); PG8_STAGE(PG8_SB(1, 1), b3 + hstep, voffB); PG8_STAGE(PG8_SA(1, 0), a3, voffA);
;             PG8_WAIT_V(8); PG8_WAIT_L(0); PG8_BAR; PG8_MMA(1, 0, At, B0); PG8_MMA(1, 1, At, B1); PG8_BAR; PG8_SCHED;
	s_setprio 1
	v_mfma_f32_16x16x32_bf16 v[142:145], v[164:167], v[196:199], v[142:145]
	v_mfma_f32_16x16x32_bf16 v[138:141], v[172:175], v[196:199], v[138:141]
	v_mfma_f32_16x16x32_bf16 v[126:129], v[164:167], v[216:219], v[126:129]
	v_mfma_f32_16x16x32_bf16 v[122:125], v[172:175], v[216:219], v[122:125]
	v_mfma_f32_16x16x32_bf16 v[110:113], v[164:167], v[224:227], v[110:113]
	v_mfma_f32_16x16x32_bf16 v[106:109], v[172:175], v[224:227], v[106:109]
	v_mfma_f32_16x16x32_bf16 v[94:97], v[164:167], v[232:235], v[94:97]
	v_mfma_f32_16x16x32_bf16 v[90:93], v[172:175], v[232:235], v[90:93]
	v_mfma_f32_16x16x32_bf16 v[142:145], v[168:171], v[200:203], v[142:145]
	v_mfma_f32_16x16x32_bf16 v[138:141], v[176:179], v[200:203], v[138:141]
	v_mfma_f32_16x16x32_bf16 v[126:129], v[168:171], v[220:223], v[126:129]
	v_mfma_f32_16x16x32_bf16 v[122:125], v[176:179], v[220:223], v[122:125]
	v_mfma_f32_16x16x32_bf16 v[110:113], v[168:171], v[228:231], v[110:113]
	v_mfma_f32_16x16x32_bf16 v[106:109], v[176:179], v[228:231], v[106:109]
	v_mfma_f32_16x16x32_bf16 v[94:97], v[168:171], v[236:239], v[94:97]
	v_mfma_f32_16x16x32_bf16 v[90:93], v[176:179], v[236:239], v[90:93]
	v_mfma_f32_16x16x32_bf16 v[134:137], v[180:183], v[196:199], v[134:137]
	v_mfma_f32_16x16x32_bf16 v[130:133], v[188:191], v[196:199], v[130:133]
	v_mfma_f32_16x16x32_bf16 v[118:121], v[180:183], v[216:219], v[118:121]
	v_mfma_f32_16x16x32_bf16 v[114:117], v[188:191], v[216:219], v[114:117]
	v_mfma_f32_16x16x32_bf16 v[102:105], v[180:183], v[224:227], v[102:105]
	v_mfma_f32_16x16x32_bf16 v[98:101], v[188:191], v[224:227], v[98:101]
	v_mfma_f32_16x16x32_bf16 v[86:89], v[180:183], v[232:235], v[86:89]
	v_mfma_f32_16x16x32_bf16 v[82:85], v[188:191], v[232:235], v[82:85]
	v_mfma_f32_16x16x32_bf16 v[134:137], v[184:187], v[200:203], v[134:137]
	v_mfma_f32_16x16x32_bf16 v[130:133], v[192:195], v[200:203], v[130:133]
	v_mfma_f32_16x16x32_bf16 v[118:121], v[184:187], v[220:223], v[118:121]
	v_mfma_f32_16x16x32_bf16 v[114:117], v[192:195], v[220:223], v[114:117]
	v_mfma_f32_16x16x32_bf16 v[102:105], v[184:187], v[228:231], v[102:105]
	v_mfma_f32_16x16x32_bf16 v[98:101], v[192:195], v[228:231], v[98:101]
	v_mfma_f32_16x16x32_bf16 v[86:89], v[184:187], v[236:239], v[86:89]
	v_mfma_f32_16x16x32_bf16 v[82:85], v[192:195], v[236:239], v[82:85]
	s_setprio 0
	s_barrier
	s_add_i32 s65, s90, s34
	s_mov_b32 m0, s65
	ds_read_b128 v[196:199], v163 offset:16384
	ds_read_b128 v[200:203], v163 offset:17408
	ds_read_b128 v[216:219], v163 offset:18432
	ds_read_b128 v[220:223], v163 offset:19456
	ds_read_b128 v[224:227], v163 offset:20480
	ds_read_b128 v[228:231], v163 offset:21504
	ds_read_b128 v[232:235], v163 offset:22528
	ds_read_b128 v[236:239], v163 offset:23552
	global_load_lds_dwordx4 v148, s[22:23]
	s_add_i32 m0, s65, 0x2000
	s_add_u32 s66, s22, 0x40000
	s_addc_u32 s67, s23, 0
	s_add_i32 s65, s81, s34
	global_load_lds_dwordx4 v152, s[22:23]
	s_mov_b32 m0, s65
	s_nop 0
	global_load_lds_dwordx4 v148, s[66:67]
	s_add_i32 m0, s65, 0x2000
	s_nop 0
	global_load_lds_dwordx4 v152, s[66:67]
	s_mov_b32 m0, s35
	s_nop 0
	global_load_lds_dwordx4 v146, s[24:25]
	s_mov_b32 m0, s36
	s_nop 0
	global_load_lds_dwordx4 v150, s[24:25]
	s_waitcnt vmcnt(8) lgkmcnt(0)
	s_barrier
	s_setprio 1
	v_mfma_f32_16x16x32_bf16 v[78:81], v[164:167], v[196:199], v[78:81]
	v_mfma_f32_16x16x32_bf16 v[74:77], v[172:175], v[196:199], v[74:77]
	v_mfma_f32_16x16x32_bf16 v[62:65], v[164:167], v[216:219], v[62:65]
	v_mfma_f32_16x16x32_bf16 v[58:61], v[172:175], v[216:219], v[58:61]
	v_mfma_f32_16x16x32_bf16 v[46:49], v[164:167], v[224:227], v[46:49]
	v_mfma_f32_16x16x32_bf16 v[42:45], v[172:175], v[224:227], v[42:45]
	v_mfma_f32_16x16x32_bf16 v[30:33], v[164:167], v[232:235], v[30:33]
	v_mfma_f32_16x16x32_bf16 v[26:29], v[172:175], v[232:235], v[26:29]
	v_mfma_f32_16x16x32_bf16 v[78:81], v[168:171], v[200:203], v[78:81]
	v_mfma_f32_16x16x32_bf16 v[74:77], v[176:179], v[200:203], v[74:77]
	v_mfma_f32_16x16x32_bf16 v[62:65], v[168:171], v[220:223], v[62:65]
	v_mfma_f32_16x16x32_bf16 v[58:61], v[176:179], v[220:223], v[58:61]
	v_mfma_f32_16x16x32_bf16 v[46:49], v[168:171], v[228:231], v[46:49]
	v_mfma_f32_16x16x32_bf16 v[42:45], v[176:179], v[228:231], v[42:45]
	v_mfma_f32_16x16x32_bf16 v[30:33], v[168:171], v[236:239], v[30:33]
	v_mfma_f32_16x16x32_bf16 v[26:29], v[176:179], v[236:239], v[26:29]
	v_mfma_f32_16x16x32_bf16 v[70:73], v[180:183], v[196:199], v[70:73]
	v_mfma_f32_16x16x32_bf16 v[66:69], v[188:191], v[196:199], v[66:69]
	v_mfma_f32_16x16x32_bf16 v[54:57], v[180:183], v[216:219], v[54:57]
	v_mfma_f32_16x16x32_bf16 v[50:53], v[188:191], v[216:219], v[50:53]
	v_mfma_f32_16x16x32_bf16 v[38:41], v[180:183], v[224:227], v[38:41]
	v_mfma_f32_16x16x32_bf16 v[34:37], v[188:191], v[224:227], v[34:37]
	v_mfma_f32_16x16x32_bf16 v[22:25], v[180:183], v[232:235], v[22:25]
	v_mfma_f32_16x16x32_bf16 v[18:21], v[188:191], v[232:235], v[18:21]
	v_mfma_f32_16x16x32_bf16 v[70:73], v[184:187], v[200:203], v[70:73]
	v_mfma_f32_16x16x32_bf16 v[66:69], v[192:195], v[200:203], v[66:69]
	v_mfma_f32_16x16x32_bf16 v[54:57], v[184:187], v[220:223], v[54:57]
	v_mfma_f32_16x16x32_bf16 v[50:53], v[192:195], v[220:223], v[50:53]
	v_mfma_f32_16x16x32_bf16 v[38:41], v[184:187], v[228:231], v[38:41]
	v_mfma_f32_16x16x32_bf16 v[34:37], v[192:195], v[228:231], v[34:37]
	v_mfma_f32_16x16x32_bf16 v[22:25], v[184:187], v[236:239], v[22:25]
	v_mfma_f32_16x16x32_bf16 v[18:21], v[192:195], v[236:239], v[18:21]
	s_setprio 0
	s_barrier
; #define PG8_STAGE(bufoff, gbase, voff) do { _Pragma("unroll") for (int _i = 0; _i < 2; ++_i) \
;         __builtin_amdgcn_global_load_lds((const unsigned*)((const char*)(gbase) + (voff)[_i]), (PG8_LAS unsigned*)(lds + (bufoff) + ldsw + _i * 8192), 16, 0, 0); } while (0)
; #define PG8_LDA(dst, b, h) do { _Pragma("unroll") for (int m = 0; m < 4; ++m) _Pragma("unroll") for (int k = 0; k < 2; ++k) dst[m][k] = *(const PG8_LAS bf16x8*)(lds + PG8_SA(b, h) + aoff + m * 2048 + k * 1024); } while (0)
; #define PG8_LDB(dst, b, h) do { _Pragma("unroll") for (int n = 0; n < 2; ++n) _Pragma("unroll") for (int k = 0; k < 2; ++k) dst[n][k] = *(const PG8_LAS bf16x8*)(lds + PG8_SB(b, h) + boff + n * 2048 + k * 1024); } while (0)
; #define PG8_MMA(ai, bj, At, Bt) do { __builtin_amdgcn_s_setprio(1); _Pragma("unroll") for (int m = 0; m < 4; ++m) _Pragma("unroll") for (int n = 0; n < 2; ++n) _Pragma("unroll") for (int k = 0; k < 2; ++k) \
;         acc[ai][bj][m][n] = __builtin_amdgcn_mfma_f32_16x16x32_bf16(Bt[n][k], At[m][k], acc[ai][bj][m][n], 0, 0, 0); __builtin_amdgcn_s_setprio(0); } while (0)
; #define PG8_WAIT_V(n) asm volatile("s_waitcnt vmcnt(" #n ")" ::: "memory")
; template <class Epi, class Sched, bool ALIGN_EPI = false, bool SP2 = false>
; __device__ __forceinline__ void gemm_phase(PG8_LAS unsigned char* lds, const Gemm g, const Sched& S, const Epi& E) {
;     ...
;             PG8_LDB(B0, 0, 0); PG8_LDB(B1, 0, 1); PG8_SCHED; PG8_LDA(At, 0, 0); PG8_STAGE(PG8_SA(1, 1), a1 + hstep, voffA);
;             PG8_WAIT_V(8); PG8_WAIT_L(0); PG8_BAR; PG8_MMA(0, 0, At, B0); PG8_MMA(0, 1, At, B1); PG8_BAR; PG8_SCHED;
;             PG8_LDA(At, 0, 1); PG8_STAGE(PG8_SB(0, 0), b2, voffB); PG8_STAGE(PG8_SB(0, 1), b2 + hstep, voffB); PG8_STAGE(PG8_SA(0, 0), a2, voffA);
;             PG8_WAIT_V(8); PG8_WAIT_L(0); PG8_BAR; PG8_MMA(1, 0, At, B0); PG8_MMA(1, 1, At, B1); PG8_BAR; PG8_SCHED;
;             PG8_LDB(B0, 1, 0); PG8_LDB(B1, 1, 1); PG8_SCHED; PG8_LDA(At, 1, 0); PG8_STAGE(PG8_SA(0, 1), a2 + hstep, voffA);
;             PG8_WAIT_V(8); PG8_WAIT_L(0); PG8_BAR; PG8_MMA(0, 0, At, B0); PG8_MMA(0, 1, At, B1); PG8_BAR; PG8_SCHED;
;             PG8_LDA(At, 1, 1); PG8_STAGE(PG8_SB(1, 0), b3, voffB); PG8_STAGE(PG8_SB(1, 1), b3 + hstep, voffB); PG8_STAGE(PG8_SA(1, 0), a3, voffA);
;             PG8_WAIT_V(8); PG8_WAIT_L(0); PG8_BAR; PG8_MMA(1, 0, At, B0); PG8_MMA(1, 1, At, B1); PG8_BAR; PG8_SCHED;
	v_add_u32_e32 v176, s82, v160
	v_add_u32_e32 v192, s83, v160
	ds_read_b128 v[164:167], v176
	ds_read_b128 v[168:171], v176 offset:1024
	ds_read_b128 v[172:175], v176 offset:2048
	ds_read_b128 v[176:179], v176 offset:3072
	ds_read_b128 v[180:183], v192
	ds_read_b128 v[184:187], v192 offset:1024
	ds_read_b128 v[188:191], v192 offset:2048
	ds_read_b128 v[192:195], v192 offset:3072
	s_add_u32 s24, s24, 0x40000
	s_addc_u32 s25, s25, 0
	s_mov_b32 m0, s37
	ds_read_b128 v[196:199], v163 offset:32768
	ds_read_b128 v[200:203], v163 offset:33792
	ds_read_b128 v[216:219], v163 offset:34816
	ds_read_b128 v[220:223], v163 offset:35840
	ds_read_b128 v[224:227], v163 offset:36864
	ds_read_b128 v[228:231], v163 offset:37888
	ds_read_b128 v[232:235], v163 offset:38912
	ds_read_b128 v[236:239], v163 offset:39936
	global_load_lds_dwordx4 v146, s[24:25]
	s_mov_b32 m0, s38
	s_nop 0
	global_load_lds_dwordx4 v150, s[24:25]
	s_waitcnt vmcnt(8) lgkmcnt(0)
	s_barrier
	s_setprio 1
	v_mfma_f32_16x16x32_bf16 v[142:145], v[164:167], v[196:199], v[142:145]
	v_mfma_f32_16x16x32_bf16 v[138:141], v[172:175], v[196:199], v[138:141]
	v_mfma_f32_16x16x32_bf16 v[126:129], v[164:167], v[216:219], v[126:129]
	v_mfma_f32_16x16x32_bf16 v[122:125], v[172:175], v[216:219], v[122:125]
	v_mfma_f32_16x16x32_bf16 v[110:113], v[164:167], v[224:227], v[110:113]
	v_mfma_f32_16x16x32_bf16 v[106:109], v[172:175], v[224:227], v[106:109]
	v_mfma_f32_16x16x32_bf16 v[94:97], v[164:167], v[232:235], v[94:97]
	v_mfma_f32_16x16x32_bf16 v[90:93], v[172:175], v[232:235], v[90:93]
	v_mfma_f32_16x16x32_bf16 v[142:145], v[168:171], v[200:203], v[142:145]
	v_mfma_f32_16x16x32_bf16 v[138:141], v[176:179], v[200:203], v[138:141]
	v_mfma_f32_16x16x32_bf16 v[126:129], v[168:171], v[220:223], v[126:129]
	v_mfma_f32_16x16x32_bf16 v[122:125], v[176:179], v[220:223], v[122:125]
	v_mfma_f32_16x16x32_bf16 v[110:113], v[168:171], v[228:231], v[110:113]
	v_mfma_f32_16x16x32_bf16 v[106:109], v[176:179], v[228:231], v[106:109]
	v_mfma_f32_16x16x32_bf16 v[94:97], v[168:171], v[236:239], v[94:97]
	v_mfma_f32_16x16x32_bf16 v[90:93], v[176:179], v[236:239], v[90:93]
	v_mfma_f32_16x16x32_bf16 v[134:137], v[180:183], v[196:199], v[134:137]
	v_mfma_f32_16x16x32_bf16 v[130:133], v[188:191], v[196:199], v[130:133]
	v_mfma_f32_16x16x32_bf16 v[118:121], v[180:183], v[216:219], v[118:121]
	v_mfma_f32_16x16x32_bf16 v[114:117], v[188:191], v[216:219], v[114:117]
	v_mfma_f32_16x16x32_bf16 v[102:105], v[180:183], v[224:227], v[102:105]
	v_mfma_f32_16x16x32_bf16 v[98:101], v[188:191], v[224:227], v[98:101]
	v_mfma_f32_16x16x32_bf16 v[86:89], v[180:183], v[232:235], v[86:89]
	v_mfma_f32_16x16x32_bf16 v[82:85], v[188:191], v[232:235], v[82:85]
	v_mfma_f32_16x16x32_bf16 v[134:137], v[184:187], v[200:203], v[134:137]
	v_mfma_f32_16x16x32_bf16 v[130:133], v[192:195], v[200:203], v[130:133]
	v_mfma_f32_16x16x32_bf16 v[118:121], v[184:187], v[220:223], v[118:121]
	v_mfma_f32_16x16x32_bf16 v[114:117], v[192:195], v[220:223], v[114:117]
	v_mfma_f32_16x16x32_bf16 v[102:105], v[184:187], v[228:231], v[102:105]
	v_mfma_f32_16x16x32_bf16 v[98:101], v[192:195], v[228:231], v[98:101]
	v_mfma_f32_16x16x32_bf16 v[86:89], v[184:187], v[236:239], v[86:89]
	v_mfma_f32_16x16x32_bf16 v[82:85], v[192:195], v[236:239], v[82:85]
	s_setprio 0
	s_barrier
	s_add_i32 s24, s82, s34
	s_mov_b32 m0, s24
	ds_read_b128 v[196:199], v163 offset:49152
	ds_read_b128 v[200:203], v163 offset:50176
	ds_read_b128 v[216:219], v163 offset:51200
	ds_read_b128 v[220:223], v163 offset:52224
	ds_read_b128 v[224:227], v163 offset:53248
	ds_read_b128 v[228:231], v163 offset:54272
	ds_read_b128 v[232:235], v163 offset:55296
	ds_read_b128 v[236:239], v163 offset:56320
	global_load_lds_dwordx4 v148, s[98:99]
	s_add_i32 m0, s24, 0x2000
	s_add_u32 s22, s22, 0x40080
	s_addc_u32 s23, s23, 0
	s_add_i32 s24, s83, s34
	global_load_lds_dwordx4 v152, s[98:99]
	s_mov_b32 m0, s24
	s_nop 0
	global_load_lds_dwordx4 v148, s[22:23]
	s_add_i32 m0, s24, 0x2000
	s_nop 0
	global_load_lds_dwordx4 v152, s[22:23]
	s_mov_b32 m0, s39
	s_nop 0
	global_load_lds_dwordx4 v146, s[100:101]
	s_mov_b32 m0, s42
	s_nop 0
	global_load_lds_dwordx4 v150, s[100:101]
	s_waitcnt vmcnt(8) lgkmcnt(0)
	s_barrier
	s_setprio 1
	v_mfma_f32_16x16x32_bf16 v[78:81], v[164:167], v[196:199], v[78:81]
	v_mfma_f32_16x16x32_bf16 v[74:77], v[172:175], v[196:199], v[74:77]
	v_mfma_f32_16x16x32_bf16 v[62:65], v[164:167], v[216:219], v[62:65]
	v_mfma_f32_16x16x32_bf16 v[58:61], v[172:175], v[216:219], v[58:61]
	v_mfma_f32_16x16x32_bf16 v[46:49], v[164:167], v[224:227], v[46:49]
	v_mfma_f32_16x16x32_bf16 v[42:45], v[172:175], v[224:227], v[42:45]
	v_mfma_f32_16x16x32_bf16 v[30:33], v[164:167], v[232:235], v[30:33]
	v_mfma_f32_16x16x32_bf16 v[26:29], v[172:175], v[232:235], v[26:29]
	v_mfma_f32_16x16x32_bf16 v[78:81], v[168:171], v[200:203], v[78:81]
	v_mfma_f32_16x16x32_bf16 v[74:77], v[176:179], v[200:203], v[74:77]
	v_mfma_f32_16x16x32_bf16 v[62:65], v[168:171], v[220:223], v[62:65]
	v_mfma_f32_16x16x32_bf16 v[58:61], v[176:179], v[220:223], v[58:61]
	v_mfma_f32_16x16x32_bf16 v[46:49], v[168:171], v[228:231], v[46:49]
	v_mfma_f32_16x16x32_bf16 v[42:45], v[176:179], v[228:231], v[42:45]
	v_mfma_f32_16x16x32_bf16 v[30:33], v[168:171], v[236:239], v[30:33]
	v_mfma_f32_16x16x32_bf16 v[26:29], v[176:179], v[236:239], v[26:29]
	v_mfma_f32_16x16x32_bf16 v[70:73], v[180:183], v[196:199], v[70:73]
	v_mfma_f32_16x16x32_bf16 v[66:69], v[188:191], v[196:199], v[66:69]
	v_mfma_f32_16x16x32_bf16 v[54:57], v[180:183], v[216:219], v[54:57]
	v_mfma_f32_16x16x32_bf16 v[50:53], v[188:191], v[216:219], v[50:53]
	v_mfma_f32_16x16x32_bf16 v[38:41], v[180:183], v[224:227], v[38:41]
	v_mfma_f32_16x16x32_bf16 v[34:37], v[188:191], v[224:227], v[34:37]
	v_mfma_f32_16x16x32_bf16 v[22:25], v[180:183], v[232:235], v[22:25]
	v_mfma_f32_16x16x32_bf16 v[18:21], v[188:191], v[232:235], v[18:21]
	v_mfma_f32_16x16x32_bf16 v[70:73], v[184:187], v[200:203], v[70:73]
	v_mfma_f32_16x16x32_bf16 v[66:69], v[192:195], v[200:203], v[66:69]
	v_mfma_f32_16x16x32_bf16 v[54:57], v[184:187], v[220:223], v[54:57]
	v_mfma_f32_16x16x32_bf16 v[50:53], v[192:195], v[220:223], v[50:53]
	v_mfma_f32_16x16x32_bf16 v[38:41], v[184:187], v[228:231], v[38:41]
	v_mfma_f32_16x16x32_bf16 v[34:37], v[192:195], v[228:231], v[34:37]
	v_mfma_f32_16x16x32_bf16 v[22:25], v[184:187], v[236:239], v[22:25]
	v_mfma_f32_16x16x32_bf16 v[18:21], v[192:195], v[236:239], v[18:21]
	s_setprio 0
	s_barrier
	s_add_i32 s64, s64, 2
	s_add_u32 s20, s20, 0x100
	s_addc_u32 s21, s21, 0
	s_add_u32 s62, s62, 0x100
	s_addc_u32 s63, s63, 0
	s_cmp_gt_u32 s64, 13
	s_cbranch_scc0 .LBB0_762
	s_and_b64 vcc, exec, s[10:11]
	s_cbranch_vccz .LBB0_765
	s_barrier
